# streaming (nt) hint on the mixer's MIX stores, on top of the previous best
# speedup vs baseline: 1.0506x; 1.0006x over previous
.LBB0_744:
	v_and_b32_e32 v45, 64, v228
	v_xor_b32_e32 v44, 16, v228
	v_add_u32_e32 v45, 64, v45
	v_cmp_lt_i32_e32 vcc, v44, v45
	v_or_b32_e32 v78, s38, v206
	v_mov_b32_e32 v47, s39
	v_cndmask_b32_e32 v44, v228, v44, vcc
	v_lshlrev_b32_e32 v77, 2, v44
	v_xor_b32_e32 v44, 32, v228
	v_cmp_lt_i32_e32 vcc, v44, v45
	s_add_i32 s8, s22, 0x200
	v_or_b32_e32 v46, s68, v78
	v_cndmask_b32_e32 v44, v228, v44, vcc
	v_lshlrev_b32_e32 v76, 2, v44
	v_lshlrev_b64 v[44:45], 2, v[46:47]
	s_ashr_i32 s10, s8, 4
	v_and_b32_e32 v51, 0x7fffff, v45
	v_and_b32_e32 v50, 0xffffff80, v44
	v_lshl_add_u64 v[44:45], s[12:13], 0, v[196:197]
	s_mov_b64 s[0:1], 0x1c801000
	s_ashr_i32 s11, s10, 31
	v_lshl_add_u64 v[48:49], v[44:45], 0, s[0:1]
	v_lshl_add_u64 v[44:45], v[50:51], 0, s[10:11]
	v_lshlrev_b64 v[44:45], 9, v[44:45]
	v_lshl_add_u64 v[44:45], v[48:49], 0, v[44:45]
	global_load_dwordx2 v[44:45], v[44:45], off nt
	s_add_i32 s7, s22, 0x210
	s_ashr_i32 s18, s7, 4
	s_ashr_i32 s19, s18, 31
	v_lshl_add_u64 v[52:53], v[50:51], 0, s[18:19]
	v_lshlrev_b64 v[52:53], 9, v[52:53]
	v_lshl_add_u64 v[52:53], v[48:49], 0, v[52:53]
	global_load_dwordx2 v[74:75], v[52:53], off nt
	v_mul_f32_e32 v79, v93, v93
	v_fmac_f32_e32 v79, v92, v92
	v_fmac_f32_e32 v79, v94, v94
	v_fmac_f32_e32 v79, v95, v95
	v_fmac_f32_e32 v79, v88, v88
	v_fmac_f32_e32 v79, v89, v89
	v_fmac_f32_e32 v79, v90, v90
	s_add_i32 s6, s22, 0x220
	v_fmac_f32_e32 v79, v91, v91
	s_ashr_i32 s20, s6, 4
	v_fmac_f32_e32 v79, v84, v84
	s_ashr_i32 s21, s20, 31
	v_fmac_f32_e32 v79, v85, v85
	v_lshl_add_u64 v[52:53], v[50:51], 0, s[20:21]
	s_add_i32 s5, s22, 0x230
	v_fmac_f32_e32 v79, v86, v86
	v_lshlrev_b64 v[52:53], 9, v[52:53]
	s_ashr_i32 s24, s5, 4
	v_fmac_f32_e32 v79, v87, v87
	v_lshl_add_u64 v[52:53], v[48:49], 0, v[52:53]
	s_ashr_i32 s25, s24, 31
	v_fmac_f32_e32 v79, v64, v64
	global_load_dwordx2 v[72:73], v[52:53], off nt
	v_lshl_add_u64 v[52:53], v[50:51], 0, s[24:25]
	s_add_i32 s4, s22, 0x240
	v_fmac_f32_e32 v79, v65, v65
	v_lshlrev_b64 v[52:53], 9, v[52:53]
	s_ashr_i32 s34, s4, 4
	v_fmac_f32_e32 v79, v66, v66
	v_lshl_add_u64 v[52:53], v[48:49], 0, v[52:53]
	s_ashr_i32 s35, s34, 31
	v_fmac_f32_e32 v79, v67, v67
	global_load_dwordx2 v[70:71], v[52:53], off nt
	v_lshl_add_u64 v[52:53], v[50:51], 0, s[34:35]
	s_add_i32 s1, s22, 0x250
	v_fmac_f32_e32 v79, v60, v60
	v_lshlrev_b64 v[52:53], 9, v[52:53]
	s_ashr_i32 s36, s1, 4
	v_fmac_f32_e32 v79, v61, v61
	v_lshl_add_u64 v[52:53], v[48:49], 0, v[52:53]
	s_ashr_i32 s37, s36, 31
	v_fmac_f32_e32 v79, v62, v62
	global_load_dwordx2 v[68:69], v[52:53], off nt
	v_lshl_add_u64 v[52:53], v[50:51], 0, s[36:37]
	s_add_i32 s0, s22, 0x260
	s_addk_i32 s22, 0x270
	v_fmac_f32_e32 v79, v63, v63
	v_lshlrev_b64 v[52:53], 9, v[52:53]
	s_ashr_i32 s38, s0, 4
	s_ashr_i32 s40, s22, 4
	v_fmac_f32_e32 v79, v40, v40
	v_lshl_add_u64 v[52:53], v[48:49], 0, v[52:53]
	s_ashr_i32 s39, s38, 31
	s_ashr_i32 s41, s40, 31
	v_fmac_f32_e32 v79, v41, v41
	global_load_dwordx2 v[58:59], v[52:53], off nt
	v_lshl_add_u64 v[52:53], v[50:51], 0, s[38:39]
	v_lshl_add_u64 v[50:51], v[50:51], 0, s[40:41]
	v_fmac_f32_e32 v79, v42, v42
	v_lshlrev_b64 v[52:53], 9, v[52:53]
	v_lshlrev_b64 v[50:51], 9, v[50:51]
	v_fmac_f32_e32 v79, v43, v43
	v_pk_mul_f32 v[54:55], v[36:37], v[36:37]
	v_lshl_add_u64 v[52:53], v[48:49], 0, v[52:53]
	v_lshl_add_u64 v[50:51], v[48:49], 0, v[50:51]
	v_add_f32_e32 v54, v54, v79
	global_load_dwordx2 v[56:57], v[52:53], off nt
	v_add_f32_e32 v54, v55, v54
	global_load_dwordx2 v[50:51], v[50:51], off nt
	v_pk_mul_f32 v[52:53], v[38:39], v[38:39]
	v_mov_b32_e32 v97, v92
	v_add_f32_e32 v52, v52, v54
	v_add_f32_e32 v79, v53, v52
	v_pk_mul_f32 v[54:55], v[32:33], v[32:33]
	v_pk_mul_f32 v[52:53], v[34:35], v[34:35]
	v_add_f32_e32 v54, v54, v79
	v_add_f32_e32 v54, v55, v54
	v_add_f32_e32 v52, v52, v54
	v_add_f32_e32 v52, v53, v52
	ds_bpermute_b32 v53, v77, v52
	s_waitcnt vmcnt(7)
	v_lshlrev_b32_e32 v54, 16, v44
	v_lshlrev_b32_e32 v80, 16, v45
	v_and_b32_e32 v82, 0xffff0000, v45
	v_mul_f32_e32 v45, 0xbfb8aa3b, v54
	s_waitcnt lgkmcnt(0)
	v_add_f32_e32 v52, v52, v53
	ds_bpermute_b32 v53, v76, v52
	v_exp_f32_e32 v45, v45
	v_and_b32_e32 v44, 0xffff0000, v44
	s_ashr_i32 s42, s8, 5
	s_ashr_i32 s43, s42, 31
	s_waitcnt lgkmcnt(0)
	v_add_f32_e32 v52, v52, v53
	v_add_f32_e32 v45, 1.0, v45
	v_fmamk_f32 v52, v52, 0x3c000000, v227
	v_rcp_f32_e32 v96, v45
	v_mul_f32_e32 v45, 0xbfb8aa3b, v44
	v_cmp_gt_f32_e32 vcc, s15, v52
	v_mul_f32_e32 v53, 0x4b800000, v52
	v_exp_f32_e32 v45, v45
	v_cndmask_b32_e32 v52, v52, v53, vcc
	v_rsq_f32_e32 v52, v52
	s_mov_b64 s[8:9], 0xfe01000
	v_add_f32_e32 v45, 1.0, v45
	v_rcp_f32_e32 v92, v45
	v_mul_f32_e32 v53, 0x45800000, v52
	v_cndmask_b32_e32 v55, v52, v53, vcc
	v_mov_b32_e32 v45, v55
	v_pk_mul_f32 v[44:45], v[92:93], v[44:45]
	v_pk_mul_f32 v[96:97], v[96:97], v[54:55]
	v_mul_f32_e32 v44, v44, v45
	v_lshlrev_b64 v[52:53], 1, v[46:47]
	v_mul_f32_e32 v46, v96, v97
	v_cvt_pk_bf16_f32 v92, v46, v44
	v_mul_f32_e32 v44, 0xbfb8aa3b, v80
	v_exp_f32_e32 v44, v44
	v_mov_b32_e32 v45, v94
	v_mov_b32_e32 v81, v55
	v_mov_b32_e32 v83, v55
	v_add_f32_e32 v44, 1.0, v44
	v_rcp_f32_e32 v44, v44
	s_waitcnt vmcnt(6)
	v_lshlrev_b32_e32 v54, 16, v74
	v_and_b32_e32 v53, 0x3fffff, v53
	v_and_b32_e32 v52, 0xffffffc0, v52
	v_pk_mul_f32 v[44:45], v[44:45], v[80:81]
	v_lshl_add_u64 v[80:81], v[52:53], 0, s[42:43]
	v_mul_f32_e32 v46, v44, v45
	v_mul_f32_e32 v44, 0xbfb8aa3b, v82
	v_exp_f32_e32 v44, v44
	v_lshlrev_b64 v[80:81], 10, v[80:81]
	v_mov_b32_e32 v185, v197
	v_and_b32_e32 v74, 0xffff0000, v74
	v_add_f32_e32 v44, 1.0, v44
	v_rcp_f32_e32 v94, v44
	s_ashr_i32 s44, s6, 5
	s_ashr_i32 s45, s44, 31
	s_ashr_i32 s46, s5, 5
	v_pk_mul_f32 v[44:45], v[94:95], v[82:83]
	v_and_b32_e32 v82, 0xffff0000, v75
	v_mul_f32_e32 v44, v44, v45
	v_cvt_pk_bf16_f32 v93, v46, v44
	v_and_or_b32 v44, v207, 16, v206
	v_mul_f32_e32 v46, 0xbfb8aa3b, v54
	v_lshlrev_b32_e32 v196, 4, v44
	v_exp_f32_e32 v46, v46
	v_lshl_add_u64 v[44:45], s[12:13], 0, v[196:197]
	v_lshl_add_u64 v[44:45], v[44:45], 0, s[8:9]
	v_lshl_add_u64 v[80:81], v[44:45], 0, v[80:81]
	v_lshl_add_u64 v[80:81], v[80:81], 0, v[184:185]
	v_add_f32_e32 v46, 1.0, v46
	global_store_dwordx2 v[80:81], v[92:93], off nt
	v_rcp_f32_e32 v92, v46
	v_mov_b32_e32 v93, v88
	v_lshlrev_b32_e32 v80, 16, v75
	v_mov_b32_e32 v75, v55
	v_pk_mul_f32 v[92:93], v[92:93], v[54:55]
	v_mul_f32_e32 v54, 0xbfb8aa3b, v74
	v_exp_f32_e32 v54, v54
	v_mul_f32_e32 v46, v92, v93
	v_mov_b32_e32 v81, v55
	s_ashr_i32 s12, s7, 5
	v_add_f32_e32 v54, 1.0, v54
	v_rcp_f32_e32 v88, v54
	s_ashr_i32 s13, s12, 31
	s_ashr_i32 s47, s46, 31
	s_ashr_i32 s48, s4, 5
	v_pk_mul_f32 v[74:75], v[88:89], v[74:75]
	v_mov_b32_e32 v89, v90
	v_mul_f32_e32 v54, v74, v75
	v_cvt_pk_bf16_f32 v74, v46, v54
	v_mul_f32_e32 v46, 0xbfb8aa3b, v80
	v_exp_f32_e32 v46, v46
	v_mul_f32_e32 v54, 0xbfb8aa3b, v82
	v_exp_f32_e32 v54, v54
	s_ashr_i32 s49, s48, 31
	v_add_f32_e32 v46, 1.0, v46
	v_rcp_f32_e32 v88, v46
	v_add_f32_e32 v54, 1.0, v54
	v_rcp_f32_e32 v90, v54
	s_ashr_i32 s50, s1, 5
	v_pk_mul_f32 v[80:81], v[88:89], v[80:81]
	s_ashr_i32 s51, s50, 31
	v_mul_f32_e32 v46, v80, v81
	v_pk_mul_f32 v[80:81], v[90:91], v[82:83]
	v_mov_b32_e32 v83, v84
	v_mul_f32_e32 v54, v80, v81
	v_cvt_pk_bf16_f32 v75, v46, v54
	s_waitcnt vmcnt(6)
	v_lshlrev_b32_e32 v54, 16, v72
	v_mul_f32_e32 v46, 0xbfb8aa3b, v54
	v_exp_f32_e32 v46, v46
	v_and_b32_e32 v72, 0xffff0000, v72
	v_lshl_add_u64 v[80:81], v[52:53], 0, s[12:13]
	v_lshlrev_b64 v[80:81], 10, v[80:81]
	v_add_f32_e32 v46, 1.0, v46
	v_rcp_f32_e32 v82, v46
	v_lshl_add_u64 v[80:81], v[44:45], 0, v[80:81]
	v_lshl_add_u64 v[80:81], v[80:81], 0, v[184:185]
	global_store_dwordx2 v[80:81], v[74:75], off offset:512 nt
	v_pk_mul_f32 v[82:83], v[82:83], v[54:55]
	v_mul_f32_e32 v54, 0xbfb8aa3b, v72
	v_exp_f32_e32 v54, v54
	v_lshlrev_b32_e32 v74, 16, v73
	v_and_b32_e32 v80, 0xffff0000, v73
	v_mov_b32_e32 v73, v55
	v_add_f32_e32 v54, 1.0, v54
	v_rcp_f32_e32 v84, v54
	v_mul_f32_e32 v46, v82, v83
	v_mov_b32_e32 v83, v86
	v_mov_b32_e32 v75, v55
	v_pk_mul_f32 v[72:73], v[84:85], v[72:73]
	v_mov_b32_e32 v81, v55
	v_mul_f32_e32 v54, v72, v73
	v_cvt_pk_bf16_f32 v72, v46, v54
	v_mul_f32_e32 v46, 0xbfb8aa3b, v74
	v_exp_f32_e32 v46, v46
	v_mul_f32_e32 v54, 0xbfb8aa3b, v80
	v_exp_f32_e32 v54, v54
	s_ashr_i32 s52, s0, 5
	v_add_f32_e32 v46, 1.0, v46
	v_rcp_f32_e32 v82, v46
	v_add_f32_e32 v54, 1.0, v54
	v_rcp_f32_e32 v86, v54
	s_ashr_i32 s53, s52, 31
	v_pk_mul_f32 v[74:75], v[82:83], v[74:75]
	s_ashr_i32 s54, s22, 5
	v_mul_f32_e32 v46, v74, v75
	v_pk_mul_f32 v[74:75], v[86:87], v[80:81]
	v_mov_b32_e32 v81, v64
	v_mul_f32_e32 v54, v74, v75
	v_cvt_pk_bf16_f32 v73, v46, v54
	s_waitcnt vmcnt(6)
	v_lshlrev_b32_e32 v54, 16, v70
	v_mul_f32_e32 v46, 0xbfb8aa3b, v54
	v_exp_f32_e32 v46, v46
	v_and_b32_e32 v70, 0xffff0000, v70
	v_lshl_add_u64 v[74:75], v[52:53], 0, s[44:45]
	v_lshlrev_b64 v[74:75], 10, v[74:75]
	v_add_f32_e32 v46, 1.0, v46
	v_rcp_f32_e32 v80, v46
	v_lshl_add_u64 v[74:75], v[44:45], 0, v[74:75]
	v_lshl_add_u64 v[74:75], v[74:75], 0, v[184:185]
	global_store_dwordx2 v[74:75], v[72:73], off nt
	v_pk_mul_f32 v[80:81], v[80:81], v[54:55]
	v_mul_f32_e32 v54, 0xbfb8aa3b, v70
	v_exp_f32_e32 v54, v54
	v_lshlrev_b32_e32 v72, 16, v71
	v_and_b32_e32 v74, 0xffff0000, v71
	v_mov_b32_e32 v71, v55
	v_add_f32_e32 v54, 1.0, v54
	v_rcp_f32_e32 v64, v54
	v_mul_f32_e32 v46, v80, v81
	v_mov_b32_e32 v75, v55
	v_mov_b32_e32 v73, v55
	v_pk_mul_f32 v[64:65], v[64:65], v[70:71]
	v_mov_b32_e32 v71, v66
	v_mul_f32_e32 v54, v64, v65
	v_cvt_pk_bf16_f32 v64, v46, v54
	v_mul_f32_e32 v54, 0xbfb8aa3b, v74
	v_mul_f32_e32 v46, 0xbfb8aa3b, v72
	v_exp_f32_e32 v54, v54
	v_exp_f32_e32 v46, v46
	s_ashr_i32 s55, s54, 31
	v_add_f32_e32 v54, 1.0, v54
	v_add_f32_e32 v46, 1.0, v46
	v_rcp_f32_e32 v66, v54
	v_rcp_f32_e32 v70, v46
	v_pk_mul_f32 v[66:67], v[66:67], v[74:75]
	v_pk_mul_f32 v[70:71], v[70:71], v[72:73]
	v_mul_f32_e32 v54, v66, v67
	v_mul_f32_e32 v46, v70, v71
	v_cvt_pk_bf16_f32 v65, v46, v54
	s_waitcnt vmcnt(6)
	v_lshlrev_b32_e32 v54, 16, v68
	v_mul_f32_e32 v46, 0xbfb8aa3b, v54
	v_exp_f32_e32 v46, v46
	v_lshl_add_u64 v[66:67], v[52:53], 0, s[46:47]
	v_lshlrev_b64 v[66:67], 10, v[66:67]
	v_lshl_add_u64 v[66:67], v[44:45], 0, v[66:67]
	v_add_f32_e32 v46, 1.0, v46
	v_rcp_f32_e32 v70, v46
	v_lshl_add_u64 v[66:67], v[66:67], 0, v[184:185]
	global_store_dwordx2 v[66:67], v[64:65], off offset:512 nt
	v_and_b32_e32 v64, 0xffff0000, v68
	v_mov_b32_e32 v71, v60
	v_pk_mul_f32 v[70:71], v[70:71], v[54:55]
	v_mul_f32_e32 v54, 0xbfb8aa3b, v64
	v_exp_f32_e32 v54, v54
	v_mov_b32_e32 v65, v55
	v_and_b32_e32 v68, 0xffff0000, v69
	v_lshlrev_b32_e32 v66, 16, v69
	v_add_f32_e32 v54, 1.0, v54
	v_rcp_f32_e32 v60, v54
	v_mul_f32_e32 v46, v70, v71
	v_mov_b32_e32 v69, v55
	v_mov_b32_e32 v67, v55
	v_pk_mul_f32 v[60:61], v[60:61], v[64:65]
	v_mov_b32_e32 v65, v62
	v_mul_f32_e32 v54, v60, v61
	v_cvt_pk_bf16_f32 v60, v46, v54
	v_mul_f32_e32 v54, 0xbfb8aa3b, v68
	v_mul_f32_e32 v46, 0xbfb8aa3b, v66
	v_exp_f32_e32 v54, v54
	v_exp_f32_e32 v46, v46
	v_add_f32_e32 v54, 1.0, v54
	v_add_f32_e32 v46, 1.0, v46
	v_rcp_f32_e32 v62, v54
	v_rcp_f32_e32 v64, v46
	v_pk_mul_f32 v[62:63], v[62:63], v[68:69]
	v_pk_mul_f32 v[64:65], v[64:65], v[66:67]
	v_mul_f32_e32 v54, v62, v63
	v_mul_f32_e32 v46, v64, v65
	v_cvt_pk_bf16_f32 v61, v46, v54
	s_waitcnt vmcnt(6)
	v_lshlrev_b32_e32 v54, 16, v58
	v_and_b32_e32 v58, 0xffff0000, v58
	v_mov_b32_e32 v65, v40
	v_mul_f32_e32 v40, 0xbfb8aa3b, v58
	v_exp_f32_e32 v40, v40
	v_lshl_add_u64 v[62:63], v[52:53], 0, s[48:49]
	v_lshlrev_b64 v[62:63], 10, v[62:63]
	v_lshl_add_u64 v[62:63], v[44:45], 0, v[62:63]
	v_add_f32_e32 v40, 1.0, v40
	v_rcp_f32_e32 v40, v40
	v_lshl_add_u64 v[62:63], v[62:63], 0, v[184:185]
	global_store_dwordx2 v[62:63], v[60:61], off nt
	v_lshlrev_b32_e32 v60, 16, v59
	v_and_b32_e32 v62, 0xffff0000, v59
	v_mov_b32_e32 v59, v55
	v_pk_mul_f32 v[40:41], v[40:41], v[58:59]
	v_mov_b32_e32 v59, v42
	v_mul_f32_e32 v40, v40, v41
	v_mul_f32_e32 v41, 0xbfb8aa3b, v60
	v_mul_f32_e32 v42, 0xbfb8aa3b, v62
	v_mul_f32_e32 v46, 0xbfb8aa3b, v54
	v_exp_f32_e32 v41, v41
	v_exp_f32_e32 v42, v42
	v_exp_f32_e32 v46, v46
	v_mov_b32_e32 v61, v55
	v_add_f32_e32 v41, 1.0, v41
	v_add_f32_e32 v42, 1.0, v42
	v_add_f32_e32 v46, 1.0, v46
	v_rcp_f32_e32 v58, v41
	v_rcp_f32_e32 v42, v42
	v_rcp_f32_e32 v64, v46
	v_mov_b32_e32 v63, v55
	v_pk_mul_f32 v[58:59], v[58:59], v[60:61]
	v_pk_mul_f32 v[42:43], v[42:43], v[62:63]
	v_pk_mul_f32 v[64:65], v[64:65], v[54:55]
	v_mul_f32_e32 v41, v58, v59
	v_mul_f32_e32 v42, v42, v43
	v_mul_f32_e32 v46, v64, v65
	v_cvt_pk_bf16_f32 v40, v46, v40
	v_cvt_pk_bf16_f32 v41, v41, v42
	v_lshl_add_u64 v[42:43], v[52:53], 0, s[50:51]
	v_lshlrev_b64 v[42:43], 10, v[42:43]
	v_lshl_add_u64 v[42:43], v[44:45], 0, v[42:43]
	v_lshl_add_u64 v[42:43], v[42:43], 0, v[184:185]
	global_store_dwordx2 v[42:43], v[40:41], off offset:512 nt
	s_waitcnt vmcnt(7)
	v_and_b32_e32 v40, 0xffff0000, v56
	v_mov_b32_e32 v59, v36
	v_mul_f32_e32 v36, 0xbfb8aa3b, v40
	v_exp_f32_e32 v36, v36
	v_lshlrev_b32_e32 v54, 16, v56
	v_mul_f32_e32 v41, 0xbfb8aa3b, v54
	v_exp_f32_e32 v41, v41
	v_add_f32_e32 v36, 1.0, v36
	v_rcp_f32_e32 v36, v36
	v_lshlrev_b32_e32 v42, 16, v57
	v_add_f32_e32 v41, 1.0, v41
	v_rcp_f32_e32 v58, v41
	v_mov_b32_e32 v41, v55
	v_and_b32_e32 v56, 0xffff0000, v57
	v_pk_mul_f32 v[36:37], v[36:37], v[40:41]
	v_mov_b32_e32 v41, v38
	v_mul_f32_e32 v36, v36, v37
	v_mul_f32_e32 v37, 0xbfb8aa3b, v42
	v_mul_f32_e32 v38, 0xbfb8aa3b, v56
	v_exp_f32_e32 v37, v37
	v_exp_f32_e32 v38, v38
	v_pk_mul_f32 v[58:59], v[58:59], v[54:55]
	v_mov_b32_e32 v57, v55
	v_add_f32_e32 v37, 1.0, v37
	v_add_f32_e32 v38, 1.0, v38
	v_rcp_f32_e32 v40, v37
	v_rcp_f32_e32 v38, v38
	v_mul_f32_e32 v43, v58, v59
	v_cvt_pk_bf16_f32 v36, v43, v36
	v_mov_b32_e32 v43, v55
	v_pk_mul_f32 v[40:41], v[40:41], v[42:43]
	v_pk_mul_f32 v[38:39], v[38:39], v[56:57]
	v_mul_f32_e32 v37, v40, v41
	v_mul_f32_e32 v38, v38, v39
	v_cvt_pk_bf16_f32 v37, v37, v38
	v_lshl_add_u64 v[38:39], v[52:53], 0, s[52:53]
	v_lshlrev_b64 v[38:39], 10, v[38:39]
	v_lshl_add_u64 v[38:39], v[44:45], 0, v[38:39]
	v_lshl_add_u64 v[38:39], v[38:39], 0, v[184:185]
	global_store_dwordx2 v[38:39], v[36:37], off nt
	s_waitcnt vmcnt(7)
	v_and_b32_e32 v36, 0xffff0000, v50
	v_mov_b32_e32 v43, v32
	v_mul_f32_e32 v32, 0xbfb8aa3b, v36
	v_exp_f32_e32 v32, v32
	v_lshlrev_b32_e32 v54, 16, v50
	v_mul_f32_e32 v37, 0xbfb8aa3b, v54
	v_exp_f32_e32 v37, v37
	v_add_f32_e32 v32, 1.0, v32
	v_rcp_f32_e32 v32, v32
	v_lshlrev_b32_e32 v38, 16, v51
	v_add_f32_e32 v37, 1.0, v37
	v_rcp_f32_e32 v42, v37
	v_mov_b32_e32 v37, v55
	v_and_b32_e32 v40, 0xffff0000, v51
	v_pk_mul_f32 v[32:33], v[32:33], v[36:37]
	v_mov_b32_e32 v37, v34
	v_mul_f32_e32 v32, v32, v33
	v_mul_f32_e32 v33, 0xbfb8aa3b, v38
	v_mul_f32_e32 v34, 0xbfb8aa3b, v40
	v_exp_f32_e32 v33, v33
	v_exp_f32_e32 v34, v34
	v_pk_mul_f32 v[42:43], v[42:43], v[54:55]
	v_mov_b32_e32 v41, v55
	v_add_f32_e32 v33, 1.0, v33
	v_add_f32_e32 v34, 1.0, v34
	v_rcp_f32_e32 v36, v33
	v_rcp_f32_e32 v34, v34
	v_mul_f32_e32 v39, v42, v43
	v_cvt_pk_bf16_f32 v32, v39, v32
	v_mov_b32_e32 v39, v55
	v_pk_mul_f32 v[36:37], v[36:37], v[38:39]
	v_pk_mul_f32 v[34:35], v[34:35], v[40:41]
	v_mul_f32_e32 v33, v36, v37
	v_mul_f32_e32 v34, v34, v35
	v_cvt_pk_bf16_f32 v33, v33, v34
	v_lshl_add_u64 v[34:35], v[52:53], 0, s[54:55]
	v_lshlrev_b64 v[34:35], 10, v[34:35]
	v_lshl_add_u64 v[34:35], v[44:45], 0, v[34:35]
	v_lshl_add_u64 v[34:35], v[34:35], 0, v[184:185]
	v_or_b32_e32 v46, s17, v78
	global_store_dwordx2 v[34:35], v[32:33], off offset:512 nt
	v_lshlrev_b64 v[32:33], 2, v[46:47]
	v_and_b32_e32 v33, 0x7fffff, v33
	v_and_b32_e32 v32, 0xffffffc0, v32
	v_lshl_add_u64 v[34:35], v[32:33], 0, s[10:11]
	v_lshlrev_b64 v[34:35], 9, v[34:35]
	v_lshl_add_u64 v[34:35], v[48:49], 0, v[34:35]
	global_load_dwordx2 v[56:57], v[34:35], off nt
	v_lshl_add_u64 v[34:35], v[32:33], 0, s[18:19]
	v_lshlrev_b64 v[34:35], 9, v[34:35]
	v_lshl_add_u64 v[34:35], v[48:49], 0, v[34:35]
	global_load_dwordx2 v[54:55], v[34:35], off nt
	v_lshl_add_u64 v[34:35], v[32:33], 0, s[20:21]
	v_lshlrev_b64 v[34:35], 9, v[34:35]
	v_lshl_add_u64 v[34:35], v[48:49], 0, v[34:35]
	global_load_dwordx2 v[52:53], v[34:35], off nt
	v_lshl_add_u64 v[34:35], v[32:33], 0, s[24:25]
	v_lshlrev_b64 v[34:35], 9, v[34:35]
	v_lshl_add_u64 v[34:35], v[48:49], 0, v[34:35]
	global_load_dwordx2 v[50:51], v[34:35], off nt
	v_lshl_add_u64 v[34:35], v[32:33], 0, s[34:35]
	v_lshlrev_b64 v[34:35], 9, v[34:35]
	v_lshl_add_u64 v[34:35], v[48:49], 0, v[34:35]
	global_load_dwordx2 v[42:43], v[34:35], off nt
	v_lshl_add_u64 v[34:35], v[32:33], 0, s[36:37]
	v_lshlrev_b64 v[34:35], 9, v[34:35]
	v_lshl_add_u64 v[34:35], v[48:49], 0, v[34:35]
	global_load_dwordx2 v[40:41], v[34:35], off nt
	v_lshl_add_u64 v[34:35], v[32:33], 0, s[38:39]
	v_lshl_add_u64 v[32:33], v[32:33], 0, s[40:41]
	v_lshlrev_b64 v[34:35], 9, v[34:35]
	v_lshlrev_b64 v[32:33], 9, v[32:33]
	v_lshl_add_u64 v[34:35], v[48:49], 0, v[34:35]
	v_lshl_add_u64 v[32:33], v[48:49], 0, v[32:33]
	v_mul_f32_e32 v48, v29, v29
	v_fmac_f32_e32 v48, v28, v28
	v_fmac_f32_e32 v48, v30, v30
	v_fmac_f32_e32 v48, v31, v31
	v_fmac_f32_e32 v48, v24, v24
	v_fmac_f32_e32 v48, v25, v25
	v_fmac_f32_e32 v48, v26, v26
	v_fmac_f32_e32 v48, v27, v27
	v_fmac_f32_e32 v48, v20, v20
	v_fmac_f32_e32 v48, v21, v21
	v_fmac_f32_e32 v48, v22, v22
	v_fmac_f32_e32 v48, v23, v23
	v_fmac_f32_e32 v48, v16, v16
	v_fmac_f32_e32 v48, v17, v17
	v_fmac_f32_e32 v48, v18, v18
	v_fmac_f32_e32 v48, v19, v19
	v_fmac_f32_e32 v48, v12, v12
	v_fmac_f32_e32 v48, v13, v13
	v_fmac_f32_e32 v48, v14, v14
	v_fmac_f32_e32 v48, v15, v15
	v_fmac_f32_e32 v48, v8, v8
	v_fmac_f32_e32 v48, v9, v9
	v_fmac_f32_e32 v48, v10, v10
	v_fmac_f32_e32 v48, v11, v11
	v_pk_mul_f32 v[36:37], v[4:5], v[4:5]
	global_load_dwordx2 v[38:39], v[34:35], off nt
	v_add_f32_e32 v36, v36, v48
	global_load_dwordx2 v[32:33], v[32:33], off nt
	v_pk_mul_f32 v[34:35], v[6:7], v[6:7]
	v_add_f32_e32 v36, v37, v36
	v_add_f32_e32 v34, v34, v36
	v_add_f32_e32 v48, v35, v34
	v_pk_mul_f32 v[36:37], v[0:1], v[0:1]
	v_pk_mul_f32 v[34:35], v[2:3], v[2:3]
	v_add_f32_e32 v36, v36, v48
	v_add_f32_e32 v36, v37, v36
	v_add_f32_e32 v34, v34, v36
	v_add_f32_e32 v34, v35, v34
	ds_bpermute_b32 v35, v77, v34
	v_mov_b32_e32 v59, v28
	s_waitcnt lgkmcnt(0)
	v_add_f32_e32 v34, v34, v35
	ds_bpermute_b32 v35, v76, v34
	s_waitcnt lgkmcnt(0)
	v_add_f32_e32 v34, v34, v35
	v_fmamk_f32 v34, v34, 0x3c000000, v227
	v_cmp_gt_f32_e32 vcc, s15, v34
	v_mul_f32_e32 v35, 0x4b800000, v34
	s_waitcnt vmcnt(7)
	v_lshlrev_b32_e32 v36, 16, v56
	v_cndmask_b32_e32 v34, v34, v35, vcc
	v_rsq_f32_e32 v34, v34
	v_lshlrev_b32_e32 v48, 16, v57
	v_mul_f32_e32 v35, 0x45800000, v34
	v_cndmask_b32_e32 v37, v34, v35, vcc
	v_lshlrev_b64 v[34:35], 1, v[46:47]
	v_and_b32_e32 v46, 0xffff0000, v56
	v_mul_f32_e32 v28, 0xbfb8aa3b, v46
	v_exp_f32_e32 v28, v28
	v_mul_f32_e32 v47, 0xbfb8aa3b, v36
	v_exp_f32_e32 v47, v47
	v_and_b32_e32 v56, 0xffff0000, v57
	v_add_f32_e32 v28, 1.0, v28
	v_rcp_f32_e32 v28, v28
	v_add_f32_e32 v47, 1.0, v47
	v_rcp_f32_e32 v58, v47
	v_mov_b32_e32 v47, v37
	v_pk_mul_f32 v[28:29], v[28:29], v[46:47]
	v_mov_b32_e32 v47, v30
	v_mul_f32_e32 v28, v28, v29
	v_mul_f32_e32 v29, 0xbfb8aa3b, v48
	v_mul_f32_e32 v30, 0xbfb8aa3b, v56
	v_exp_f32_e32 v29, v29
	v_exp_f32_e32 v30, v30
	v_mov_b32_e32 v49, v37
	v_mov_b32_e32 v57, v37
	v_add_f32_e32 v29, 1.0, v29
	v_add_f32_e32 v30, 1.0, v30
	v_rcp_f32_e32 v46, v29
	v_rcp_f32_e32 v30, v30
	v_and_b32_e32 v35, 0x3fffff, v35
	v_and_b32_e32 v34, 0xffffffe0, v34
	v_pk_mul_f32 v[46:47], v[46:47], v[48:49]
	v_pk_mul_f32 v[30:31], v[30:31], v[56:57]
	v_pk_mul_f32 v[58:59], v[58:59], v[36:37]
	v_mul_f32_e32 v29, v46, v47
	v_mul_f32_e32 v30, v30, v31
	v_mul_f32_e32 v36, v58, v59
	v_cvt_pk_bf16_f32 v28, v36, v28
	v_cvt_pk_bf16_f32 v29, v29, v30
	v_lshl_add_u64 v[30:31], v[34:35], 0, s[42:43]
	v_lshlrev_b64 v[30:31], 10, v[30:31]
	v_lshl_add_u64 v[30:31], v[44:45], 0, v[30:31]
	v_lshl_add_u64 v[30:31], v[30:31], 0, v[184:185]
	global_store_dwordx2 v[30:31], v[28:29], off nt
	s_waitcnt vmcnt(7)
	v_and_b32_e32 v28, 0xffff0000, v54
	v_mov_b32_e32 v49, v24
	v_mul_f32_e32 v24, 0xbfb8aa3b, v28
	v_exp_f32_e32 v24, v24
	v_lshlrev_b32_e32 v36, 16, v54
	v_mul_f32_e32 v29, 0xbfb8aa3b, v36
	v_exp_f32_e32 v29, v29
	v_add_f32_e32 v24, 1.0, v24
	v_rcp_f32_e32 v24, v24
	v_lshlrev_b32_e32 v30, 16, v55
	v_add_f32_e32 v29, 1.0, v29
	v_rcp_f32_e32 v48, v29
	v_mov_b32_e32 v29, v37
	v_and_b32_e32 v46, 0xffff0000, v55
	v_pk_mul_f32 v[24:25], v[24:25], v[28:29]
	v_mov_b32_e32 v29, v26
	v_mul_f32_e32 v24, v24, v25
	v_mul_f32_e32 v25, 0xbfb8aa3b, v30
	v_mul_f32_e32 v26, 0xbfb8aa3b, v46
	v_exp_f32_e32 v25, v25
	v_exp_f32_e32 v26, v26
	v_pk_mul_f32 v[48:49], v[48:49], v[36:37]
	v_mov_b32_e32 v47, v37
	v_add_f32_e32 v25, 1.0, v25
	v_add_f32_e32 v26, 1.0, v26
	v_rcp_f32_e32 v28, v25
	v_rcp_f32_e32 v26, v26
	v_mul_f32_e32 v31, v48, v49
	v_cvt_pk_bf16_f32 v24, v31, v24
	v_mov_b32_e32 v31, v37
	v_pk_mul_f32 v[28:29], v[28:29], v[30:31]
	v_pk_mul_f32 v[26:27], v[26:27], v[46:47]
	v_mul_f32_e32 v25, v28, v29
	v_mul_f32_e32 v26, v26, v27
	v_cvt_pk_bf16_f32 v25, v25, v26
	v_lshl_add_u64 v[26:27], v[34:35], 0, s[12:13]
	v_lshlrev_b64 v[26:27], 10, v[26:27]
	v_lshl_add_u64 v[26:27], v[44:45], 0, v[26:27]
	v_lshl_add_u64 v[26:27], v[26:27], 0, v[184:185]
	global_store_dwordx2 v[26:27], v[24:25], off offset:512 nt
	s_waitcnt vmcnt(7)
	v_and_b32_e32 v24, 0xffff0000, v52
	v_mov_b32_e32 v31, v20
	v_mul_f32_e32 v20, 0xbfb8aa3b, v24
	v_exp_f32_e32 v20, v20
	v_lshlrev_b32_e32 v36, 16, v52
	v_mul_f32_e32 v25, 0xbfb8aa3b, v36
	v_exp_f32_e32 v25, v25
	v_add_f32_e32 v20, 1.0, v20
	v_rcp_f32_e32 v20, v20
	v_lshlrev_b32_e32 v26, 16, v53
	v_add_f32_e32 v25, 1.0, v25
	v_rcp_f32_e32 v30, v25
	v_mov_b32_e32 v25, v37
	v_and_b32_e32 v28, 0xffff0000, v53
	v_pk_mul_f32 v[20:21], v[20:21], v[24:25]
	v_mov_b32_e32 v25, v22
	v_mul_f32_e32 v20, v20, v21
	v_mul_f32_e32 v21, 0xbfb8aa3b, v26
	v_mul_f32_e32 v22, 0xbfb8aa3b, v28
	v_exp_f32_e32 v21, v21
	v_exp_f32_e32 v22, v22
	v_pk_mul_f32 v[30:31], v[30:31], v[36:37]
	v_mov_b32_e32 v29, v37
	v_add_f32_e32 v21, 1.0, v21
	v_add_f32_e32 v22, 1.0, v22
	v_rcp_f32_e32 v24, v21
	v_rcp_f32_e32 v22, v22
	v_mul_f32_e32 v27, v30, v31
	v_cvt_pk_bf16_f32 v20, v27, v20
	v_mov_b32_e32 v27, v37
	v_pk_mul_f32 v[24:25], v[24:25], v[26:27]
	v_pk_mul_f32 v[22:23], v[22:23], v[28:29]
	v_mul_f32_e32 v21, v24, v25
	v_mul_f32_e32 v22, v22, v23
	v_cvt_pk_bf16_f32 v21, v21, v22
	v_lshl_add_u64 v[22:23], v[34:35], 0, s[44:45]
	v_lshlrev_b64 v[22:23], 10, v[22:23]
	v_lshl_add_u64 v[22:23], v[44:45], 0, v[22:23]
	v_lshl_add_u64 v[22:23], v[22:23], 0, v[184:185]
	global_store_dwordx2 v[22:23], v[20:21], off nt
	s_waitcnt vmcnt(7)
	v_and_b32_e32 v20, 0xffff0000, v50
	v_mov_b32_e32 v27, v16
	v_mul_f32_e32 v16, 0xbfb8aa3b, v20
	v_exp_f32_e32 v16, v16
	v_lshlrev_b32_e32 v36, 16, v50
	v_mul_f32_e32 v21, 0xbfb8aa3b, v36
	v_exp_f32_e32 v21, v21
	v_add_f32_e32 v16, 1.0, v16
	v_rcp_f32_e32 v16, v16
	v_lshlrev_b32_e32 v22, 16, v51
	v_add_f32_e32 v21, 1.0, v21
	v_rcp_f32_e32 v26, v21
	v_mov_b32_e32 v21, v37
	v_and_b32_e32 v24, 0xffff0000, v51
	v_pk_mul_f32 v[16:17], v[16:17], v[20:21]
	v_mov_b32_e32 v21, v18
	v_mul_f32_e32 v16, v16, v17
	v_mul_f32_e32 v17, 0xbfb8aa3b, v22
	v_mul_f32_e32 v18, 0xbfb8aa3b, v24
	v_exp_f32_e32 v17, v17
	v_exp_f32_e32 v18, v18
	v_pk_mul_f32 v[26:27], v[26:27], v[36:37]
	v_mov_b32_e32 v25, v37
	v_add_f32_e32 v17, 1.0, v17
	v_add_f32_e32 v18, 1.0, v18
	v_rcp_f32_e32 v20, v17
	v_rcp_f32_e32 v18, v18
	v_mul_f32_e32 v23, v26, v27
	v_cvt_pk_bf16_f32 v16, v23, v16
	v_mov_b32_e32 v23, v37
	v_pk_mul_f32 v[20:21], v[20:21], v[22:23]
	v_pk_mul_f32 v[18:19], v[18:19], v[24:25]
	v_mul_f32_e32 v17, v20, v21
	v_mul_f32_e32 v18, v18, v19
	v_cvt_pk_bf16_f32 v17, v17, v18
	v_lshl_add_u64 v[18:19], v[34:35], 0, s[46:47]
	v_lshlrev_b64 v[18:19], 10, v[18:19]
	v_lshl_add_u64 v[18:19], v[44:45], 0, v[18:19]
	v_lshl_add_u64 v[18:19], v[18:19], 0, v[184:185]
	global_store_dwordx2 v[18:19], v[16:17], off offset:512 nt
	s_waitcnt vmcnt(7)
	v_and_b32_e32 v16, 0xffff0000, v42
	v_mov_b32_e32 v23, v12
	v_mul_f32_e32 v12, 0xbfb8aa3b, v16
	v_exp_f32_e32 v12, v12
	v_lshlrev_b32_e32 v36, 16, v42
	v_mul_f32_e32 v17, 0xbfb8aa3b, v36
	v_exp_f32_e32 v17, v17
	v_add_f32_e32 v12, 1.0, v12
	v_rcp_f32_e32 v12, v12
	v_lshlrev_b32_e32 v18, 16, v43
	v_add_f32_e32 v17, 1.0, v17
	v_rcp_f32_e32 v22, v17
	v_mov_b32_e32 v17, v37
	v_and_b32_e32 v20, 0xffff0000, v43
	v_pk_mul_f32 v[12:13], v[12:13], v[16:17]
	v_mov_b32_e32 v17, v14
	v_mul_f32_e32 v12, v12, v13
	v_mul_f32_e32 v13, 0xbfb8aa3b, v18
	v_mul_f32_e32 v14, 0xbfb8aa3b, v20
	v_exp_f32_e32 v13, v13
	v_exp_f32_e32 v14, v14
	v_pk_mul_f32 v[22:23], v[22:23], v[36:37]
	v_mov_b32_e32 v21, v37
	v_add_f32_e32 v13, 1.0, v13
	v_add_f32_e32 v14, 1.0, v14
	v_rcp_f32_e32 v16, v13
	v_rcp_f32_e32 v14, v14
	v_mul_f32_e32 v19, v22, v23
	v_cvt_pk_bf16_f32 v12, v19, v12
	v_mov_b32_e32 v19, v37
	v_pk_mul_f32 v[16:17], v[16:17], v[18:19]
	v_pk_mul_f32 v[14:15], v[14:15], v[20:21]
	v_mul_f32_e32 v13, v16, v17
	v_mul_f32_e32 v14, v14, v15
	v_cvt_pk_bf16_f32 v13, v13, v14
	v_lshl_add_u64 v[14:15], v[34:35], 0, s[48:49]
	v_lshlrev_b64 v[14:15], 10, v[14:15]
	v_lshl_add_u64 v[14:15], v[44:45], 0, v[14:15]
	v_lshl_add_u64 v[14:15], v[14:15], 0, v[184:185]
	global_store_dwordx2 v[14:15], v[12:13], off nt
	s_waitcnt vmcnt(7)
	v_and_b32_e32 v12, 0xffff0000, v40
	v_mov_b32_e32 v19, v8
	v_mul_f32_e32 v8, 0xbfb8aa3b, v12
	v_exp_f32_e32 v8, v8
	v_lshlrev_b32_e32 v36, 16, v40
	v_mul_f32_e32 v13, 0xbfb8aa3b, v36
	v_exp_f32_e32 v13, v13
	v_add_f32_e32 v8, 1.0, v8
	v_rcp_f32_e32 v8, v8
	v_lshlrev_b32_e32 v14, 16, v41
	v_add_f32_e32 v13, 1.0, v13
	v_rcp_f32_e32 v18, v13
	v_mov_b32_e32 v13, v37
	v_and_b32_e32 v16, 0xffff0000, v41
	v_pk_mul_f32 v[8:9], v[8:9], v[12:13]
	v_mov_b32_e32 v13, v10
	v_mul_f32_e32 v8, v8, v9
	v_mul_f32_e32 v9, 0xbfb8aa3b, v14
	v_mul_f32_e32 v10, 0xbfb8aa3b, v16
	v_exp_f32_e32 v9, v9
	v_exp_f32_e32 v10, v10
	v_pk_mul_f32 v[18:19], v[18:19], v[36:37]
	v_mov_b32_e32 v17, v37
	v_add_f32_e32 v9, 1.0, v9
	v_add_f32_e32 v10, 1.0, v10
	v_rcp_f32_e32 v12, v9
	v_rcp_f32_e32 v10, v10
	v_mul_f32_e32 v15, v18, v19
	v_cvt_pk_bf16_f32 v8, v15, v8
	v_mov_b32_e32 v15, v37
	v_pk_mul_f32 v[12:13], v[12:13], v[14:15]
	v_pk_mul_f32 v[10:11], v[10:11], v[16:17]
	v_mul_f32_e32 v9, v12, v13
	v_mul_f32_e32 v10, v10, v11
	v_cvt_pk_bf16_f32 v9, v9, v10
	v_lshl_add_u64 v[10:11], v[34:35], 0, s[50:51]
	v_lshlrev_b64 v[10:11], 10, v[10:11]
	v_lshl_add_u64 v[10:11], v[44:45], 0, v[10:11]
	v_lshl_add_u64 v[10:11], v[10:11], 0, v[184:185]
	global_store_dwordx2 v[10:11], v[8:9], off offset:512 nt
	s_waitcnt vmcnt(7)
	v_and_b32_e32 v8, 0xffff0000, v38
	v_mov_b32_e32 v15, v4
	v_mul_f32_e32 v4, 0xbfb8aa3b, v8
	v_exp_f32_e32 v4, v4
	v_lshlrev_b32_e32 v36, 16, v38
	v_mul_f32_e32 v9, 0xbfb8aa3b, v36
	v_exp_f32_e32 v9, v9
	v_add_f32_e32 v4, 1.0, v4
	v_rcp_f32_e32 v4, v4
	v_lshlrev_b32_e32 v10, 16, v39
	v_add_f32_e32 v9, 1.0, v9
	v_rcp_f32_e32 v14, v9
	v_mov_b32_e32 v9, v37
	v_and_b32_e32 v12, 0xffff0000, v39
	v_pk_mul_f32 v[4:5], v[4:5], v[8:9]
	v_mov_b32_e32 v9, v6
	v_mul_f32_e32 v4, v4, v5
	v_mul_f32_e32 v5, 0xbfb8aa3b, v10
	v_mul_f32_e32 v6, 0xbfb8aa3b, v12
	v_exp_f32_e32 v5, v5
	v_exp_f32_e32 v6, v6
	v_pk_mul_f32 v[14:15], v[14:15], v[36:37]
	v_mov_b32_e32 v13, v37
	v_add_f32_e32 v5, 1.0, v5
	v_add_f32_e32 v6, 1.0, v6
	v_rcp_f32_e32 v8, v5
	v_rcp_f32_e32 v6, v6
	v_mul_f32_e32 v11, v14, v15
	v_cvt_pk_bf16_f32 v4, v11, v4
	v_mov_b32_e32 v11, v37
	v_pk_mul_f32 v[8:9], v[8:9], v[10:11]
	v_pk_mul_f32 v[6:7], v[6:7], v[12:13]
	v_mul_f32_e32 v5, v8, v9
	v_mul_f32_e32 v6, v6, v7
	v_cvt_pk_bf16_f32 v5, v5, v6
	v_lshl_add_u64 v[6:7], v[34:35], 0, s[52:53]
	v_lshlrev_b64 v[6:7], 10, v[6:7]
	v_lshl_add_u64 v[6:7], v[44:45], 0, v[6:7]
	v_lshl_add_u64 v[6:7], v[6:7], 0, v[184:185]
	global_store_dwordx2 v[6:7], v[4:5], off nt
	s_waitcnt vmcnt(7)
	v_and_b32_e32 v4, 0xffff0000, v32
	v_mov_b32_e32 v11, v0
	v_mul_f32_e32 v0, 0xbfb8aa3b, v4
	v_exp_f32_e32 v0, v0
	v_lshlrev_b32_e32 v36, 16, v32
	v_mul_f32_e32 v5, 0xbfb8aa3b, v36
	v_exp_f32_e32 v5, v5
	v_add_f32_e32 v0, 1.0, v0
	v_rcp_f32_e32 v0, v0
	v_lshlrev_b32_e32 v6, 16, v33
	v_add_f32_e32 v5, 1.0, v5
	v_rcp_f32_e32 v10, v5
	v_mov_b32_e32 v5, v37
	v_and_b32_e32 v8, 0xffff0000, v33
	v_pk_mul_f32 v[0:1], v[0:1], v[4:5]
	v_mov_b32_e32 v5, v2
	v_mul_f32_e32 v0, v0, v1
	v_mul_f32_e32 v1, 0xbfb8aa3b, v6
	v_mul_f32_e32 v2, 0xbfb8aa3b, v8
	v_exp_f32_e32 v1, v1
	v_exp_f32_e32 v2, v2
	v_pk_mul_f32 v[10:11], v[10:11], v[36:37]
	v_mov_b32_e32 v9, v37
	v_add_f32_e32 v1, 1.0, v1
	v_add_f32_e32 v2, 1.0, v2
	v_rcp_f32_e32 v4, v1
	v_rcp_f32_e32 v2, v2
	v_mul_f32_e32 v7, v10, v11
	v_cvt_pk_bf16_f32 v0, v7, v0
	v_mov_b32_e32 v7, v37
	v_pk_mul_f32 v[4:5], v[4:5], v[6:7]
	v_pk_mul_f32 v[2:3], v[2:3], v[8:9]
	v_mul_f32_e32 v1, v4, v5
	v_mul_f32_e32 v2, v2, v3
	v_cvt_pk_bf16_f32 v1, v1, v2
	v_lshl_add_u64 v[2:3], v[34:35], 0, s[54:55]
.LBB0_745:
	v_lshlrev_b64 v[2:3], 10, v[2:3]
	v_readlane_b32 s0, v255, 29
	v_lshl_add_u64 v[2:3], v[44:45], 0, v[2:3]
	v_mov_b32_e32 v185, v197
	s_add_i32 s16, s16, s62
	s_add_i32 s3, s3, s0
	v_lshl_add_u64 v[2:3], v[2:3], 0, v[184:185]
	s_cmpk_gt_i32 s16, 0xff
	global_store_dwordx2 v[2:3], v[0:1], off offset:512 nt
	s_cbranch_scc1 .LBB0_801

.Lscan_done:
	s_add_u32 s6, s10, 0xfe01000
	s_addc_u32 s7, s11, 0
	s_ashr_i32 s42, s5, 7
	s_lshr_b32 s8, s5, 5
	s_and_b32 s22, s5, 0xffffff80
	s_add_i32 s0, s42, s2
	s_and_b32 s70, s8, 2
	s_lshl_b32 s8, s22, 1
	s_ashr_i32 s1, s0, 31
	s_add_i32 s8, s8, 0
	s_lshl_b32 s68, s70, 4
	v_bfe_u32 v34, v136, 4, 2
	s_lshl_b64 s[0:1], s[0:1], 15
	s_add_i32 s8, s8, 0x13c00
	s_or_b32 s17, s68, 16
	v_and_b32_e32 v206, 15, v136
	v_lshlrev_b32_e32 v32, 4, v34
	s_add_u32 s0, s10, s0
	v_add_u32_e32 v0, s8, v32
	v_or_b32_e32 v212, s68, v206
	s_movk_i32 s8, 0x410
	s_addc_u32 s1, s11, s1
	v_mov_b32_e32 v33, v197
	v_mad_u32_u24 v1, v212, s8, v0
	v_lshl_add_u64 v[32:33], s[0:1], 0, v[32:33]
	s_mov_b64 s[0:1], 0x3800000
	s_ashr_i32 s39, s38, 31
	s_barrier
	ds_read_b128 v[28:31], v1
	ds_read_b128 v[24:27], v1 offset:64
	ds_read_b128 v[20:23], v1 offset:128
	ds_read_b128 v[16:19], v1 offset:192
	v_or_b32_e32 v1, s17, v206
	v_lshlrev_b32_e32 v207, 3, v34
	v_lshl_add_u64 v[120:121], v[32:33], 0, s[0:1]
	v_lshlrev_b32_e32 v208, 2, v34
	v_lshl_add_u64 v[34:35], s[10:11], 0, v[196:197]
	s_mov_b64 s[0:1], 0x1c801000
	s_or_b32 s12, s38, s68
	s_mov_b32 s13, s39
	v_mad_u32_u24 v0, v1, s8, v0
	v_lshl_add_u64 v[118:119], v[34:35], 0, s[0:1]
	s_lshl_b64 s[0:1], s[12:13], 2
	s_ashr_i32 s8, s22, 4
	s_and_b32 s20, s1, 0x7fffff
	s_and_b32 s21, s0, 0xffffff80
	s_ashr_i32 s9, s8, 31
	s_add_u32 s0, s21, s8
	v_or_b32_e32 v32, s22, v208
	s_addc_u32 s1, s20, s9
	v_ashrrev_i32_e32 v33, 31, v32
	s_lshl_b64 s[0:1], s[0:1], 9
	s_or_b32 s10, s38, s17
	s_mov_b32 s11, s39
	v_lshl_add_u64 v[122:123], v[32:33], 2, s[66:67]
	v_lshl_add_u64 v[32:33], v[118:119], 0, s[0:1]
	s_lshl_b64 s[0:1], s[10:11], 2
	s_and_b32 s24, s1, 0x7fffff
	s_and_b32 s25, s0, 0xffffffc0
	s_add_u32 s0, s25, s8
	v_lshlrev_b32_e32 v34, 8, v206
	v_mov_b32_e32 v35, v197
	s_addc_u32 s1, s24, s9
	v_lshl_add_u64 v[124:125], v[120:121], 0, v[34:35]
	s_lshl_b64 s[0:1], s[0:1], 9
	ds_read_b128 v[12:15], v0
	ds_read_b128 v[8:11], v0 offset:64
	ds_read_b128 v[4:7], v0 offset:128
	ds_read_b128 v[0:3], v0 offset:192
	v_lshl_add_u64 v[32:33], v[118:119], 0, s[0:1]
	s_or_b32 s0, s22, 16
	s_ashr_i32 s8, s0, 4
	s_ashr_i32 s9, s8, 31
	v_or_b32_e32 v210, 16, v206
	s_add_u32 s0, s21, s8
	v_lshlrev_b32_e32 v32, 8, v210
	v_mov_b32_e32 v33, v197
	s_addc_u32 s1, s20, s9
	v_lshl_add_u64 v[32:33], v[120:121], 0, v[32:33]
	s_lshl_b64 s[0:1], s[0:1], 9
	v_lshl_add_u64 v[32:33], v[118:119], 0, s[0:1]
	s_add_u32 s0, s25, s8
	s_addc_u32 s1, s24, s9
	s_lshl_b64 s[0:1], s[0:1], 9
	v_lshl_add_u64 v[32:33], v[118:119], 0, s[0:1]
	s_or_b32 s0, s22, 32
	s_ashr_i32 s8, s0, 4
	s_ashr_i32 s9, s8, 31
	v_or_b32_e32 v211, 32, v206
	s_add_u32 s0, s21, s8
	v_lshlrev_b32_e32 v32, 8, v211
	v_mov_b32_e32 v33, v197
	s_addc_u32 s1, s20, s9
	v_lshl_add_u64 v[32:33], v[120:121], 0, v[32:33]
	s_lshl_b64 s[0:1], s[0:1], 9
	v_lshl_add_u64 v[32:33], v[118:119], 0, s[0:1]
	s_add_u32 s0, s25, s8
	s_addc_u32 s1, s24, s9
	s_lshl_b64 s[0:1], s[0:1], 9
	v_lshl_add_u64 v[32:33], v[118:119], 0, s[0:1]
	s_or_b32 s0, s22, 48
	s_ashr_i32 s8, s0, 4
	s_ashr_i32 s9, s8, 31
	s_add_u32 s0, s21, s8
	v_or_b32_e32 v209, 48, v206
	s_addc_u32 s1, s20, s9
	v_lshlrev_b32_e32 v32, 8, v209
	v_mov_b32_e32 v33, v197
	s_lshl_b64 s[0:1], s[0:1], 9
	v_lshl_add_u64 v[32:33], v[120:121], 0, v[32:33]
	s_add_u32 s0, s25, s8
	s_addc_u32 s1, s24, s9
	s_lshl_b64 s[0:1], s[0:1], 9
	v_and_b32_e32 v137, 4, v208
	s_nop 0
	s_waitcnt vmcnt(0) lgkmcnt(7)
	v_mov_b32_e32 v32, v148
	v_mov_b32_e32 v33, v149
	v_mov_b32_e32 v34, v150
	v_mov_b32_e32 v35, v151
	v_mfma_f32_16x16x32_bf16 v[138:141], v[108:111], v[28:31], 0
	s_waitcnt vmcnt(23)
	v_lshlrev_b32_e32 v142, 16, v112
	v_lshlrev_b32_e32 v144, 16, v113
	v_and_b32_e32 v146, 0xffff0000, v113
	s_waitcnt lgkmcnt(6)
	v_mfma_f32_16x16x32_bf16 v[138:141], v[104:107], v[24:27], v[138:141]
	v_mul_f32_e32 v113, 0xbfb8aa3b, v142
	v_exp_f32_e32 v113, v113
	v_and_b32_e32 v112, 0xffff0000, v112
	s_waitcnt lgkmcnt(5)
	v_mfma_f32_16x16x32_bf16 v[138:141], v[100:103], v[20:23], v[138:141]
	s_waitcnt vmcnt(21)
	v_mov_b32_e32 v149, v92
	v_add_f32_e32 v113, 1.0, v113
	v_rcp_f32_e32 v148, v113
	s_waitcnt lgkmcnt(4)
	v_mfma_f32_16x16x32_bf16 v[138:141], v[96:99], v[16:19], v[138:141]
	v_mul_f32_e32 v113, 0xbfb8aa3b, v112
	v_exp_f32_e32 v113, v113
	s_lshl_b64 s[0:1], s[12:13], 1
	s_ashr_i32 s26, s22, 5
	s_and_b32 s13, s1, 0x3fffff
	s_nop 2
	v_mov_b32_e32 v143, v138
	v_pk_mul_f32 v[142:143], v[148:149], v[142:143]
	v_add_f32_e32 v113, 1.0, v113
	v_mul_f32_e32 v138, v142, v143
	v_rcp_f32_e32 v142, v113
	v_mov_b32_e32 v143, v93
	v_mov_b32_e32 v113, v139
	v_mov_b32_e32 v145, v140
	v_pk_mul_f32 v[112:113], v[142:143], v[112:113]
	s_and_b32 s19, s0, 0xffffffc0
	v_mul_f32_e32 v112, v112, v113
	v_cvt_pk_bf16_f32 v138, v138, v112
	v_mul_f32_e32 v112, 0xbfb8aa3b, v144
	v_exp_f32_e32 v112, v112
	v_mov_b32_e32 v113, v94
	v_mov_b32_e32 v147, v141
	s_ashr_i32 s27, s26, 31
	v_add_f32_e32 v112, 1.0, v112
	v_rcp_f32_e32 v112, v112
	s_add_u32 s0, s19, s26
	s_addc_u32 s1, s13, s27
	s_lshl_b64 s[0:1], s[0:1], 10
	v_pk_mul_f32 v[112:113], v[112:113], v[144:145]
	s_add_u32 s0, s6, s0
	v_mul_f32_e32 v139, v112, v113
	v_mul_f32_e32 v112, 0xbfb8aa3b, v146
	v_exp_f32_e32 v112, v112
	v_mov_b32_e32 v113, v95
	s_addc_u32 s1, s7, s1
	v_lshlrev_b32_e32 v184, 1, v137
	v_add_f32_e32 v112, 1.0, v112
	v_rcp_f32_e32 v112, v112
	v_mov_b32_e32 v185, v197
	s_waitcnt vmcnt(16)
	v_lshlrev_b32_e32 v142, 16, v116
	v_lshlrev_b32_e32 v144, 16, v117
	v_pk_mul_f32 v[112:113], v[112:113], v[146:147]
	v_and_b32_e32 v146, 0xffff0000, v117
	v_mul_f32_e32 v112, v112, v113
	v_cvt_pk_bf16_f32 v139, v139, v112
	v_lshrrev_b32_e32 v112, 1, v136
	v_and_or_b32 v112, v112, 16, v206
	v_lshlrev_b32_e32 v112, 4, v112
	v_mov_b32_e32 v113, v197
	v_lshl_add_u64 v[140:141], s[0:1], 0, v[112:113]
	v_lshl_add_u64 v[140:141], v[140:141], 0, v[184:185]
	global_store_dwordx2 v[140:141], v[138:139], off nt
	v_mfma_f32_16x16x32_bf16 v[138:141], v[88:91], v[28:31], 0
	v_mul_f32_e32 v117, 0xbfb8aa3b, v142
	v_exp_f32_e32 v117, v117
	v_and_b32_e32 v116, 0xffff0000, v116
	v_mfma_f32_16x16x32_bf16 v[138:141], v[84:87], v[24:27], v[138:141]
	s_waitcnt vmcnt(15)
	v_mov_b32_e32 v149, v72
	v_add_f32_e32 v117, 1.0, v117
	v_rcp_f32_e32 v148, v117
	v_mfma_f32_16x16x32_bf16 v[138:141], v[80:83], v[20:23], v[138:141]
	v_mul_f32_e32 v117, 0xbfb8aa3b, v116
	v_exp_f32_e32 v117, v117
	v_or_b32_e32 v213, 16, v208
	v_mfma_f32_16x16x32_bf16 v[138:141], v[76:79], v[16:19], v[138:141]
	s_or_b32 s33, s26, 1
	v_add_f32_e32 v117, 1.0, v117
	s_ashr_i32 s34, s33, 31
	s_waitcnt lgkmcnt(3)
	v_mfma_f32_16x16x32_bf16 v[108:111], v[108:111], v[12:15], 0
	v_or_b32_e32 v222, 48, v208
	s_nop 1
	v_mov_b32_e32 v143, v138
	v_pk_mul_f32 v[142:143], v[148:149], v[142:143]
	v_mov_b32_e32 v145, v140
	v_mul_f32_e32 v137, v142, v143
	v_rcp_f32_e32 v142, v117
	v_mov_b32_e32 v143, v73
	v_mov_b32_e32 v117, v139
	v_mov_b32_e32 v147, v141
	v_pk_mul_f32 v[116:117], v[142:143], v[116:117]
	s_waitcnt vmcnt(10)
	v_lshlrev_b32_e32 v142, 16, v134
	v_mul_f32_e32 v116, v116, v117
	v_cvt_pk_bf16_f32 v138, v137, v116
	v_mul_f32_e32 v116, 0xbfb8aa3b, v144
	v_exp_f32_e32 v116, v116
	v_mov_b32_e32 v117, v74
	v_and_b32_e32 v134, 0xffff0000, v134
	s_waitcnt vmcnt(8)
	v_mov_b32_e32 v149, v52
	v_add_f32_e32 v116, 1.0, v116
	v_rcp_f32_e32 v116, v116
	s_waitcnt lgkmcnt(2)
	v_mfma_f32_16x16x32_bf16 v[104:107], v[104:107], v[8:11], v[108:111]
	v_or_b32_e32 v238, 0x60, v206
	v_or_b32_e32 v223, 0x70, v206
	v_pk_mul_f32 v[116:117], v[116:117], v[144:145]
	v_lshlrev_b32_e32 v144, 16, v135
	v_mul_f32_e32 v137, v116, v117
	v_mul_f32_e32 v116, 0xbfb8aa3b, v146
	v_exp_f32_e32 v116, v116
	v_mov_b32_e32 v117, v75
	s_waitcnt lgkmcnt(1)
	v_mfma_f32_16x16x32_bf16 v[100:103], v[100:103], v[4:7], v[104:107]
	v_mov_b32_e32 v109, v92
	v_add_f32_e32 v116, 1.0, v116
	v_rcp_f32_e32 v116, v116
	v_mfma_f32_16x16x32_bf16 v[88:91], v[88:91], v[12:15], 0
	v_lshlrev_b32_e32 v104, 16, v133
	v_and_b32_e32 v106, 0xffff0000, v133
	v_pk_mul_f32 v[116:117], v[116:117], v[146:147]
	v_and_b32_e32 v146, 0xffff0000, v135
	v_mul_f32_e32 v116, v116, v117
	v_cvt_pk_bf16_f32 v139, v137, v116
	v_lshlrev_b32_e32 v116, 1, v213
	v_and_or_b32 v116, v116, 48, v206
	v_lshlrev_b32_e32 v116, 4, v116
	v_mov_b32_e32 v117, v197
	v_lshl_add_u64 v[140:141], s[0:1], 0, v[116:117]
	v_lshl_add_u64 v[140:141], v[140:141], 0, v[184:185]
	global_store_dwordx2 v[140:141], v[138:139], off nt
	v_mfma_f32_16x16x32_bf16 v[138:141], v[68:71], v[28:31], 0
	v_mul_f32_e32 v135, 0xbfb8aa3b, v142
	v_exp_f32_e32 v135, v135
	s_add_u32 s0, s19, s33
	v_mfma_f32_16x16x32_bf16 v[138:141], v[64:67], v[24:27], v[138:141]
	s_addc_u32 s1, s13, s34
	v_add_f32_e32 v135, 1.0, v135
	v_rcp_f32_e32 v148, v135
	v_mfma_f32_16x16x32_bf16 v[138:141], v[60:63], v[20:23], v[138:141]
	v_mul_f32_e32 v135, 0xbfb8aa3b, v134
	v_exp_f32_e32 v135, v135
	s_lshl_b64 s[0:1], s[0:1], 10
	v_mfma_f32_16x16x32_bf16 v[138:141], v[56:59], v[16:19], v[138:141]
	s_add_u32 s0, s6, s0
	v_add_f32_e32 v135, 1.0, v135
	s_addc_u32 s1, s7, s1
	s_waitcnt lgkmcnt(0)
	v_mfma_f32_16x16x32_bf16 v[96:99], v[96:99], v[0:3], v[100:103]
	s_nop 2
	v_and_b32_e32 v102, 0xffff0000, v132
	v_mov_b32_e32 v143, v138
	v_pk_mul_f32 v[142:143], v[148:149], v[142:143]
	v_mov_b32_e32 v145, v140
	v_mul_f32_e32 v137, v142, v143
	v_rcp_f32_e32 v142, v135
	v_mov_b32_e32 v143, v53
	v_mov_b32_e32 v135, v139
	v_mov_b32_e32 v139, v54
	v_pk_mul_f32 v[134:135], v[142:143], v[134:135]
	v_mov_b32_e32 v147, v141
	v_mul_f32_e32 v134, v134, v135
	v_mul_f32_e32 v135, 0xbfb8aa3b, v144
	v_exp_f32_e32 v135, v135
	v_cvt_pk_bf16_f32 v134, v137, v134
	v_mul_f32_e32 v137, 0xbfb8aa3b, v146
	v_exp_f32_e32 v137, v137
	v_add_f32_e32 v135, 1.0, v135
	v_rcp_f32_e32 v138, v135
	s_waitcnt vmcnt(2)
	v_lshlrev_b32_e32 v142, 16, v115
	v_add_f32_e32 v137, 1.0, v137
	v_mfma_f32_16x16x32_bf16 v[84:87], v[84:87], v[8:11], v[88:91]
	v_mul_f32_e64 v138, v138, v144
	v_mul_f32_e64 v139, v139, v145
	v_and_b32_e32 v144, 0xffff0000, v115
	v_mul_f32_e32 v135, v138, v139
	v_rcp_f32_e32 v138, v137
	v_mov_b32_e32 v139, v55
	v_mul_f32_e32 v92, 0xbfb8aa3b, v102
	v_exp_f32_e32 v92, v92
	v_pk_mul_f32 v[138:139], v[138:139], v[146:147]
	v_mov_b32_e32 v147, v32
	v_mul_f32_e32 v137, v138, v139
	v_lshl_add_u64 v[138:139], s[0:1], 0, v[112:113]
	v_lshl_add_u64 v[138:139], v[138:139], 0, v[184:185]
	v_cvt_pk_bf16_f32 v135, v135, v137
	global_store_dwordx2 v[138:139], v[134:135], off nt
	v_mfma_f32_16x16x32_bf16 v[138:141], v[48:51], v[28:31], 0
	v_lshlrev_b32_e32 v134, 16, v114
	v_mul_f32_e32 v115, 0xbfb8aa3b, v134
	v_exp_f32_e32 v115, v115
	v_mfma_f32_16x16x32_bf16 v[138:141], v[44:47], v[24:27], v[138:141]
	v_and_b32_e32 v114, 0xffff0000, v114
	v_lshlrev_b32_e32 v100, 16, v132
	v_add_f32_e32 v115, 1.0, v115
	v_mfma_f32_16x16x32_bf16 v[138:141], v[40:43], v[20:23], v[138:141]
	v_rcp_f32_e32 v146, v115
	v_mul_f32_e32 v115, 0xbfb8aa3b, v114
	v_exp_f32_e32 v115, v115
	v_mfma_f32_16x16x32_bf16 v[138:141], v[36:39], v[16:19], v[138:141]
	v_mul_f32_e32 v101, 0xbfb8aa3b, v100
	v_add_f32_e32 v92, 1.0, v92
	v_add_f32_e32 v115, 1.0, v115
	v_mfma_f32_16x16x32_bf16 v[80:83], v[80:83], v[4:7], v[84:87]
	v_exp_f32_e32 v101, v101
	s_nop 2
	v_mov_b32_e32 v135, v138
	v_pk_mul_f32 v[134:135], v[146:147], v[134:135]
	v_mov_b32_e32 v143, v140
	v_mul_f32_e32 v137, v134, v135
	v_rcp_f32_e32 v134, v115
	v_mov_b32_e32 v135, v33
	v_mov_b32_e32 v115, v139
	v_mfma_f32_16x16x32_bf16 v[68:71], v[68:71], v[12:15], 0
	v_mul_f32_e64 v114, v134, v114
	v_mul_f32_e64 v115, v135, v115
	v_rcp_f32_e32 v92, v92
	v_mul_f32_e32 v114, v114, v115
	v_cvt_pk_bf16_f32 v134, v137, v114
	v_mul_f32_e32 v114, 0xbfb8aa3b, v142
	v_exp_f32_e32 v114, v114
	v_mov_b32_e32 v115, v34
	v_mfma_f32_16x16x32_bf16 v[76:79], v[76:79], v[0:3], v[80:83]
	v_mov_b32_e32 v89, v72
	v_add_f32_e32 v114, 1.0, v114
	v_rcp_f32_e32 v114, v114
	v_and_b32_e32 v82, 0xffff0000, v130
	v_mfma_f32_16x16x32_bf16 v[64:67], v[64:67], v[8:11], v[68:71]
	v_mul_f32_e32 v72, 0xbfb8aa3b, v82
	v_pk_mul_f32 v[114:115], v[114:115], v[142:143]
	v_mov_b32_e32 v145, v141
	v_mul_f32_e32 v135, v114, v115
	v_mul_f32_e32 v114, 0xbfb8aa3b, v144
	v_exp_f32_e32 v114, v114
	v_mov_b32_e32 v115, v35
	v_mov_b32_e32 v103, v97
	v_exp_f32_e32 v72, v72
	v_add_f32_e32 v114, 1.0, v114
	v_rcp_f32_e32 v114, v114
	v_add_f32_e32 v101, 1.0, v101
	v_pk_mul_f32 v[92:93], v[92:93], v[102:103]
	v_rcp_f32_e32 v108, v101
	v_pk_mul_f32 v[114:115], v[114:115], v[144:145]
	v_mul_f32_e32 v92, v92, v93
	v_mul_f32_e32 v114, v114, v115
	v_mul_f32_e32 v93, 0xbfb8aa3b, v104
	v_mov_b32_e32 v97, v94
	v_mul_f32_e32 v94, 0xbfb8aa3b, v106
	v_mfma_f32_16x16x32_bf16 v[60:63], v[60:63], v[4:7], v[64:67]
	v_cvt_pk_bf16_f32 v135, v135, v114
	v_lshlrev_b32_e32 v114, 1, v222
	v_exp_f32_e32 v93, v93
	v_mfma_f32_16x16x32_bf16 v[48:51], v[48:51], v[12:15], 0
	v_exp_f32_e32 v94, v94
	v_lshlrev_b32_e32 v80, 16, v130
	v_and_or_b32 v114, v114, 48, v206
	v_mul_f32_e32 v81, 0xbfb8aa3b, v80
	v_add_f32_e32 v72, 1.0, v72
	v_lshlrev_b32_e32 v114, 4, v114
	v_mov_b32_e32 v115, v197
	v_mov_b32_e32 v101, v96
	v_exp_f32_e32 v81, v81
	v_rcp_f32_e32 v72, v72
	v_lshl_add_u64 v[138:139], s[0:1], 0, v[114:115]
	v_pk_mul_f32 v[100:101], v[108:109], v[100:101]
	v_mfma_f32_16x16x32_bf16 v[56:59], v[56:59], v[0:3], v[60:63]
	v_lshl_add_u64 v[138:139], v[138:139], 0, v[184:185]
	s_lshl_b64 s[0:1], s[10:11], 1
	v_mul_f32_e32 v96, v100, v101
	v_and_b32_e32 v62, 0xffff0000, v128
	v_mfma_f32_16x16x32_bf16 v[44:47], v[44:47], v[8:11], v[48:51]
	v_add_f32_e32 v93, 1.0, v93
	v_add_f32_e32 v94, 1.0, v94
	v_mov_b32_e32 v69, v52
	v_mul_f32_e32 v52, 0xbfb8aa3b, v62
	global_store_dwordx2 v[138:139], v[134:135], off nt
	s_and_b32 s8, s1, 0x3fffff
	s_and_b32 s9, s0, 0xffffffe0
	v_cvt_pk_bf16_f32 v92, v96, v92
	v_rcp_f32_e32 v96, v93
	v_rcp_f32_e32 v94, v94
	v_mov_b32_e32 v83, v77
	v_exp_f32_e32 v52, v52
	s_add_u32 s0, s9, s26
	v_lshlrev_b32_e32 v84, 16, v131
	v_and_b32_e32 v86, 0xffff0000, v131
	v_add_f32_e32 v81, 1.0, v81
	v_pk_mul_f32 v[72:73], v[72:73], v[82:83]
	s_addc_u32 s1, s8, s27
	v_rcp_f32_e32 v88, v81
	v_mul_f32_e32 v72, v72, v73
	v_mul_f32_e32 v73, 0xbfb8aa3b, v84
	v_mov_b32_e32 v77, v74
	v_mul_f32_e32 v74, 0xbfb8aa3b, v86
	v_mfma_f32_16x16x32_bf16 v[40:43], v[40:43], v[4:7], v[44:47]
	v_mov_b32_e32 v105, v98
	v_mov_b32_e32 v107, v99
	s_lshl_b64 s[0:1], s[0:1], 10
	v_exp_f32_e32 v73, v73
	v_exp_f32_e32 v74, v74
	v_lshlrev_b32_e32 v60, 16, v128
	v_pk_mul_f32 v[96:97], v[96:97], v[104:105]
	v_pk_mul_f32 v[94:95], v[94:95], v[106:107]
	s_add_u32 s0, s6, s0
	v_mul_f32_e32 v61, 0xbfb8aa3b, v60
	v_add_f32_e32 v52, 1.0, v52
	v_mul_f32_e32 v93, v96, v97
	v_mul_f32_e32 v94, v94, v95
	s_addc_u32 s1, s7, s1
	v_mov_b32_e32 v81, v76
	v_exp_f32_e32 v61, v61
	v_rcp_f32_e32 v52, v52
	v_cvt_pk_bf16_f32 v93, v93, v94
	v_lshl_add_u64 v[94:95], s[0:1], 0, v[112:113]
	v_pk_mul_f32 v[80:81], v[88:89], v[80:81]
	v_mfma_f32_16x16x32_bf16 v[36:39], v[36:39], v[0:3], v[40:43]
	v_lshl_add_u64 v[94:95], v[94:95], 0, v[184:185]
	v_mul_f32_e32 v76, v80, v81
	v_add_f32_e32 v73, 1.0, v73
	s_waitcnt vmcnt(4)
	v_and_b32_e32 v42, 0xffff0000, v126
	v_add_f32_e32 v74, 1.0, v74
	v_mov_b32_e32 v49, v32
	v_mul_f32_e32 v32, 0xbfb8aa3b, v42
	global_store_dwordx2 v[94:95], v[92:93], off nt
	v_cvt_pk_bf16_f32 v72, v76, v72
	v_rcp_f32_e32 v76, v73
	v_rcp_f32_e32 v74, v74
	v_mov_b32_e32 v63, v57
	v_exp_f32_e32 v32, v32
	v_lshlrev_b32_e32 v64, 16, v129
	v_and_b32_e32 v66, 0xffff0000, v129
	v_add_f32_e32 v61, 1.0, v61
	v_pk_mul_f32 v[52:53], v[52:53], v[62:63]
	v_rcp_f32_e32 v68, v61
	v_mul_f32_e32 v52, v52, v53
	v_mul_f32_e32 v53, 0xbfb8aa3b, v64
	v_mov_b32_e32 v57, v54
	v_mul_f32_e32 v54, 0xbfb8aa3b, v66
	v_mov_b32_e32 v85, v78
	v_mov_b32_e32 v87, v79
	v_exp_f32_e32 v53, v53
	v_exp_f32_e32 v54, v54
	v_lshlrev_b32_e32 v40, 16, v126
	v_pk_mul_f32 v[76:77], v[76:77], v[84:85]
	v_pk_mul_f32 v[74:75], v[74:75], v[86:87]
	v_mul_f32_e32 v41, 0xbfb8aa3b, v40
	v_add_f32_e32 v32, 1.0, v32
	v_mul_f32_e32 v73, v76, v77
	v_mul_f32_e32 v74, v74, v75
	v_mov_b32_e32 v61, v56
	v_exp_f32_e32 v41, v41
	v_rcp_f32_e32 v32, v32
	v_cvt_pk_bf16_f32 v73, v73, v74
	v_lshl_add_u64 v[74:75], s[0:1], 0, v[116:117]
	v_pk_mul_f32 v[60:61], v[68:69], v[60:61]
	v_lshl_add_u64 v[74:75], v[74:75], 0, v[184:185]
	v_mul_f32_e32 v56, v60, v61
	v_add_f32_e32 v53, 1.0, v53
	v_add_f32_e32 v54, 1.0, v54
	global_store_dwordx2 v[74:75], v[72:73], off nt
	v_cvt_pk_bf16_f32 v52, v56, v52
	v_rcp_f32_e32 v56, v53
	v_rcp_f32_e32 v54, v54
	v_mov_b32_e32 v43, v37
	s_add_u32 s0, s9, s33
	v_lshlrev_b32_e32 v44, 16, v127
	v_and_b32_e32 v46, 0xffff0000, v127
	v_add_f32_e32 v41, 1.0, v41
	v_pk_mul_f32 v[32:33], v[32:33], v[42:43]
	s_addc_u32 s1, s8, s34
	v_rcp_f32_e32 v48, v41
	v_mul_f32_e32 v32, v32, v33
	v_mul_f32_e32 v33, 0xbfb8aa3b, v44
	v_mov_b32_e32 v37, v34
	v_mul_f32_e32 v34, 0xbfb8aa3b, v46
	v_mov_b32_e32 v65, v58
	v_mov_b32_e32 v67, v59
	s_lshl_b64 s[0:1], s[0:1], 10
	v_exp_f32_e32 v33, v33
	v_exp_f32_e32 v34, v34
	v_pk_mul_f32 v[56:57], v[56:57], v[64:65]
	v_pk_mul_f32 v[54:55], v[54:55], v[66:67]
	s_add_u32 s0, s6, s0
	v_mul_f32_e32 v53, v56, v57
	v_mul_f32_e32 v54, v54, v55
	s_addc_u32 s1, s7, s1
	v_mov_b32_e32 v41, v36
	v_cvt_pk_bf16_f32 v53, v53, v54
	v_lshl_add_u64 v[54:55], s[0:1], 0, v[112:113]
	v_pk_mul_f32 v[40:41], v[48:49], v[40:41]
	v_lshl_add_u64 v[54:55], v[54:55], 0, v[184:185]
	v_mul_f32_e32 v36, v40, v41
	v_add_f32_e32 v33, 1.0, v33
	v_add_f32_e32 v34, 1.0, v34
	global_store_dwordx2 v[54:55], v[52:53], off nt
	v_cvt_pk_bf16_f32 v32, v36, v32
	v_rcp_f32_e32 v36, v33
	v_rcp_f32_e32 v34, v34
	v_mov_b32_e32 v45, v38
	v_mov_b32_e32 v47, v39
	v_pk_mul_f32 v[36:37], v[36:37], v[44:45]
	v_pk_mul_f32 v[34:35], v[34:35], v[46:47]
	v_mul_f32_e32 v33, v36, v37
	v_mul_f32_e32 v34, v34, v35
	v_cvt_pk_bf16_f32 v33, v33, v34
	v_lshl_add_u64 v[34:35], s[0:1], 0, v[114:115]
	v_lshl_add_u64 v[34:35], v[34:35], 0, v[184:185]
	global_store_dwordx2 v[34:35], v[32:33], off nt
	v_add_co_u32_e32 v32, vcc, s71, v124
	s_movk_i32 s0, 0x5000
	s_nop 0
	v_addc_co_u32_e32 v33, vcc, 0, v125, vcc
	v_add_co_u32_e32 v34, vcc, s0, v124
	s_or_b32 s0, s22, 64
	s_ashr_i32 s10, s0, 4
	s_ashr_i32 s11, s10, 31
	s_add_u32 s0, s21, s10
	s_addc_u32 s1, s20, s11
	v_addc_co_u32_e32 v35, vcc, 0, v125, vcc
	s_lshl_b64 s[0:1], s[0:1], 9
	global_load_dwordx4 v[108:111], v[34:35], off offset:-4096
	global_load_dwordx4 v[104:107], v[32:33], off offset:64
	global_load_dwordx4 v[100:103], v[32:33], off offset:128
	global_load_dwordx4 v[96:99], v[32:33], off offset:192
	v_lshl_add_u64 v[32:33], v[118:119], 0, s[0:1]
	s_add_u32 s0, s25, s10
	s_addc_u32 s1, s24, s11
	s_lshl_b64 s[0:1], s[0:1], 9
	global_load_dwordx2 v[134:135], v[32:33], off nt
	v_lshl_add_u64 v[32:33], v[118:119], 0, s[0:1]
	s_or_b32 s0, s22, 0x50
	s_ashr_i32 s10, s0, 4
	s_ashr_i32 s11, s10, 31
	s_add_u32 s0, s21, s10
	s_addc_u32 s1, s20, s11
	s_lshl_b64 s[0:1], s[0:1], 9
	global_load_dwordx4 v[92:95], v[122:123], off offset:256
	global_load_dwordx2 v[128:129], v[32:33], off nt
	global_load_dwordx4 v[88:91], v[34:35], off
	global_load_dwordx4 v[84:87], v[34:35], off offset:64
	global_load_dwordx4 v[80:83], v[34:35], off offset:128
	global_load_dwordx4 v[76:79], v[34:35], off offset:192
	v_lshl_add_u64 v[32:33], v[118:119], 0, s[0:1]
	s_add_u32 s0, s25, s10
	s_addc_u32 s1, s24, s11
	s_lshl_b64 s[0:1], s[0:1], 9
	global_load_dwordx2 v[132:133], v[32:33], off nt
	v_lshl_add_u64 v[32:33], v[118:119], 0, s[0:1]
	s_or_b32 s0, s22, 0x60
	s_ashr_i32 s10, s0, 4
	s_ashr_i32 s11, s10, 31
	s_add_u32 s0, s21, s10
	global_load_dwordx2 v[126:127], v[32:33], off nt
	v_lshlrev_b32_e32 v32, 8, v238
	v_mov_b32_e32 v33, v197
	s_addc_u32 s1, s20, s11
	v_lshl_add_u64 v[32:33], v[120:121], 0, v[32:33]
	s_lshl_b64 s[0:1], s[0:1], 9
	global_load_dwordx4 v[72:75], v[122:123], off offset:320
	global_load_dwordx4 v[68:71], v[32:33], off
	global_load_dwordx4 v[64:67], v[32:33], off offset:64
	global_load_dwordx4 v[60:63], v[32:33], off offset:128
	global_load_dwordx4 v[56:59], v[32:33], off offset:192
	v_lshl_add_u64 v[32:33], v[118:119], 0, s[0:1]
	s_add_u32 s0, s25, s10
	s_addc_u32 s1, s24, s11
	s_lshl_b64 s[0:1], s[0:1], 9
	global_load_dwordx2 v[130:131], v[32:33], off nt
	v_lshl_add_u64 v[32:33], v[118:119], 0, s[0:1]
	s_or_b32 s0, s22, 0x70
	s_ashr_i32 s10, s0, 4
	s_ashr_i32 s11, s10, 31
	s_add_u32 s0, s21, s10
	s_addc_u32 s1, s20, s11
	global_load_dwordx2 v[124:125], v[32:33], off nt
	v_lshlrev_b32_e32 v32, 8, v223
	v_mov_b32_e32 v33, v197
	s_lshl_b64 s[0:1], s[0:1], 9
	v_lshl_add_u64 v[32:33], v[120:121], 0, v[32:33]
	v_lshl_add_u64 v[120:121], v[118:119], 0, s[0:1]
	s_add_u32 s0, s25, s10
	global_load_dwordx4 v[52:55], v[122:123], off offset:384
	global_load_dwordx4 v[48:51], v[32:33], off
	global_load_dwordx4 v[44:47], v[32:33], off offset:64
	global_load_dwordx4 v[40:43], v[32:33], off offset:128
	global_load_dwordx4 v[36:39], v[32:33], off offset:192
	s_addc_u32 s1, s24, s11
	s_lshl_b64 s[0:1], s[0:1], 9
	v_lshl_add_u64 v[118:119], v[118:119], 0, s[0:1]
	global_load_dwordx4 v[32:35], v[122:123], off offset:448
	s_nop 0
	global_load_dwordx2 v[120:121], v[120:121], off nt
	s_nop 0
	global_load_dwordx2 v[118:119], v[118:119], off nt
	s_waitcnt vmcnt(27)
	v_mfma_f32_16x16x32_bf16 v[138:141], v[108:111], v[28:31], 0
	s_waitcnt vmcnt(23)
	v_lshlrev_b32_e32 v122, 16, v134
	v_mul_f32_e32 v123, 0xbfb8aa3b, v122
	v_exp_f32_e32 v123, v123
	v_mfma_f32_16x16x32_bf16 v[138:141], v[104:107], v[24:27], v[138:141]
	s_waitcnt vmcnt(22)
	v_mov_b32_e32 v147, v92
	v_and_b32_e32 v134, 0xffff0000, v134
	v_add_f32_e32 v123, 1.0, v123
	v_mfma_f32_16x16x32_bf16 v[138:141], v[100:103], v[20:23], v[138:141]
	v_rcp_f32_e32 v146, v123
	v_lshlrev_b32_e32 v142, 16, v135
	v_and_b32_e32 v144, 0xffff0000, v135
	v_mfma_f32_16x16x32_bf16 v[138:141], v[96:99], v[16:19], v[138:141]
	s_or_b32 s11, s26, 2
	s_ashr_i32 s20, s11, 31
	s_add_u32 s0, s19, s11
	s_addc_u32 s1, s13, s20
	s_lshl_b64 s[0:1], s[0:1], 10
	s_nop 2
	v_mov_b32_e32 v123, v138
	v_pk_mul_f32 v[122:123], v[146:147], v[122:123]
	v_mov_b32_e32 v135, v139
	v_mul_f32_e32 v137, v122, v123
	v_mul_f32_e32 v122, 0xbfb8aa3b, v134
	v_exp_f32_e32 v122, v122
	v_mov_b32_e32 v123, v93
	v_mov_b32_e32 v143, v140
	v_mov_b32_e32 v145, v141
	v_add_f32_e32 v122, 1.0, v122
	v_rcp_f32_e32 v122, v122
	s_waitcnt vmcnt(20)
	v_mfma_f32_16x16x32_bf16 v[138:141], v[88:91], v[28:31], 0
	s_add_u32 s0, s6, s0
	s_addc_u32 s1, s7, s1
	v_pk_mul_f32 v[122:123], v[122:123], v[134:135]
	v_mov_b32_e32 v135, v94
	v_mul_f32_e32 v122, v122, v123
	v_mul_f32_e32 v123, 0xbfb8aa3b, v142
	v_exp_f32_e32 v123, v123
	v_cvt_pk_bf16_f32 v122, v137, v122
	s_waitcnt vmcnt(19)
	v_mfma_f32_16x16x32_bf16 v[138:141], v[84:87], v[24:27], v[138:141]
	v_and_b32_e32 v220, 63, v136
	v_add_f32_e32 v123, 1.0, v123
	v_rcp_f32_e32 v134, v123
	s_waitcnt vmcnt(18)
	v_mfma_f32_16x16x32_bf16 v[138:141], v[80:83], v[20:23], v[138:141]
	v_lshlrev_b32_e32 v186, 4, v220
	v_lshlrev_b32_e32 v188, 1, v207
	v_pk_mul_f32 v[134:135], v[134:135], v[142:143]
	s_waitcnt vmcnt(17)
	v_mfma_f32_16x16x32_bf16 v[138:141], v[76:79], v[16:19], v[138:141]
	v_mul_f32_e32 v123, v134, v135
	v_mul_f32_e32 v134, 0xbfb8aa3b, v144
	v_exp_f32_e32 v134, v134
	v_mov_b32_e32 v135, v95
	s_waitcnt vmcnt(16)
	v_and_b32_e32 v142, 0xffff0000, v133
	s_nop 1
	v_mov_b32_e32 v143, v141
	v_add_f32_e32 v134, 1.0, v134
	v_rcp_f32_e32 v134, v134
	v_not_b32_e32 v219, v208
	v_or_b32_e32 v218, 2, v208
	v_or_b32_e32 v217, 3, v208
	v_pk_mul_f32 v[134:135], v[134:135], v[144:145]
	s_waitcnt vmcnt(14)
	v_mov_b32_e32 v145, v72
	v_mul_f32_e32 v134, v134, v135
	v_cvt_pk_bf16_f32 v123, v123, v134
	v_lshl_add_u64 v[134:135], s[0:1], 0, v[112:113]
	v_lshl_add_u64 v[134:135], v[134:135], 0, v[184:185]
	global_store_dwordx2 v[134:135], v[122:123], off nt
	v_lshlrev_b32_e32 v122, 16, v132
	v_mul_f32_e32 v123, 0xbfb8aa3b, v122
	v_exp_f32_e32 v123, v123
	v_and_b32_e32 v132, 0xffff0000, v132
	v_lshlrev_b32_e32 v134, 16, v133
	v_mov_b32_e32 v133, v139
	v_add_f32_e32 v123, 1.0, v123
	v_rcp_f32_e32 v144, v123
	v_mov_b32_e32 v123, v138
	s_waitcnt vmcnt(10)
	v_lshlrev_b32_e32 v138, 16, v131
	v_or_b32_e32 v216, 17, v208
	v_pk_mul_f32 v[122:123], v[144:145], v[122:123]
	v_or_b32_e32 v215, 18, v208
	v_mul_f32_e32 v135, v122, v123
	v_mul_f32_e32 v122, 0xbfb8aa3b, v132
	v_exp_f32_e32 v122, v122
	v_mov_b32_e32 v123, v73
	v_or_b32_e32 v214, 19, v208
	v_readlane_b32 s27, v255, 46
	v_add_f32_e32 v122, 1.0, v122
	v_rcp_f32_e32 v122, v122
	s_nop 0
	v_pk_mul_f32 v[122:123], v[122:123], v[132:133]
	s_nop 0
	v_mul_f32_e32 v122, v122, v123
	v_mul_f32_e32 v123, 0xbfb8aa3b, v134
	v_exp_f32_e32 v123, v123
	v_cvt_pk_bf16_f32 v122, v135, v122
	v_mov_b32_e32 v133, v74
	v_mov_b32_e32 v135, v140
	v_add_f32_e32 v123, 1.0, v123
	v_rcp_f32_e32 v132, v123
	v_and_b32_e32 v140, 0xffff0000, v131
	v_pk_mul_f32 v[132:133], v[132:133], v[134:135]
	s_nop 0
	v_mul_f32_e32 v123, v132, v133
	v_mul_f32_e32 v132, 0xbfb8aa3b, v142
	v_exp_f32_e32 v132, v132
	v_mov_b32_e32 v133, v75
	v_add_f32_e32 v132, 1.0, v132
	v_rcp_f32_e32 v132, v132
	s_nop 0
	v_pk_mul_f32 v[132:133], v[132:133], v[142:143]
	s_nop 0
	v_mul_f32_e32 v132, v132, v133
	v_cvt_pk_bf16_f32 v123, v123, v132
	v_lshl_add_u64 v[132:133], s[0:1], 0, v[116:117]
	v_lshl_add_u64 v[132:133], v[132:133], 0, v[184:185]
	global_store_dwordx2 v[132:133], v[122:123], off nt
	v_mfma_f32_16x16x32_bf16 v[132:135], v[68:71], v[28:31], 0
	v_lshlrev_b32_e32 v122, 16, v130
	v_mul_f32_e32 v123, 0xbfb8aa3b, v122
	v_exp_f32_e32 v123, v123
	v_mfma_f32_16x16x32_bf16 v[132:135], v[64:67], v[24:27], v[132:135]
	s_waitcnt vmcnt(9)
	v_mov_b32_e32 v143, v52
	v_and_b32_e32 v130, 0xffff0000, v130
	v_add_f32_e32 v123, 1.0, v123
	v_mfma_f32_16x16x32_bf16 v[132:135], v[60:63], v[20:23], v[132:135]
	v_rcp_f32_e32 v142, v123
	s_ashr_i32 s0, s5, 5
	s_or_b32 s5, s0, 3
	v_mfma_f32_16x16x32_bf16 v[132:135], v[56:59], v[16:19], v[132:135]
	s_ashr_i32 s10, s5, 31
	s_add_u32 s0, s19, s5
	s_addc_u32 s1, s13, s10
	s_waitcnt vmcnt(8)
	v_mfma_f32_16x16x32_bf16 v[28:31], v[48:51], v[28:31], 0
	s_lshl_b64 s[0:1], s[0:1], 10
	s_nop 1
	v_mov_b32_e32 v123, v132
	v_pk_mul_f32 v[122:123], v[142:143], v[122:123]
	s_waitcnt vmcnt(7)
	v_mfma_f32_16x16x32_bf16 v[24:27], v[44:47], v[24:27], v[28:31]
	v_mul_f32_e32 v132, v122, v123
	v_mul_f32_e32 v122, 0xbfb8aa3b, v130
	v_exp_f32_e32 v122, v122
	v_mov_b32_e32 v123, v53
	v_mov_b32_e32 v131, v133
	s_waitcnt vmcnt(6)
	v_mfma_f32_16x16x32_bf16 v[20:23], v[40:43], v[20:23], v[24:27]
	v_add_f32_e32 v122, 1.0, v122
	v_rcp_f32_e32 v122, v122
	v_mov_b32_e32 v139, v134
	s_waitcnt vmcnt(5)
	v_mfma_f32_16x16x32_bf16 v[16:19], v[36:39], v[16:19], v[20:23]
	s_waitcnt vmcnt(4)
	v_mov_b32_e32 v29, v32
	v_pk_mul_f32 v[122:123], v[122:123], v[130:131]
	v_mov_b32_e32 v131, v54
	v_mul_f32_e32 v122, v122, v123
	v_mul_f32_e32 v123, 0xbfb8aa3b, v138
	v_exp_f32_e32 v123, v123
	s_waitcnt vmcnt(3)
	v_lshlrev_b32_e32 v20, 16, v120
	v_mul_f32_e32 v21, 0xbfb8aa3b, v20
	v_exp_f32_e32 v21, v21
	v_add_f32_e32 v123, 1.0, v123
	v_rcp_f32_e32 v130, v123
	v_and_b32_e32 v22, 0xffff0000, v120
	v_add_f32_e32 v21, 1.0, v21
	v_rcp_f32_e32 v28, v21
	v_mov_b32_e32 v21, v16
	v_mul_f32_e32 v16, 0xbfb8aa3b, v22
	v_pk_mul_f32 v[130:131], v[130:131], v[138:139]
	v_exp_f32_e32 v16, v16
	v_mul_f32_e32 v123, v130, v131
	v_mul_f32_e32 v130, 0xbfb8aa3b, v140
	v_exp_f32_e32 v130, v130
	v_pk_mul_f32 v[20:21], v[28:29], v[20:21]
	v_add_f32_e32 v16, 1.0, v16
	v_mul_f32_e32 v25, v20, v21
	v_rcp_f32_e32 v20, v16
	v_add_f32_e32 v130, 1.0, v130
	v_rcp_f32_e32 v130, v130
	v_mov_b32_e32 v21, v33
	v_mov_b32_e32 v23, v17
	v_lshlrev_b32_e32 v24, 16, v121
	v_pk_mul_f32 v[16:17], v[20:21], v[22:23]
	v_mov_b32_e32 v131, v55
	v_mov_b32_e32 v141, v135
	v_mul_f32_e32 v16, v16, v17
	v_mul_f32_e32 v17, 0xbfb8aa3b, v24
	v_pk_mul_f32 v[130:131], v[130:131], v[140:141]
	s_add_u32 s0, s6, s0
	v_exp_f32_e32 v17, v17
	v_mul_f32_e32 v130, v130, v131
	s_addc_u32 s1, s7, s1
	v_cvt_pk_bf16_f32 v122, v132, v122
	v_cvt_pk_bf16_f32 v123, v123, v130
	v_lshl_add_u64 v[130:131], s[0:1], 0, v[112:113]
	v_lshl_add_u64 v[130:131], v[130:131], 0, v[184:185]
	v_and_b32_e32 v26, 0xffff0000, v121
	global_store_dwordx2 v[130:131], v[122:123], off nt
	v_cvt_pk_bf16_f32 v16, v25, v16
	v_add_f32_e32 v17, 1.0, v17
	v_mov_b32_e32 v25, v18
	v_mul_f32_e32 v18, 0xbfb8aa3b, v26
	v_rcp_f32_e32 v20, v17
	v_exp_f32_e32 v18, v18
	v_mov_b32_e32 v21, v34
	v_mov_b32_e32 v27, v19
	v_pk_mul_f32 v[20:21], v[20:21], v[24:25]
	v_add_f32_e32 v18, 1.0, v18
	v_mul_f32_e32 v17, v20, v21
	v_rcp_f32_e32 v20, v18
	v_mov_b32_e32 v21, v35
	v_and_b32_e32 v22, 0xffff0000, v128
	v_mov_b32_e32 v29, v92
	v_pk_mul_f32 v[18:19], v[20:21], v[26:27]
	v_lshlrev_b32_e32 v20, 16, v128
	v_mul_f32_e32 v18, v18, v19
	v_cvt_pk_bf16_f32 v17, v17, v18
	v_lshl_add_u64 v[18:19], s[0:1], 0, v[114:115]
	v_lshl_add_u64 v[18:19], v[18:19], 0, v[184:185]
	global_store_dwordx2 v[18:19], v[16:17], off nt
	v_mfma_f32_16x16x32_bf16 v[16:19], v[108:111], v[12:15], 0
	v_mul_f32_e32 v21, 0xbfb8aa3b, v20
	v_exp_f32_e32 v21, v21
	v_lshlrev_b32_e32 v24, 16, v129
	v_mfma_f32_16x16x32_bf16 v[16:19], v[104:107], v[8:11], v[16:19]
	v_and_b32_e32 v26, 0xffff0000, v129
	v_add_f32_e32 v21, 1.0, v21
	v_rcp_f32_e32 v28, v21
	v_mfma_f32_16x16x32_bf16 v[16:19], v[100:103], v[4:7], v[16:19]
	s_add_u32 s0, s9, s11
	s_addc_u32 s1, s8, s20
	s_lshl_b64 s[0:1], s[0:1], 10
	v_mfma_f32_16x16x32_bf16 v[16:19], v[96:99], v[0:3], v[16:19]
	s_add_u32 s0, s6, s0
	s_addc_u32 s1, s7, s1
	s_nop 5
	v_mov_b32_e32 v21, v16
	v_mul_f32_e32 v16, 0xbfb8aa3b, v22
	v_exp_f32_e32 v16, v16
	v_mov_b32_e32 v23, v17
	v_mov_b32_e32 v25, v18
	v_mul_f32_e32 v18, 0xbfb8aa3b, v26
	v_add_f32_e32 v16, 1.0, v16
	v_rcp_f32_e32 v92, v16
	v_exp_f32_e32 v18, v18
	v_pk_mul_f32 v[20:21], v[28:29], v[20:21]
	v_mov_b32_e32 v27, v19
	v_pk_mul_f32 v[16:17], v[92:93], v[22:23]
	v_mul_f32_e32 v20, v20, v21
	v_mul_f32_e32 v16, v16, v17
	v_mul_f32_e32 v17, 0xbfb8aa3b, v24
	v_exp_f32_e32 v17, v17
	v_add_f32_e32 v18, 1.0, v18
	v_cvt_pk_bf16_f32 v16, v20, v16
	v_mov_b32_e32 v21, v94
	v_add_f32_e32 v17, 1.0, v17
	v_rcp_f32_e32 v20, v17
	v_rcp_f32_e32 v94, v18
	v_and_b32_e32 v22, 0xffff0000, v126
	v_mov_b32_e32 v29, v72
	v_pk_mul_f32 v[20:21], v[20:21], v[24:25]
	v_pk_mul_f32 v[18:19], v[94:95], v[26:27]
	v_mul_f32_e32 v17, v20, v21
	v_mul_f32_e32 v18, v18, v19
	v_cvt_pk_bf16_f32 v17, v17, v18
	v_lshl_add_u64 v[18:19], s[0:1], 0, v[112:113]
	v_lshl_add_u64 v[18:19], v[18:19], 0, v[184:185]
	global_store_dwordx2 v[18:19], v[16:17], off nt
	v_mfma_f32_16x16x32_bf16 v[16:19], v[88:91], v[12:15], 0
	v_lshlrev_b32_e32 v20, 16, v126
	v_mul_f32_e32 v21, 0xbfb8aa3b, v20
	v_exp_f32_e32 v21, v21
	v_mfma_f32_16x16x32_bf16 v[16:19], v[84:87], v[8:11], v[16:19]
	v_lshlrev_b32_e32 v24, 16, v127
	v_and_b32_e32 v26, 0xffff0000, v127
	v_add_f32_e32 v21, 1.0, v21
	v_mfma_f32_16x16x32_bf16 v[16:19], v[80:83], v[4:7], v[16:19]
	v_rcp_f32_e32 v28, v21
	v_mfma_f32_16x16x32_bf16 v[16:19], v[76:79], v[0:3], v[16:19]
	s_nop 7
	v_mov_b32_e32 v21, v16
	v_mul_f32_e32 v16, 0xbfb8aa3b, v22
	v_exp_f32_e32 v16, v16
	v_mov_b32_e32 v23, v17
	v_mov_b32_e32 v25, v18
	v_mul_f32_e32 v18, 0xbfb8aa3b, v26
	v_add_f32_e32 v16, 1.0, v16
	v_rcp_f32_e32 v72, v16
	v_exp_f32_e32 v18, v18
	v_pk_mul_f32 v[20:21], v[28:29], v[20:21]
	v_mov_b32_e32 v27, v19
	v_pk_mul_f32 v[16:17], v[72:73], v[22:23]
	v_mul_f32_e32 v20, v20, v21
	v_mul_f32_e32 v16, v16, v17
	v_mul_f32_e32 v17, 0xbfb8aa3b, v24
	v_exp_f32_e32 v17, v17
	v_add_f32_e32 v18, 1.0, v18
	v_cvt_pk_bf16_f32 v16, v20, v16
	v_mov_b32_e32 v21, v74
	v_add_f32_e32 v17, 1.0, v17
	v_rcp_f32_e32 v20, v17
	v_rcp_f32_e32 v74, v18
	v_and_b32_e32 v22, 0xffff0000, v124
	v_mov_b32_e32 v29, v52
	v_pk_mul_f32 v[20:21], v[20:21], v[24:25]
	v_pk_mul_f32 v[18:19], v[74:75], v[26:27]
	v_mul_f32_e32 v17, v20, v21
	v_mul_f32_e32 v18, v18, v19
	v_cvt_pk_bf16_f32 v17, v17, v18
	v_lshl_add_u64 v[18:19], s[0:1], 0, v[116:117]
	v_lshl_add_u64 v[18:19], v[18:19], 0, v[184:185]
	global_store_dwordx2 v[18:19], v[16:17], off nt
	v_mfma_f32_16x16x32_bf16 v[16:19], v[68:71], v[12:15], 0
	v_lshlrev_b32_e32 v20, 16, v124
	v_mul_f32_e32 v21, 0xbfb8aa3b, v20
	v_exp_f32_e32 v21, v21
	v_mfma_f32_16x16x32_bf16 v[16:19], v[64:67], v[8:11], v[16:19]
	v_lshlrev_b32_e32 v24, 16, v125
	v_and_b32_e32 v26, 0xffff0000, v125
	v_add_f32_e32 v21, 1.0, v21
	v_mfma_f32_16x16x32_bf16 v[12:15], v[48:51], v[12:15], 0
	v_rcp_f32_e32 v28, v21
	s_add_u32 s0, s9, s5
	s_addc_u32 s1, s8, s10
	v_mfma_f32_16x16x32_bf16 v[16:19], v[60:63], v[4:7], v[16:19]
	s_lshl_b64 s[0:1], s[0:1], 10
	s_add_u32 s0, s6, s0
	s_addc_u32 s1, s7, s1
	v_mfma_f32_16x16x32_bf16 v[8:11], v[44:47], v[8:11], v[12:15]
	s_cmp_lg_u32 s4, 0
	v_mfma_f32_16x16x32_bf16 v[16:19], v[56:59], v[0:3], v[16:19]
	s_nop 0
	v_mov_b32_e32 v13, v32
	v_mfma_f32_16x16x32_bf16 v[4:7], v[40:43], v[4:7], v[8:11]
	v_mfma_f32_16x16x32_bf16 v[0:3], v[36:39], v[0:3], v[4:7]
	s_nop 3
	v_mov_b32_e32 v21, v16
	v_mul_f32_e32 v16, 0xbfb8aa3b, v22
	v_exp_f32_e32 v16, v16
	s_waitcnt vmcnt(6)
	v_lshlrev_b32_e32 v4, 16, v118
	v_mul_f32_e32 v5, 0xbfb8aa3b, v4
	v_exp_f32_e32 v5, v5
	v_add_f32_e32 v16, 1.0, v16
	v_rcp_f32_e32 v52, v16
	v_and_b32_e32 v6, 0xffff0000, v118
	v_add_f32_e32 v5, 1.0, v5
	v_rcp_f32_e32 v12, v5
	v_mov_b32_e32 v5, v0
	v_mul_f32_e32 v0, 0xbfb8aa3b, v6
	v_mov_b32_e32 v23, v17
	v_exp_f32_e32 v0, v0
	v_pk_mul_f32 v[16:17], v[52:53], v[22:23]
	v_mov_b32_e32 v25, v18
	v_mul_f32_e32 v16, v16, v17
	v_mul_f32_e32 v17, 0xbfb8aa3b, v24
	v_mul_f32_e32 v18, 0xbfb8aa3b, v26
	v_exp_f32_e32 v17, v17
	v_exp_f32_e32 v18, v18
	v_add_f32_e32 v0, 1.0, v0
	v_rcp_f32_e32 v32, v0
	v_pk_mul_f32 v[20:21], v[28:29], v[20:21]
	v_add_f32_e32 v17, 1.0, v17
	v_mul_f32_e32 v20, v20, v21
	v_add_f32_e32 v18, 1.0, v18
	v_cvt_pk_bf16_f32 v16, v20, v16
	v_rcp_f32_e32 v20, v17
	v_mov_b32_e32 v21, v54
	v_rcp_f32_e32 v54, v18
	v_mov_b32_e32 v7, v1
	v_lshlrev_b32_e32 v8, 16, v119
	v_and_b32_e32 v10, 0xffff0000, v119
	v_pk_mul_f32 v[0:1], v[32:33], v[6:7]
	v_mov_b32_e32 v9, v2
	v_mul_f32_e32 v0, v0, v1
	v_mul_f32_e32 v1, 0xbfb8aa3b, v8
	v_mul_f32_e32 v2, 0xbfb8aa3b, v10
	v_mov_b32_e32 v27, v19
	v_exp_f32_e32 v1, v1
	v_exp_f32_e32 v2, v2
	v_pk_mul_f32 v[20:21], v[20:21], v[24:25]
	v_pk_mul_f32 v[18:19], v[54:55], v[26:27]
	v_mul_f32_e32 v17, v20, v21
	v_mul_f32_e32 v18, v18, v19
	v_cvt_pk_bf16_f32 v17, v17, v18
	v_lshl_add_u64 v[18:19], s[0:1], 0, v[112:113]
	v_pk_mul_f32 v[4:5], v[12:13], v[4:5]
	v_lshl_add_u64 v[18:19], v[18:19], 0, v[184:185]
	v_mul_f32_e32 v4, v4, v5
	v_add_f32_e32 v1, 1.0, v1
	v_add_f32_e32 v2, 1.0, v2
	global_store_dwordx2 v[18:19], v[16:17], off nt
	v_cvt_pk_bf16_f32 v0, v4, v0
	v_rcp_f32_e32 v4, v1
	v_mov_b32_e32 v5, v34
	v_rcp_f32_e32 v34, v2
	v_mov_b32_e32 v11, v3
	v_pk_mul_f32 v[4:5], v[4:5], v[8:9]
	v_pk_mul_f32 v[2:3], v[34:35], v[10:11]
	v_mul_f32_e32 v1, v4, v5
	v_mul_f32_e32 v2, v2, v3
	v_cvt_pk_bf16_f32 v1, v1, v2
	v_lshl_add_u64 v[2:3], s[0:1], 0, v[114:115]
	v_lshl_add_u64 v[2:3], v[2:3], 0, v[184:185]
	global_store_dwordx2 v[2:3], v[0:1], off nt
	v_cvt_f32_i32_e32 v0, s42
	s_mov_b64 s[0:1], -1
	s_barrier
	v_sub_f32_e32 v221, 0xc0a00000, v0
	s_cbranch_scc0 .LBB0_788
	v_cmp_gt_f32_e32 vcc, s75, v221
	s_bfe_u32 s4, s16, 0x40004
	s_and_b64 s[0:1], vcc, exec
	v_cndmask_b32_e32 v0, 0, v231, vcc
	v_add_f32_e32 v0, v221, v0
	v_exp_f32_e32 v0, v0
	s_cselect_b32 s0, 0xffffffc0, 0
	s_mov_b64 s[20:21], s[64:65]
	v_mov_b32_e32 v187, v197
	v_ldexp_f32 v0, v0, s0
	s_lshl_b32 s0, s42, 2
	s_add_i32 s0, s12, s0
	v_sub_f32_e32 v120, 1.0, v0
	v_lshl_add_u64 v[0:1], s[20:21], 0, v[186:187]
	s_mov_b64 s[6:7], 0x1a801000
	s_ashr_i32 s1, s0, 31
	v_lshl_add_u64 v[0:1], v[0:1], 0, s[6:7]
	s_lshl_b64 s[6:7], s[0:1], 10
	s_add_i32 s0, s0, 16
	s_ashr_i32 s1, s0, 31
	s_lshl_b64 s[0:1], s[0:1], 10
	s_ashr_i32 s5, s69, 4
	s_ashr_i32 s19, s18, 31
	v_lshl_add_u64 v[2:3], v[0:1], 0, s[6:7]
	v_lshl_add_u64 v[0:1], v[0:1], 0, s[0:1]
	s_add_u32 s0, s20, 0xee01000
	s_addc_u32 s1, s21, 0
	s_lshl_b32 s7, s4, 13
	s_lshl_b32 s8, s5, 17
	s_lshl_b32 s6, s42, 11
	s_or_b32 s7, s7, s8
	s_add_i32 s6, s7, s6
	s_ashr_i32 s7, s6, 31
	global_load_dwordx4 v[44:47], v[2:3], off nt
	global_load_dwordx4 v[48:51], v[2:3], off offset:1024 nt
	global_load_dwordx4 v[52:55], v[2:3], off offset:2048 nt
	global_load_dwordx4 v[56:59], v[2:3], off offset:3072 nt
	global_load_dwordx4 v[32:35], v[0:1], off nt
	global_load_dwordx4 v[20:23], v[0:1], off offset:1024 nt
	global_load_dwordx4 v[24:27], v[0:1], off offset:2048 nt
	global_load_dwordx4 v[28:31], v[0:1], off offset:3072 nt
	v_mov_b32_e32 v1, s7
	s_or_b32 s7, s6, 0x100
	s_ashr_i32 s8, s7, 31
	v_or_b32_e32 v0, s6, v220
	v_or_b32_e32 v16, s7, v220
	v_mov_b32_e32 v17, s8
	v_lshl_add_u64 v[12:13], v[0:1], 4, s[0:1]
	v_lshl_add_u64 v[60:61], v[16:17], 4, s[0:1]
	global_load_dwordx4 v[0:3], v[12:13], off
	global_load_dwordx4 v[4:7], v[12:13], off offset:1024
	global_load_dwordx4 v[8:11], v[12:13], off offset:2048
	s_nop 0
	global_load_dwordx4 v[12:15], v[12:13], off offset:3072
	s_nop 0
	global_load_dwordx4 v[16:19], v[60:61], off
	global_load_dwordx4 v[36:39], v[60:61], off offset:1024
	global_load_dwordx4 v[40:43], v[60:61], off offset:2048
	s_nop 0
	global_load_dwordx4 v[60:63], v[60:61], off offset:3072
	v_or_b32_e32 v239, 32, v208
	s_waitcnt vmcnt(7)
	v_mfma_f32_16x16x32_bf16 v[64:67], v[0:3], v[44:47], 0
	s_or_b32 s7, s6, 0x200
	s_ashr_i32 s8, s7, 31
	v_mfma_f32_16x16x32_bf16 v[0:3], v[0:3], v[32:35], 0
	s_waitcnt vmcnt(6)
	v_mfma_f32_16x16x32_bf16 v[64:67], v[4:7], v[48:51], v[64:67]
	v_mfma_f32_16x16x32_bf16 v[0:3], v[4:7], v[20:23], v[0:3]
	s_waitcnt vmcnt(5)
	v_mfma_f32_16x16x32_bf16 v[4:7], v[8:11], v[52:55], v[64:67]
	v_mfma_f32_16x16x32_bf16 v[0:3], v[8:11], v[24:27], v[0:3]
	s_waitcnt vmcnt(4)
	v_mfma_f32_16x16x32_bf16 v[8:11], v[12:15], v[56:59], v[4:7]
	v_mfma_f32_16x16x32_bf16 v[0:3], v[12:15], v[28:31], v[0:3]
	s_waitcnt vmcnt(3)
	v_mfma_f32_16x16x32_bf16 v[4:7], v[16:19], v[44:47], 0
	v_mfma_f32_16x16x32_bf16 v[12:15], v[16:19], v[32:35], 0
	s_waitcnt vmcnt(2)
	v_mfma_f32_16x16x32_bf16 v[4:7], v[36:39], v[48:51], v[4:7]
	v_mfma_f32_16x16x32_bf16 v[12:15], v[36:39], v[20:23], v[12:15]
	s_waitcnt vmcnt(1)
	v_mfma_f32_16x16x32_bf16 v[4:7], v[40:43], v[52:55], v[4:7]
	v_mfma_f32_16x16x32_bf16 v[16:19], v[40:43], v[24:27], v[12:15]
	s_waitcnt vmcnt(0)
	v_mfma_f32_16x16x32_bf16 v[12:15], v[60:63], v[56:59], v[4:7]
	v_mfma_f32_16x16x32_bf16 v[4:7], v[60:63], v[28:31], v[16:19]
	s_nop 4
	v_or_b32_e32 v16, s7, v220
	s_or_b32 s7, s6, 0x300
	v_mov_b32_e32 v17, s8
	s_ashr_i32 s8, s7, 31
	v_or_b32_e32 v64, s7, v220
	v_mov_b32_e32 v65, s8
	v_lshl_add_u64 v[60:61], v[16:17], 4, s[0:1]
	v_lshl_add_u64 v[76:77], v[64:65], 4, s[0:1]
	global_load_dwordx4 v[16:19], v[60:61], off
	global_load_dwordx4 v[36:39], v[60:61], off offset:1024
	global_load_dwordx4 v[40:43], v[60:61], off offset:2048
	s_nop 0
	global_load_dwordx4 v[60:63], v[60:61], off offset:3072
	s_nop 0
	global_load_dwordx4 v[64:67], v[76:77], off
	global_load_dwordx4 v[68:71], v[76:77], off offset:1024
	global_load_dwordx4 v[72:75], v[76:77], off offset:2048
	s_nop 0
	global_load_dwordx4 v[76:79], v[76:77], off offset:3072
	s_waitcnt vmcnt(7)
	v_mfma_f32_16x16x32_bf16 v[80:83], v[16:19], v[44:47], 0
	s_or_b32 s7, s6, 0x400
	s_ashr_i32 s8, s7, 31
	v_mfma_f32_16x16x32_bf16 v[16:19], v[16:19], v[32:35], 0
	s_waitcnt vmcnt(6)
	v_mfma_f32_16x16x32_bf16 v[80:83], v[36:39], v[48:51], v[80:83]
	v_mfma_f32_16x16x32_bf16 v[16:19], v[36:39], v[20:23], v[16:19]
	s_waitcnt vmcnt(5)
	v_mfma_f32_16x16x32_bf16 v[36:39], v[40:43], v[52:55], v[80:83]
	v_mfma_f32_16x16x32_bf16 v[16:19], v[40:43], v[24:27], v[16:19]
	s_waitcnt vmcnt(4)
	v_mfma_f32_16x16x32_bf16 v[40:43], v[60:63], v[56:59], v[36:39]
	v_mfma_f32_16x16x32_bf16 v[16:19], v[60:63], v[28:31], v[16:19]
	s_waitcnt vmcnt(3)
	v_mfma_f32_16x16x32_bf16 v[36:39], v[64:67], v[44:47], 0
	v_mfma_f32_16x16x32_bf16 v[60:63], v[64:67], v[32:35], 0
	s_waitcnt vmcnt(2)
	v_mfma_f32_16x16x32_bf16 v[36:39], v[68:71], v[48:51], v[36:39]
	v_mfma_f32_16x16x32_bf16 v[60:63], v[68:71], v[20:23], v[60:63]
	s_waitcnt vmcnt(1)
	v_mfma_f32_16x16x32_bf16 v[36:39], v[72:75], v[52:55], v[36:39]
	v_mfma_f32_16x16x32_bf16 v[64:67], v[72:75], v[24:27], v[60:63]
	s_waitcnt vmcnt(0)
	v_mfma_f32_16x16x32_bf16 v[60:63], v[76:79], v[56:59], v[36:39]
	v_mfma_f32_16x16x32_bf16 v[36:39], v[76:79], v[28:31], v[64:67]
	s_nop 4
	v_or_b32_e32 v64, s7, v220
	s_or_b32 s7, s6, 0x500
	v_mov_b32_e32 v65, s8
	s_ashr_i32 s8, s7, 31
	v_or_b32_e32 v80, s7, v220
	v_mov_b32_e32 v81, s8
	v_lshl_add_u64 v[76:77], v[64:65], 4, s[0:1]
	v_lshl_add_u64 v[92:93], v[80:81], 4, s[0:1]
	global_load_dwordx4 v[64:67], v[76:77], off
	global_load_dwordx4 v[68:71], v[76:77], off offset:1024
	global_load_dwordx4 v[72:75], v[76:77], off offset:2048
	s_nop 0
	global_load_dwordx4 v[76:79], v[76:77], off offset:3072
	s_nop 0
	global_load_dwordx4 v[80:83], v[92:93], off
	global_load_dwordx4 v[84:87], v[92:93], off offset:1024
	global_load_dwordx4 v[88:91], v[92:93], off offset:2048
	s_nop 0
	global_load_dwordx4 v[92:95], v[92:93], off offset:3072
	s_waitcnt vmcnt(7)
	v_mfma_f32_16x16x32_bf16 v[96:99], v[64:67], v[44:47], 0
	s_or_b32 s7, s6, 0x600
	s_or_b32 s6, s6, 0x700
	s_ashr_i32 s8, s7, 31
	v_mfma_f32_16x16x32_bf16 v[64:67], v[64:67], v[32:35], 0
	s_waitcnt vmcnt(6)
	v_mfma_f32_16x16x32_bf16 v[64:67], v[68:71], v[20:23], v[64:67]
	v_mfma_f32_16x16x32_bf16 v[96:99], v[68:71], v[48:51], v[96:99]
	s_waitcnt vmcnt(5)
	v_mfma_f32_16x16x32_bf16 v[64:67], v[72:75], v[24:27], v[64:67]
	v_mfma_f32_16x16x32_bf16 v[68:71], v[72:75], v[52:55], v[96:99]
	s_waitcnt vmcnt(4)
	v_mfma_f32_16x16x32_bf16 v[100:103], v[76:79], v[28:31], v[64:67]
	s_waitcnt vmcnt(3)
	v_mfma_f32_16x16x32_bf16 v[64:67], v[80:83], v[44:47], 0
	v_mfma_f32_16x16x32_bf16 v[96:99], v[76:79], v[56:59], v[68:71]
	v_mfma_f32_16x16x32_bf16 v[68:71], v[80:83], v[32:35], 0
	v_or_b32_e32 v80, s6, v220
	s_waitcnt vmcnt(2)
	v_mfma_f32_16x16x32_bf16 v[64:67], v[84:87], v[48:51], v[64:67]
	v_mfma_f32_16x16x32_bf16 v[68:71], v[84:87], v[20:23], v[68:71]
	s_waitcnt vmcnt(1)
	v_mfma_f32_16x16x32_bf16 v[64:67], v[88:91], v[52:55], v[64:67]
	v_mfma_f32_16x16x32_bf16 v[68:71], v[88:91], v[24:27], v[68:71]
	s_waitcnt vmcnt(0)
	v_mfma_f32_16x16x32_bf16 v[84:87], v[92:95], v[56:59], v[64:67]
	s_nop 4
	v_or_b32_e32 v64, s7, v220
	s_ashr_i32 s7, s6, 31
	v_mov_b32_e32 v65, s8
	v_mov_b32_e32 v81, s7
	v_lshl_add_u64 v[76:77], v[64:65], 4, s[0:1]
	v_lshl_add_u64 v[108:109], v[80:81], 4, s[0:1]
	v_mfma_f32_16x16x32_bf16 v[104:107], v[92:95], v[28:31], v[68:71]
	global_load_dwordx4 v[64:67], v[76:77], off
	s_nop 1
	global_load_dwordx4 v[68:71], v[76:77], off offset:1024
	global_load_dwordx4 v[72:75], v[76:77], off offset:2048
	s_nop 0
	global_load_dwordx4 v[76:79], v[76:77], off offset:3072
	s_nop 0
	global_load_dwordx4 v[80:83], v[108:109], off
	global_load_dwordx4 v[88:91], v[108:109], off offset:1024
	global_load_dwordx4 v[92:95], v[108:109], off offset:2048
	s_nop 0
	global_load_dwordx4 v[108:111], v[108:109], off offset:3072
	s_waitcnt vmcnt(7)
	v_mfma_f32_16x16x32_bf16 v[112:115], v[64:67], v[44:47], 0
	v_cmp_gt_f32_e32 vcc, s15, v120
	s_and_b64 s[0:1], vcc, exec
	s_cselect_b32 s0, 32, 0
	v_mfma_f32_16x16x32_bf16 v[64:67], v[64:67], v[32:35], 0
	s_or_b32 s6, s68, 64
	s_lshl_b32 s1, s42, 4
	s_ashr_i32 s43, s42, 31
	s_waitcnt vmcnt(6)
	v_mfma_f32_16x16x32_bf16 v[64:67], v[68:71], v[20:23], v[64:67]
	s_lshl_b64 s[10:11], s[42:43], 12
	v_mov_b32_e32 v189, v197
	v_mfma_f32_16x16x32_bf16 v[112:115], v[68:71], v[48:51], v[112:115]
	s_waitcnt vmcnt(5)
	v_mfma_f32_16x16x32_bf16 v[64:67], v[72:75], v[24:27], v[64:67]
	v_mfma_f32_16x16x32_bf16 v[68:71], v[72:75], v[52:55], v[112:115]
	s_waitcnt vmcnt(4)
	v_mfma_f32_16x16x32_bf16 v[116:119], v[76:79], v[28:31], v[64:67]
	s_waitcnt vmcnt(3)
	v_mfma_f32_16x16x32_bf16 v[64:67], v[80:83], v[44:47], 0
	v_mfma_f32_16x16x32_bf16 v[112:115], v[76:79], v[56:59], v[68:71]
	v_mfma_f32_16x16x32_bf16 v[68:71], v[80:83], v[32:35], 0
	s_waitcnt vmcnt(2)
	v_mfma_f32_16x16x32_bf16 v[64:67], v[88:91], v[48:51], v[64:67]
	v_mfma_f32_16x16x32_bf16 v[68:71], v[88:91], v[20:23], v[68:71]
	s_waitcnt vmcnt(1)
	v_mfma_f32_16x16x32_bf16 v[64:67], v[92:95], v[52:55], v[64:67]
	v_mfma_f32_16x16x32_bf16 v[68:71], v[92:95], v[24:27], v[68:71]
	s_waitcnt vmcnt(0)
	v_mfma_f32_16x16x32_bf16 v[92:95], v[108:111], v[56:59], v[64:67]
	s_nop 4
	v_ldexp_f32 v64, v120, s0
	v_log_f32_e32 v64, v64
	v_cndmask_b32_e32 v65, 0, v232, vcc
	s_lshl_b32 s0, s5, 6
	s_add_i32 s1, s1, s0
	v_sub_f32_e32 v185, v64, v65
	v_add3_u32 v64, v206, s6, 1
	v_cvt_f32_u32_e32 v64, v64
	s_or_b32 s0, s1, s4
	v_lshl_or_b32 v190, s0, 9, v206
	s_lshl_b64 s[0:1], s[18:19], 10
	v_mul_f32_e32 v64, v185, v64
	v_exp_f32_e32 v120, v64
	s_add_u32 s0, s20, s0
	s_addc_u32 s1, s21, s1
	s_add_u32 s0, s0, 0x1b801000
	v_pk_mul_f32 v[64:65], v[120:121], v[8:9] op_sel_hi:[0,1]
	v_add_u32_e32 v8, s68, v206
	v_add_u32_e32 v8, 0x51, v8
	v_cvt_f32_ubyte0_e32 v8, v8
	v_mul_f32_e32 v8, v185, v8
	s_addc_u32 s1, s1, 0
	v_mfma_f32_16x16x32_bf16 v[108:111], v[108:111], v[28:31], v[68:71]
	v_mul_f32_e64 v76, v120, v60
	v_mul_f32_e64 v77, v120, v61
	v_exp_f32_e32 v60, v8
	s_add_u32 s4, s0, s10
	s_addc_u32 s5, s1, s11
	v_lshl_add_u64 v[204:205], s[4:5], 0, v[186:187]
	v_pk_mul_f32 v[82:83], v[120:121], v[98:99] op_sel_hi:[0,1]
	v_add_co_u32_e32 v98, vcc, s71, v204
	v_pk_mul_f32 v[66:67], v[120:121], v[10:11] op_sel_hi:[0,1]
	v_pk_mul_f32 v[70:71], v[120:121], v[14:15] op_sel_hi:[0,1]
	v_pk_mul_f32 v[68:69], v[120:121], v[12:13] op_sel_hi:[0,1]
	v_pk_mul_f32 v[74:75], v[120:121], v[42:43] op_sel_hi:[0,1]
	v_pk_mul_f32 v[72:73], v[120:121], v[40:41] op_sel_hi:[0,1]
	v_pk_mul_f32 v[78:79], v[120:121], v[62:63] op_sel_hi:[0,1]
	v_pk_mul_f32 v[80:81], v[120:121], v[96:97] op_sel_hi:[0,1]
	v_pk_mul_f32 v[88:89], v[120:121], v[112:113] op_sel_hi:[0,1]
	v_pk_mul_f32 v[2:3], v[60:61], v[2:3] op_sel_hi:[0,1]
	v_pk_mul_f32 v[0:1], v[60:61], v[0:1] op_sel_hi:[0,1]
	v_pk_mul_f32 v[6:7], v[60:61], v[6:7] op_sel_hi:[0,1]
	v_pk_mul_f32 v[4:5], v[60:61], v[4:5] op_sel_hi:[0,1]
	v_pk_mul_f32 v[10:11], v[60:61], v[18:19] op_sel_hi:[0,1]
	v_pk_mul_f32 v[8:9], v[60:61], v[16:17] op_sel_hi:[0,1]
	v_pk_mul_f32 v[14:15], v[60:61], v[38:39] op_sel_hi:[0,1]
	v_pk_mul_f32 v[12:13], v[60:61], v[36:37] op_sel_hi:[0,1]
	v_pk_mul_f32 v[18:19], v[60:61], v[102:103] op_sel_hi:[0,1]
	v_pk_mul_f32 v[16:17], v[60:61], v[100:101] op_sel_hi:[0,1]
	v_pk_mul_f32 v[38:39], v[60:61], v[106:107] op_sel_hi:[0,1]
	v_pk_mul_f32 v[36:37], v[60:61], v[104:105] op_sel_hi:[0,1]
	v_pk_mul_f32 v[42:43], v[60:61], v[118:119] op_sel_hi:[0,1]
	v_pk_mul_f32 v[40:41], v[60:61], v[116:117] op_sel_hi:[0,1]
	v_pk_mul_f32 v[62:63], v[60:61], v[110:111] op_sel_hi:[0,1]
	v_pk_mul_f32 v[60:61], v[60:61], v[108:109] op_sel_hi:[0,1]
	v_lshl_add_u64 v[96:97], s[20:21], 0, v[188:189]
	global_load_dwordx4 v[144:147], v186, s[4:5]
	global_load_dwordx4 v[148:151], v186, s[4:5] offset:1024
	global_load_dwordx4 v[152:155], v186, s[4:5] offset:2048
	global_load_dwordx4 v[156:159], v186, s[4:5] offset:3072
	s_mov_b64 s[4:5], 0x4000
	v_addc_co_u32_e32 v99, vcc, 0, v205, vcc
	v_or_b32_e32 v100, 16, v190
	v_or_b32_e32 v104, 32, v190
	v_or_b32_e32 v108, 48, v190
	v_or_b32_e32 v112, 64, v190
	v_or_b32_e32 v124, 0x50, v190
	v_or_b32_e32 v132, 0x60, v190
	v_or_b32_e32 v140, 0x70, v190
	v_pk_mul_f32 v[86:87], v[120:121], v[86:87] op_sel_hi:[0,1]
	v_pk_mul_f32 v[84:85], v[120:121], v[84:85] op_sel_hi:[0,1]
	v_pk_mul_f32 v[90:91], v[120:121], v[114:115] op_sel_hi:[0,1]
	v_pk_mul_f32 v[94:95], v[120:121], v[94:95] op_sel_hi:[0,1]
	v_pk_mul_f32 v[92:93], v[120:121], v[92:93] op_sel_hi:[0,1]
	v_lshl_add_u64 v[202:203], v[96:97], 0, s[58:59]
	v_lshl_add_u64 v[96:97], v[204:205], 0, s[4:5]
	global_load_dwordx4 v[136:139], v[98:99], off
	global_load_dwordx4 v[128:131], v[96:97], off offset:1024
	global_load_dwordx4 v[116:119], v[96:97], off offset:2048
	global_load_dwordx4 v[120:123], v[96:97], off offset:3072
	v_ashrrev_i32_e32 v191, 31, v190
	v_ashrrev_i32_e32 v101, 31, v100
	v_ashrrev_i32_e32 v105, 31, v104
	v_ashrrev_i32_e32 v109, 31, v108
	v_ashrrev_i32_e32 v113, 31, v112
	v_ashrrev_i32_e32 v125, 31, v124
	v_ashrrev_i32_e32 v133, 31, v132
	v_ashrrev_i32_e32 v141, 31, v140
	v_lshlrev_b64 v[96:97], 6, v[190:191]
	v_lshlrev_b64 v[100:101], 6, v[100:101]
	v_lshlrev_b64 v[104:105], 6, v[104:105]
	v_lshlrev_b64 v[108:109], 6, v[108:109]
	v_lshlrev_b64 v[112:113], 6, v[112:113]
	v_lshlrev_b64 v[124:125], 6, v[124:125]
	v_lshlrev_b64 v[132:133], 6, v[132:133]
	v_lshlrev_b64 v[140:141], 6, v[140:141]
	v_lshl_add_u64 v[96:97], v[202:203], 0, v[96:97]
	v_lshl_add_u64 v[100:101], v[202:203], 0, v[100:101]
	v_lshl_add_u64 v[104:105], v[202:203], 0, v[104:105]
	v_lshl_add_u64 v[108:109], v[202:203], 0, v[108:109]
	v_lshl_add_u64 v[112:113], v[202:203], 0, v[112:113]
	v_lshl_add_u64 v[124:125], v[202:203], 0, v[124:125]
	v_lshl_add_u64 v[132:133], v[202:203], 0, v[132:133]
	v_lshl_add_u64 v[140:141], v[202:203], 0, v[140:141]
	global_load_dwordx4 v[96:99], v[96:97], off
	s_nop 0
	global_load_dwordx4 v[100:103], v[100:101], off
	s_nop 0
	global_load_dwordx4 v[104:107], v[104:105], off
	s_nop 0
	global_load_dwordx4 v[108:111], v[108:109], off
	s_nop 0
	global_load_dwordx4 v[112:115], v[112:113], off
	s_nop 0
	global_load_dwordx4 v[124:127], v[124:125], off
	s_nop 0
	global_load_dwordx4 v[132:135], v[132:133], off
	s_nop 0
	global_load_dwordx4 v[140:143], v[140:141], off
	s_waitcnt vmcnt(15)
	v_mfma_f32_16x16x32_bf16 v[160:163], v[144:147], v[44:47], 0
	v_or_b32_e32 v191, s6, v206
	v_sub_u32_e32 v164, v191, v208
	v_cvt_f32_ubyte0_e32 v164, v164
	s_waitcnt vmcnt(14)
	v_mfma_f32_16x16x32_bf16 v[160:163], v[148:151], v[48:51], v[160:163]
	v_mul_f32_e32 v164, v185, v164
	v_exp_f32_e32 v164, v164
	v_or_b32_e32 v189, 0x50, v212
	s_waitcnt vmcnt(13)
	v_mfma_f32_16x16x32_bf16 v[160:163], v[152:155], v[52:55], v[160:163]
	v_sub_u32_e32 v166, v191, v213
	v_cvt_f32_ubyte0_e32 v166, v166
	v_mul_f32_e32 v166, v185, v166
	s_waitcnt vmcnt(12)
	v_mfma_f32_16x16x32_bf16 v[160:163], v[156:159], v[56:59], v[160:163]
	v_exp_f32_e32 v166, v166
	s_mov_b64 s[4:5], 0x8000
	v_mfma_f32_16x16x32_bf16 v[144:147], v[144:147], v[32:35], 0
	v_mfma_f32_16x16x32_bf16 v[144:147], v[148:151], v[20:23], v[144:147]
	s_nop 3
	v_mul_f32_e32 v160, v164, v160
	v_add_u32_e32 v164, v191, v219
	v_cvt_f32_ubyte0_e32 v164, v164
	v_mul_f32_e32 v164, v185, v164
	v_exp_f32_e32 v164, v164
	v_mfma_f32_16x16x32_bf16 v[144:147], v[152:155], v[24:27], v[144:147]
	v_sub_u32_e32 v148, v189, v208
	v_cvt_f32_ubyte0_e32 v148, v148
	v_mul_f32_e32 v161, v164, v161
	v_sub_u32_e32 v164, v191, v218
	v_cvt_f32_ubyte0_e32 v164, v164
	v_mul_f32_e32 v164, v185, v164
	v_exp_f32_e32 v164, v164
	v_cvt_pk_bf16_f32 v160, v160, v161
	v_mul_f32_e32 v148, v185, v148
	v_mfma_f32_16x16x32_bf16 v[144:147], v[156:159], v[28:31], v[144:147]
	v_mul_f32_e32 v162, v164, v162
	v_sub_u32_e32 v164, v191, v217
	v_cvt_f32_ubyte0_e32 v164, v164
	v_mul_f32_e32 v164, v185, v164
	v_exp_f32_e32 v164, v164
	v_exp_f32_e32 v148, v148
	v_mul_f32_e32 v163, v164, v163
	v_cvt_pk_bf16_f32 v161, v162, v163
	s_waitcnt vmcnt(11)
	v_mfma_f32_16x16x32_bf16 v[162:165], v[136:139], v[44:47], 0
	v_mul_f32_e32 v144, v148, v144
	v_add_u32_e32 v148, v189, v219
	v_cvt_f32_ubyte0_e32 v148, v148
	v_mfma_f32_16x16x32_bf16 v[136:139], v[136:139], v[32:35], 0
	v_mul_f32_e32 v148, v185, v148
	v_exp_f32_e32 v148, v148
	s_waitcnt vmcnt(10)
	v_mfma_f32_16x16x32_bf16 v[162:165], v[128:131], v[48:51], v[162:165]
	v_mul_f32_e32 v145, v148, v145
	v_sub_u32_e32 v148, v189, v218
	v_mfma_f32_16x16x32_bf16 v[128:131], v[128:131], v[20:23], v[136:139]
	v_cvt_f32_ubyte0_e32 v148, v148
	v_mul_f32_e32 v148, v185, v148
	v_exp_f32_e32 v148, v148
	s_waitcnt vmcnt(9)
	v_mfma_f32_16x16x32_bf16 v[162:165], v[116:119], v[52:55], v[162:165]
	v_mul_f32_e32 v146, v148, v146
	v_mfma_f32_16x16x32_bf16 v[116:119], v[116:119], v[24:27], v[128:131]
	v_sub_u32_e32 v148, v189, v217
	v_cvt_f32_ubyte0_e32 v148, v148
	v_mul_f32_e32 v148, v185, v148
	s_waitcnt vmcnt(8)
	v_mfma_f32_16x16x32_bf16 v[162:165], v[120:123], v[56:59], v[162:165]
	v_exp_f32_e32 v148, v148
	s_nop 0
	v_mul_f32_e32 v147, v148, v147
	v_mfma_f32_16x16x32_bf16 v[116:119], v[120:123], v[28:31], v[116:119]
	v_sub_u32_e32 v120, v189, v213
	v_cvt_f32_ubyte0_e32 v120, v120
	v_mul_f32_e32 v120, v185, v120
	v_exp_f32_e32 v120, v120
	v_mul_f32_e32 v162, v166, v162
	v_sub_u32_e32 v166, v191, v216
	v_cvt_f32_ubyte0_e32 v166, v166
	s_nop 0
	v_mul_f32_e32 v116, v120, v116
	v_sub_u32_e32 v120, v189, v216
	v_cvt_f32_ubyte0_e32 v120, v120
	v_mul_f32_e32 v166, v185, v166
	v_mul_f32_e32 v120, v185, v120
	v_exp_f32_e32 v166, v166
	v_exp_f32_e32 v120, v120
	v_mul_f32_e32 v163, v166, v163
	v_sub_u32_e32 v166, v191, v215
	v_mul_f32_e32 v117, v120, v117
	v_sub_u32_e32 v120, v189, v215
	v_cvt_f32_ubyte0_e32 v166, v166
	v_cvt_f32_ubyte0_e32 v120, v120
	v_mul_f32_e32 v166, v185, v166
	v_mul_f32_e32 v120, v185, v120
	v_exp_f32_e32 v166, v166
	v_exp_f32_e32 v120, v120
	v_cvt_pk_bf16_f32 v162, v162, v163
	v_mul_f32_e32 v164, v166, v164
	v_sub_u32_e32 v166, v191, v214
	v_mul_f32_e32 v118, v120, v118
	v_sub_u32_e32 v120, v189, v214
	v_cvt_f32_ubyte0_e32 v166, v166
	v_cvt_f32_ubyte0_e32 v120, v120
	v_mul_f32_e32 v166, v185, v166
	v_mul_f32_e32 v120, v185, v120
	v_exp_f32_e32 v166, v166
	v_exp_f32_e32 v120, v120
	v_mul_f32_e32 v165, v166, v165
	v_cvt_pk_bf16_f32 v163, v164, v165
	v_cvt_pk_bf16_f32 v144, v144, v145
	v_cvt_pk_bf16_f32 v145, v146, v147
	v_mul_f32_e32 v119, v120, v119
	s_waitcnt vmcnt(7)
	v_mfma_f32_16x16x32_bf16 v[64:67], v[96:99], v[160:163], v[64:67]
	v_cvt_pk_bf16_f32 v146, v116, v117
	v_cvt_pk_bf16_f32 v147, v118, v119
	s_nop 0
	v_mfma_f32_16x16x32_bf16 v[0:3], v[96:99], v[144:147], v[0:3]
	s_waitcnt vmcnt(3)
	v_mfma_f32_16x16x32_bf16 v[96:99], v[112:115], v[144:147], v[16:19]
	s_nop 2
	v_add_co_u32_e32 v18, vcc, s73, v204
	v_lshl_add_u64 v[16:17], v[204:205], 0, s[4:5]
	s_nop 0
	v_addc_co_u32_e32 v19, vcc, 0, v205, vcc
	s_mov_b64 s[4:5], 0xc000
	global_load_dwordx4 v[168:171], v[18:19], off
	global_load_dwordx4 v[172:175], v[16:17], off offset:1024
	global_load_dwordx4 v[176:179], v[16:17], off offset:2048
	global_load_dwordx4 v[180:183], v[16:17], off offset:3072
	v_lshl_add_u64 v[16:17], v[204:205], 0, s[4:5]
	s_mov_b32 s4, 0xc000
	v_add_co_u32_e32 v18, vcc, s4, v204
	v_mfma_f32_16x16x32_bf16 v[76:79], v[108:111], v[160:163], v[76:79]
	s_nop 0
	v_addc_co_u32_e32 v19, vcc, 0, v205, vcc
	s_waitcnt vmcnt(4)
	v_mfma_f32_16x16x32_bf16 v[92:95], v[140:143], v[160:163], v[92:95]
	v_mfma_f32_16x16x32_bf16 v[12:15], v[108:111], v[144:147], v[12:15]
	v_mfma_f32_16x16x32_bf16 v[108:111], v[140:143], v[144:147], v[60:63]
	global_load_dwordx4 v[164:167], v[18:19], off
	global_load_dwordx4 v[156:159], v[16:17], off offset:1024
	global_load_dwordx4 v[148:151], v[16:17], off offset:2048
	global_load_dwordx4 v[140:143], v[16:17], off offset:3072
	v_or_b32_e32 v16, 0x80, v190
	v_ashrrev_i32_e32 v17, 31, v16
	v_lshlrev_b64 v[16:17], 6, v[16:17]
	v_lshl_add_u64 v[16:17], v[202:203], 0, v[16:17]
	global_load_dwordx4 v[120:123], v[16:17], off
	v_or_b32_e32 v16, 0x90, v190
	v_ashrrev_i32_e32 v17, 31, v16
	v_lshlrev_b64 v[16:17], 6, v[16:17]
	v_lshl_add_u64 v[16:17], v[202:203], 0, v[16:17]
	v_mfma_f32_16x16x32_bf16 v[68:71], v[100:103], v[160:163], v[68:71]
	v_mfma_f32_16x16x32_bf16 v[84:87], v[124:127], v[160:163], v[84:87]
	v_mfma_f32_16x16x32_bf16 v[4:7], v[100:103], v[144:147], v[4:7]
	v_mfma_f32_16x16x32_bf16 v[100:103], v[124:127], v[144:147], v[36:39]
	global_load_dwordx4 v[124:127], v[16:17], off
	v_or_b32_e32 v16, 0xa0, v190
	v_ashrrev_i32_e32 v17, 31, v16
	v_lshlrev_b64 v[16:17], 6, v[16:17]
	v_lshl_add_u64 v[16:17], v[202:203], 0, v[16:17]
	global_load_dwordx4 v[128:131], v[16:17], off
	v_or_b32_e32 v16, 0xb0, v190
	v_ashrrev_i32_e32 v17, 31, v16
	v_lshlrev_b64 v[16:17], 6, v[16:17]
	v_lshl_add_u64 v[16:17], v[202:203], 0, v[16:17]
	v_mfma_f32_16x16x32_bf16 v[72:75], v[104:107], v[160:163], v[72:75]
	v_mfma_f32_16x16x32_bf16 v[88:91], v[132:135], v[160:163], v[88:91]
	v_mfma_f32_16x16x32_bf16 v[8:11], v[104:107], v[144:147], v[8:11]
	v_mfma_f32_16x16x32_bf16 v[104:107], v[132:135], v[144:147], v[40:43]
	global_load_dwordx4 v[132:135], v[16:17], off
	v_or_b32_e32 v16, 0xc0, v190
	v_ashrrev_i32_e32 v17, 31, v16
	v_lshlrev_b64 v[16:17], 6, v[16:17]
	v_lshl_add_u64 v[16:17], v[202:203], 0, v[16:17]
	global_load_dwordx4 v[136:139], v[16:17], off
	v_or_b32_e32 v16, 0xd0, v190
	v_ashrrev_i32_e32 v17, 31, v16
	v_lshlrev_b64 v[16:17], 6, v[16:17]
	v_lshl_add_u64 v[16:17], v[202:203], 0, v[16:17]
	global_load_dwordx4 v[144:147], v[16:17], off
	v_or_b32_e32 v16, 0xe0, v190
	v_ashrrev_i32_e32 v17, 31, v16
	v_lshlrev_b64 v[16:17], 6, v[16:17]
	v_lshl_add_u64 v[16:17], v[202:203], 0, v[16:17]
	global_load_dwordx4 v[152:155], v[16:17], off
	v_or_b32_e32 v16, 0xf0, v190
	v_ashrrev_i32_e32 v17, 31, v16
	v_lshlrev_b64 v[16:17], 6, v[16:17]
	v_lshl_add_u64 v[16:17], v[202:203], 0, v[16:17]
	v_mfma_f32_16x16x32_bf16 v[80:83], v[112:115], v[160:163], v[80:83]
	global_load_dwordx4 v[160:163], v[16:17], off
	s_waitcnt vmcnt(15)
	v_mfma_f32_16x16x32_bf16 v[16:19], v[168:171], v[44:47], 0
	v_sub_u32_e32 v36, v191, v239
	v_cvt_f32_ubyte0_e32 v36, v36
	v_mul_f32_e32 v36, v185, v36
	s_waitcnt vmcnt(14)
	v_mfma_f32_16x16x32_bf16 v[16:19], v[172:175], v[48:51], v[16:19]
	v_exp_f32_e32 v36, v36
	v_or_b32_e32 v240, 33, v208
	v_or_b32_e32 v241, 34, v208
	s_waitcnt vmcnt(13)
	v_mfma_f32_16x16x32_bf16 v[16:19], v[176:179], v[52:55], v[16:19]
	v_or_b32_e32 v242, 35, v208
	v_or_b32_e32 v243, 49, v208
	v_or_b32_e32 v244, 50, v208
	s_waitcnt vmcnt(12)
	v_mfma_f32_16x16x32_bf16 v[16:19], v[180:183], v[56:59], v[16:19]
	v_or_b32_e32 v245, 51, v208
	s_mov_b64 s[4:5], 0x10000
	s_nop 5
	v_mul_f32_e32 v16, v36, v16
	v_sub_u32_e32 v36, v191, v240
	v_cvt_f32_ubyte0_e32 v36, v36
	v_mul_f32_e32 v36, v185, v36
	v_exp_f32_e32 v36, v36
	s_nop 0
	v_mul_f32_e32 v17, v36, v17
	v_sub_u32_e32 v36, v191, v241
	v_cvt_f32_ubyte0_e32 v36, v36
	v_mul_f32_e32 v36, v185, v36
	v_exp_f32_e32 v36, v36
	v_cvt_pk_bf16_f32 v116, v16, v17
	s_nop 0
	v_mul_f32_e32 v18, v36, v18
	v_sub_u32_e32 v36, v191, v242
	v_cvt_f32_ubyte0_e32 v36, v36
	v_mul_f32_e32 v36, v185, v36
	v_exp_f32_e32 v36, v36
	s_nop 0
	v_mul_f32_e32 v19, v36, v19
	v_cvt_pk_bf16_f32 v117, v18, v19
	s_waitcnt vmcnt(11)
	v_mfma_f32_16x16x32_bf16 v[16:19], v[164:167], v[44:47], 0
	v_sub_u32_e32 v36, v191, v222
	v_cvt_f32_ubyte0_e32 v36, v36
	v_mul_f32_e32 v36, v185, v36
	s_waitcnt vmcnt(10)
	v_mfma_f32_16x16x32_bf16 v[16:19], v[156:159], v[48:51], v[16:19]
	v_exp_f32_e32 v36, v36
	s_waitcnt vmcnt(9)
	v_mfma_f32_16x16x32_bf16 v[16:19], v[148:151], v[52:55], v[16:19]
	s_waitcnt vmcnt(8)
	v_mfma_f32_16x16x32_bf16 v[16:19], v[140:143], v[56:59], v[16:19]
	s_nop 7
	v_mul_f32_e32 v16, v36, v16
	v_sub_u32_e32 v36, v191, v243
	v_cvt_f32_ubyte0_e32 v36, v36
	v_mul_f32_e32 v36, v185, v36
	v_exp_f32_e32 v36, v36
	s_nop 0
	v_mul_f32_e32 v17, v36, v17
	v_sub_u32_e32 v36, v191, v244
	v_cvt_f32_ubyte0_e32 v36, v36
	v_mul_f32_e32 v36, v185, v36
	v_exp_f32_e32 v36, v36
	v_cvt_pk_bf16_f32 v118, v16, v17
	s_nop 0
	v_mul_f32_e32 v18, v36, v18
	v_sub_u32_e32 v36, v191, v245
	v_cvt_f32_ubyte0_e32 v36, v36
	v_mul_f32_e32 v36, v185, v36
	v_exp_f32_e32 v36, v36
	s_nop 0
	v_mul_f32_e32 v19, v36, v19
	v_cvt_pk_bf16_f32 v119, v18, v19
	s_waitcnt vmcnt(5)
	v_mfma_f32_16x16x32_bf16 v[40:43], v[128:131], v[116:119], v[72:75]
	v_mfma_f32_16x16x32_bf16 v[72:75], v[168:171], v[32:35], 0
	v_mfma_f32_16x16x32_bf16 v[72:75], v[172:175], v[20:23], v[72:75]
	v_mfma_f32_16x16x32_bf16 v[72:75], v[176:179], v[24:27], v[72:75]
	s_waitcnt vmcnt(4)
	v_mfma_f32_16x16x32_bf16 v[60:63], v[132:135], v[116:119], v[76:79]
	s_nop 2
	v_sub_u32_e32 v76, v189, v239
	v_cvt_f32_ubyte0_e32 v76, v76
	v_mul_f32_e32 v76, v185, v76
	v_mfma_f32_16x16x32_bf16 v[72:75], v[180:183], v[28:31], v[72:75]
	v_exp_f32_e32 v76, v76
	v_sub_u32_e32 v78, v189, v222
	v_cvt_f32_ubyte0_e32 v78, v78
	v_mul_f32_e32 v78, v185, v78
	v_exp_f32_e32 v78, v78
	s_nop 2
	v_mul_f32_e32 v72, v76, v72
	v_sub_u32_e32 v76, v189, v240
	v_cvt_f32_ubyte0_e32 v76, v76
	v_mul_f32_e32 v76, v185, v76
	v_exp_f32_e32 v76, v76
	v_mfma_f32_16x16x32_bf16 v[16:19], v[120:123], v[116:119], v[64:67]
	v_mul_f32_e32 v73, v76, v73
	v_sub_u32_e32 v76, v189, v241
	v_cvt_f32_ubyte0_e32 v76, v76
	v_mul_f32_e32 v76, v185, v76
	v_exp_f32_e32 v76, v76
	v_cvt_pk_bf16_f32 v72, v72, v73
	v_mfma_f32_16x16x32_bf16 v[36:39], v[124:127], v[116:119], v[68:71]
	v_mul_f32_e32 v74, v76, v74
	v_sub_u32_e32 v76, v189, v242
	v_cvt_f32_ubyte0_e32 v76, v76
	v_mul_f32_e32 v76, v185, v76
	v_exp_f32_e32 v76, v76
	s_waitcnt vmcnt(3)
	v_mfma_f32_16x16x32_bf16 v[64:67], v[136:139], v[116:119], v[80:83]
	v_mul_f32_e32 v75, v76, v75
	v_cvt_pk_bf16_f32 v73, v74, v75
	v_mfma_f32_16x16x32_bf16 v[74:77], v[164:167], v[32:35], 0
	s_nop 0
	v_mfma_f32_16x16x32_bf16 v[74:77], v[156:159], v[20:23], v[74:77]
	v_mfma_f32_16x16x32_bf16 v[74:77], v[148:151], v[24:27], v[74:77]
	v_mfma_f32_16x16x32_bf16 v[74:77], v[140:143], v[28:31], v[74:77]
	s_waitcnt vmcnt(2)
	v_mfma_f32_16x16x32_bf16 v[68:71], v[144:147], v[116:119], v[84:87]
	s_waitcnt vmcnt(1)
	v_mfma_f32_16x16x32_bf16 v[112:115], v[152:155], v[116:119], v[88:91]
	s_nop 3
	v_mul_f32_e32 v74, v78, v74
	v_sub_u32_e32 v78, v189, v243
	v_cvt_f32_ubyte0_e32 v78, v78
	v_mul_f32_e32 v78, v185, v78
	v_exp_f32_e32 v78, v78
	s_waitcnt vmcnt(0)
	v_mfma_f32_16x16x32_bf16 v[116:119], v[160:163], v[116:119], v[92:95]
	v_mul_f32_e32 v75, v78, v75
	v_sub_u32_e32 v78, v189, v244
	v_cvt_f32_ubyte0_e32 v78, v78
	v_mul_f32_e32 v78, v185, v78
	v_exp_f32_e32 v78, v78
	v_cvt_pk_bf16_f32 v74, v74, v75
	s_nop 0
	v_mul_f32_e32 v76, v78, v76
	v_sub_u32_e32 v78, v189, v245
	v_cvt_f32_ubyte0_e32 v78, v78
	v_mul_f32_e32 v78, v185, v78
	v_exp_f32_e32 v78, v78
	s_nop 0
	v_mul_f32_e32 v77, v78, v77
	v_cvt_pk_bf16_f32 v75, v76, v77
	s_nop 0
	v_mfma_f32_16x16x32_bf16 v[0:3], v[120:123], v[72:75], v[0:3]
	v_mfma_f32_16x16x32_bf16 v[4:7], v[124:127], v[72:75], v[4:7]
	v_mfma_f32_16x16x32_bf16 v[8:11], v[128:131], v[72:75], v[8:11]
	v_mfma_f32_16x16x32_bf16 v[12:15], v[132:135], v[72:75], v[12:15]
	v_mfma_f32_16x16x32_bf16 v[96:99], v[136:139], v[72:75], v[96:99]
	v_mfma_f32_16x16x32_bf16 v[100:103], v[144:147], v[72:75], v[100:103]
	v_mfma_f32_16x16x32_bf16 v[104:107], v[152:155], v[72:75], v[104:107]
	v_mfma_f32_16x16x32_bf16 v[108:111], v[160:163], v[72:75], v[108:111]
	v_add_co_u32_e32 v74, vcc, s72, v204
	v_lshl_add_u64 v[72:73], v[204:205], 0, s[4:5]
	s_nop 0
	v_addc_co_u32_e32 v75, vcc, 0, v205, vcc
	s_mov_b64 s[4:5], 0x14000
	global_load_dwordx4 v[168:171], v[74:75], off
	global_load_dwordx4 v[172:175], v[72:73], off offset:1024
	global_load_dwordx4 v[176:179], v[72:73], off offset:2048
	global_load_dwordx4 v[180:183], v[72:73], off offset:3072
	v_lshl_add_u64 v[72:73], v[204:205], 0, s[4:5]
	s_mov_b32 s4, 0x14000
	v_add_co_u32_e32 v74, vcc, s4, v204
	s_nop 1
	v_addc_co_u32_e32 v75, vcc, 0, v205, vcc
	global_load_dwordx4 v[164:167], v[74:75], off
	global_load_dwordx4 v[152:155], v[72:73], off offset:1024
	global_load_dwordx4 v[156:159], v[72:73], off offset:2048
	global_load_dwordx4 v[160:163], v[72:73], off offset:3072
	v_or_b32_e32 v72, 0x100, v190
	v_ashrrev_i32_e32 v73, 31, v72
	v_lshlrev_b64 v[72:73], 6, v[72:73]
	v_lshl_add_u64 v[72:73], v[202:203], 0, v[72:73]
	global_load_dwordx4 v[120:123], v[72:73], off
	v_or_b32_e32 v72, 0x110, v190
	v_ashrrev_i32_e32 v73, 31, v72
	v_lshlrev_b64 v[72:73], 6, v[72:73]
	v_lshl_add_u64 v[72:73], v[202:203], 0, v[72:73]
	global_load_dwordx4 v[124:127], v[72:73], off
	v_or_b32_e32 v72, 0x120, v190
	v_ashrrev_i32_e32 v73, 31, v72
	v_lshlrev_b64 v[72:73], 6, v[72:73]
	v_lshl_add_u64 v[72:73], v[202:203], 0, v[72:73]
	global_load_dwordx4 v[128:131], v[72:73], off
	v_or_b32_e32 v72, 0x130, v190
	v_ashrrev_i32_e32 v73, 31, v72
	v_lshlrev_b64 v[72:73], 6, v[72:73]
	v_lshl_add_u64 v[72:73], v[202:203], 0, v[72:73]
	global_load_dwordx4 v[132:135], v[72:73], off
	v_or_b32_e32 v72, 0x140, v190
	v_ashrrev_i32_e32 v73, 31, v72
	v_lshlrev_b64 v[72:73], 6, v[72:73]
	v_lshl_add_u64 v[72:73], v[202:203], 0, v[72:73]
	global_load_dwordx4 v[136:139], v[72:73], off
	v_or_b32_e32 v72, 0x150, v190
	v_ashrrev_i32_e32 v73, 31, v72
	v_lshlrev_b64 v[72:73], 6, v[72:73]
	v_lshl_add_u64 v[72:73], v[202:203], 0, v[72:73]
	global_load_dwordx4 v[140:143], v[72:73], off
	v_or_b32_e32 v72, 0x160, v190
	v_ashrrev_i32_e32 v73, 31, v72
	v_lshlrev_b64 v[72:73], 6, v[72:73]
	v_lshl_add_u64 v[72:73], v[202:203], 0, v[72:73]
	global_load_dwordx4 v[144:147], v[72:73], off
	v_or_b32_e32 v72, 0x170, v190
	v_ashrrev_i32_e32 v73, 31, v72
	v_lshlrev_b64 v[72:73], 6, v[72:73]
	v_lshl_add_u64 v[72:73], v[202:203], 0, v[72:73]
	global_load_dwordx4 v[148:151], v[72:73], off
	s_waitcnt vmcnt(15)
	v_mfma_f32_16x16x32_bf16 v[72:75], v[168:171], v[44:47], 0
	v_or_b32_e32 v204, 64, v208
	v_sub_u32_e32 v76, v191, v204
	v_cmp_lt_i32_e32 vcc, -1, v76
	s_waitcnt vmcnt(14)
	v_mfma_f32_16x16x32_bf16 v[72:75], v[172:175], v[48:51], v[72:75]
	v_cvt_f32_u32_e32 v76, v76
	v_or_b32_e32 v205, 0x41, v208
	v_or_b32_e32 v222, 0x42, v208
	s_waitcnt vmcnt(13)
	v_mfma_f32_16x16x32_bf16 v[72:75], v[176:179], v[52:55], v[72:75]
	v_mul_f32_e32 v76, v185, v76
	v_exp_f32_e32 v76, v76
	v_or_b32_e32 v239, 0x43, v208
	s_waitcnt vmcnt(12)
	v_mfma_f32_16x16x32_bf16 v[72:75], v[180:183], v[56:59], v[72:75]
	v_or_b32_e32 v244, 0x51, v208
	v_or_b32_e32 v245, 0x52, v208
	v_or_b32_e32 v246, 0x53, v208
	s_cmp_eq_u32 s70, 0
	s_nop 3
	v_mul_f32_e32 v72, v76, v72
	v_sub_u32_e32 v76, v191, v205
	v_cndmask_b32_e32 v72, 0, v72, vcc
	v_cmp_lt_i32_e32 vcc, -1, v76
	v_cvt_f32_u32_e32 v76, v76
	v_mul_f32_e32 v76, v185, v76
	v_exp_f32_e32 v76, v76
	s_nop 0
	v_mul_f32_e32 v73, v76, v73
	v_sub_u32_e32 v76, v191, v222
	v_cndmask_b32_e32 v73, 0, v73, vcc
	v_cmp_lt_i32_e32 vcc, -1, v76
	v_cvt_f32_u32_e32 v76, v76
	v_cvt_pk_bf16_f32 v240, v72, v73
	v_mul_f32_e32 v76, v185, v76
	v_exp_f32_e32 v76, v76
	s_nop 0
	v_mul_f32_e32 v74, v76, v74
	v_sub_u32_e32 v76, v191, v239
	v_cndmask_b32_e32 v74, 0, v74, vcc
	v_cmp_lt_i32_e32 vcc, -1, v76
	v_cvt_f32_u32_e32 v76, v76
	v_mul_f32_e32 v76, v185, v76
	v_exp_f32_e32 v76, v76
	s_nop 0
	v_mul_f32_e32 v75, v76, v75
	v_cndmask_b32_e32 v75, 0, v75, vcc
	v_cvt_pk_bf16_f32 v241, v74, v75
	s_waitcnt vmcnt(11)
	v_mfma_f32_16x16x32_bf16 v[72:75], v[164:167], v[44:47], 0
	v_or_b32_e32 v76, 0x50, v208
	v_sub_u32_e32 v76, v191, v76
	v_cmp_lt_i32_e32 vcc, -1, v76
	s_waitcnt vmcnt(10)
	v_mfma_f32_16x16x32_bf16 v[72:75], v[152:155], v[48:51], v[72:75]
	v_cvt_f32_u32_e32 v76, v76
	v_mul_f32_e32 v76, v185, v76
	s_waitcnt vmcnt(9)
	v_mfma_f32_16x16x32_bf16 v[72:75], v[156:159], v[52:55], v[72:75]
	v_exp_f32_e32 v76, v76
	s_waitcnt vmcnt(8)
	v_mfma_f32_16x16x32_bf16 v[72:75], v[160:163], v[56:59], v[72:75]
	s_nop 7
	v_mul_f32_e32 v72, v76, v72
	v_sub_u32_e32 v76, v191, v244
	v_cndmask_b32_e32 v72, 0, v72, vcc
	v_cmp_lt_i32_e32 vcc, -1, v76
	v_cvt_f32_u32_e32 v76, v76
	v_mul_f32_e32 v76, v185, v76
	v_exp_f32_e32 v76, v76
	s_nop 0
	v_mul_f32_e32 v73, v76, v73
	v_sub_u32_e32 v76, v191, v245
	v_cndmask_b32_e32 v73, 0, v73, vcc
	v_cmp_lt_i32_e32 vcc, -1, v76
	v_cvt_f32_u32_e32 v76, v76
	v_cvt_pk_bf16_f32 v242, v72, v73
	v_mul_f32_e32 v76, v185, v76
	v_exp_f32_e32 v76, v76
	s_nop 0
	v_mul_f32_e32 v74, v76, v74
	v_sub_u32_e32 v76, v191, v246
	v_cndmask_b32_e32 v74, 0, v74, vcc
	v_cmp_lt_i32_e32 vcc, -1, v76
	v_cvt_f32_u32_e32 v76, v76
	v_mul_f32_e32 v76, v185, v76
	v_exp_f32_e32 v76, v76
	s_nop 0
	v_mul_f32_e32 v75, v76, v75
	v_cndmask_b32_e32 v75, 0, v75, vcc
	v_cvt_pk_bf16_f32 v243, v74, v75
	s_waitcnt vmcnt(7)
	v_mfma_f32_16x16x32_bf16 v[92:95], v[120:123], v[240:243], v[16:19]
	v_mfma_f32_16x16x32_bf16 v[16:19], v[168:171], v[32:35], 0
	v_mfma_f32_16x16x32_bf16 v[16:19], v[172:175], v[20:23], v[16:19]
	v_mfma_f32_16x16x32_bf16 v[16:19], v[176:179], v[24:27], v[16:19]
	s_waitcnt vmcnt(6)
	v_mfma_f32_16x16x32_bf16 v[88:91], v[124:127], v[240:243], v[36:39]
	s_nop 2
	v_sub_u32_e32 v36, v189, v204
	v_cvt_f32_ubyte0_e32 v36, v36
	v_mul_f32_e32 v36, v185, v36
	v_mfma_f32_16x16x32_bf16 v[16:19], v[180:183], v[28:31], v[16:19]
	v_exp_f32_e32 v36, v36
	s_waitcnt vmcnt(2)
	v_mfma_f32_16x16x32_bf16 v[72:75], v[140:143], v[240:243], v[68:71]
	s_waitcnt vmcnt(1)
	v_mfma_f32_16x16x32_bf16 v[68:71], v[144:147], v[240:243], v[112:115]
	s_nop 2
	v_mul_f32_e32 v16, v36, v16
	v_sub_u32_e32 v36, v189, v205
	v_cvt_f32_ubyte0_e32 v36, v36
	v_mul_f32_e32 v36, v185, v36
	v_exp_f32_e32 v36, v36
	v_mfma_f32_16x16x32_bf16 v[84:87], v[128:131], v[240:243], v[40:43]
	v_mul_f32_e32 v17, v36, v17
	v_sub_u32_e32 v36, v189, v222
	v_cvt_f32_ubyte0_e32 v36, v36
	v_mul_f32_e32 v36, v185, v36
	v_exp_f32_e32 v36, v36
	v_cvt_pk_bf16_f32 v112, v16, v17
	v_mfma_f32_16x16x32_bf16 v[80:83], v[132:135], v[240:243], v[60:63]
	v_mul_f32_e32 v18, v36, v18
	v_sub_u32_e32 v36, v189, v239
	v_cvt_f32_ubyte0_e32 v36, v36
	v_mul_f32_e32 v36, v185, v36
	v_exp_f32_e32 v36, v36
	v_mfma_f32_16x16x32_bf16 v[76:79], v[136:139], v[240:243], v[64:67]
	v_mul_f32_e32 v19, v36, v19
	v_cvt_pk_bf16_f32 v113, v18, v19
	v_mfma_f32_16x16x32_bf16 v[16:19], v[164:167], v[32:35], 0
	v_sub_u32_e32 v36, v212, v208
	v_cmp_lt_i32_e32 vcc, -1, v36
	v_cvt_f32_u32_e32 v36, v36
	v_mfma_f32_16x16x32_bf16 v[16:19], v[152:155], v[20:23], v[16:19]
	v_mul_f32_e32 v36, v185, v36
	v_mfma_f32_16x16x32_bf16 v[16:19], v[156:159], v[24:27], v[16:19]
	v_exp_f32_e32 v36, v36
	v_mfma_f32_16x16x32_bf16 v[16:19], v[160:163], v[28:31], v[16:19]
	s_waitcnt vmcnt(0)
	v_mfma_f32_16x16x32_bf16 v[64:67], v[148:151], v[240:243], v[116:119]
	s_nop 5
	v_mul_f32_e32 v16, v36, v16
	v_sub_u32_e32 v36, v189, v244
	v_cndmask_b32_e32 v16, 0, v16, vcc
	v_cmp_lt_i32_e32 vcc, -1, v36
	v_cvt_f32_u32_e32 v36, v36
	v_mul_f32_e32 v36, v185, v36
	v_exp_f32_e32 v36, v36
	s_nop 0
	v_mul_f32_e32 v17, v36, v17
	v_sub_u32_e32 v36, v189, v245
	v_cndmask_b32_e32 v17, 0, v17, vcc
	v_cmp_lt_i32_e32 vcc, -1, v36
	v_cvt_f32_u32_e32 v36, v36
	v_cvt_pk_bf16_f32 v114, v16, v17
	v_mul_f32_e32 v36, v185, v36
	v_exp_f32_e32 v36, v36
	s_nop 0
	v_mul_f32_e32 v18, v36, v18
	v_sub_u32_e32 v36, v189, v246
	v_cndmask_b32_e32 v18, 0, v18, vcc
	v_cmp_lt_i32_e32 vcc, -1, v36
	v_cvt_f32_u32_e32 v36, v36
	v_mul_f32_e32 v36, v185, v36
	v_exp_f32_e32 v36, v36
	s_nop 0
	v_mul_f32_e32 v19, v36, v19
	v_cndmask_b32_e32 v19, 0, v19, vcc
	v_cvt_pk_bf16_f32 v115, v18, v19
	s_nop 0
	v_mfma_f32_16x16x32_bf16 v[60:63], v[120:123], v[112:115], v[0:3]
	v_mfma_f32_16x16x32_bf16 v[40:43], v[124:127], v[112:115], v[4:7]
	v_mfma_f32_16x16x32_bf16 v[36:39], v[128:131], v[112:115], v[8:11]
	v_mfma_f32_16x16x32_bf16 v[16:19], v[132:135], v[112:115], v[12:15]
	v_mfma_f32_16x16x32_bf16 v[12:15], v[136:139], v[112:115], v[96:99]
	v_mfma_f32_16x16x32_bf16 v[8:11], v[140:143], v[112:115], v[100:103]
	v_mfma_f32_16x16x32_bf16 v[4:7], v[144:147], v[112:115], v[104:107]
	v_mfma_f32_16x16x32_bf16 v[0:3], v[148:151], v[112:115], v[108:111]
	s_cbranch_scc1 .LBB0_787
	s_add_u32 s0, s0, s10
	s_addc_u32 s1, s1, s11
	v_lshl_add_u64 v[96:97], s[0:1], 0, v[186:187]
	s_mov_b64 s[0:1], 0x18000
	v_add_co_u32_e32 v100, vcc, 0x18000, v96
	v_lshl_add_u64 v[98:99], v[96:97], 0, s[0:1]
	s_nop 0
	v_addc_co_u32_e32 v101, vcc, 0, v97, vcc
	s_mov_b64 s[0:1], 0x1c000
	global_load_dwordx4 v[144:147], v[98:99], off offset:1024
	global_load_dwordx4 v[148:151], v[98:99], off offset:2048
	global_load_dwordx4 v[156:159], v[100:101], off
	global_load_dwordx4 v[152:155], v[98:99], off offset:3072
	v_lshl_add_u64 v[98:99], v[96:97], 0, s[0:1]
	v_add_co_u32_e32 v96, vcc, 0x1c000, v96
	v_or_b32_e32 v104, 0x1a0, v190
	s_nop 0
	v_addc_co_u32_e32 v97, vcc, 0, v97, vcc
	global_load_dwordx4 v[128:131], v[98:99], off offset:1024
	global_load_dwordx4 v[132:135], v[98:99], off offset:2048
	global_load_dwordx4 v[140:143], v[96:97], off
	global_load_dwordx4 v[136:139], v[98:99], off offset:3072
	v_or_b32_e32 v96, 0x180, v190
	v_or_b32_e32 v98, 0x190, v190
	v_or_b32_e32 v106, 0x1b0, v190
	v_or_b32_e32 v112, 0x1c0, v190
	v_or_b32_e32 v114, 0x1d0, v190
	v_or_b32_e32 v120, 0x1e0, v190
	v_or_b32_e32 v122, 0x1f0, v190
	v_ashrrev_i32_e32 v97, 31, v96
	v_ashrrev_i32_e32 v99, 31, v98
	v_ashrrev_i32_e32 v105, 31, v104
	v_ashrrev_i32_e32 v107, 31, v106
	v_ashrrev_i32_e32 v113, 31, v112
	v_ashrrev_i32_e32 v115, 31, v114
	v_ashrrev_i32_e32 v121, 31, v120
	v_ashrrev_i32_e32 v123, 31, v122
	v_lshlrev_b64 v[96:97], 6, v[96:97]
	v_lshlrev_b64 v[98:99], 6, v[98:99]
	v_lshlrev_b64 v[104:105], 6, v[104:105]
	v_lshlrev_b64 v[106:107], 6, v[106:107]
	v_lshlrev_b64 v[112:113], 6, v[112:113]
	v_lshlrev_b64 v[114:115], 6, v[114:115]
	v_lshlrev_b64 v[120:121], 6, v[120:121]
	v_lshlrev_b64 v[122:123], 6, v[122:123]
	v_lshl_add_u64 v[96:97], v[202:203], 0, v[96:97]
	v_lshl_add_u64 v[100:101], v[202:203], 0, v[98:99]
	v_lshl_add_u64 v[104:105], v[202:203], 0, v[104:105]
	v_lshl_add_u64 v[108:109], v[202:203], 0, v[106:107]
	v_lshl_add_u64 v[112:113], v[202:203], 0, v[112:113]
	v_lshl_add_u64 v[116:117], v[202:203], 0, v[114:115]
	v_lshl_add_u64 v[120:121], v[202:203], 0, v[120:121]
	v_lshl_add_u64 v[124:125], v[202:203], 0, v[122:123]
	global_load_dwordx4 v[96:99], v[96:97], off
	s_nop 0
	global_load_dwordx4 v[100:103], v[100:101], off
	s_nop 0
	global_load_dwordx4 v[104:107], v[104:105], off
	s_nop 0
	global_load_dwordx4 v[108:111], v[108:109], off
	s_nop 0
	global_load_dwordx4 v[112:115], v[112:113], off
	s_nop 0
	global_load_dwordx4 v[116:119], v[116:117], off
	s_nop 0
	global_load_dwordx4 v[120:123], v[120:121], off
	s_nop 0
	global_load_dwordx4 v[124:127], v[124:125], off
	s_waitcnt vmcnt(13)
	v_mfma_f32_16x16x32_bf16 v[44:47], v[156:159], v[44:47], 0
	v_mfma_f32_16x16x32_bf16 v[44:47], v[144:147], v[48:51], v[44:47]
	v_or_b32_e32 v49, 0x61, v208
	v_sub_u32_e32 v50, v238, v49
	v_cmp_lt_i32_e64 s[40:41], -1, v50
	v_cvt_f32_u32_e32 v50, v50
	v_mfma_f32_16x16x32_bf16 v[44:47], v[148:151], v[52:55], v[44:47]
	v_sub_u32_e32 v48, v206, v208
	v_cmp_lt_i32_e32 vcc, -1, v48
	v_mul_f32_e32 v50, v185, v50
	s_waitcnt vmcnt(12)
	v_mfma_f32_16x16x32_bf16 v[44:47], v[152:155], v[56:59], v[44:47]
	v_exp_f32_e32 v50, v50
	v_cvt_f32_u32_e32 v48, v48
	v_sub_u32_e32 v49, v223, v49
	v_cvt_f32_ubyte0_e32 v49, v49
	v_mul_f32_e32 v49, v185, v49
	s_nop 2
	v_mul_f32_e32 v45, v50, v45
	v_or_b32_e32 v50, 0x62, v208
	v_sub_u32_e32 v51, v238, v50
	v_cndmask_b32_e64 v45, 0, v45, s[40:41]
	v_cmp_lt_i32_e64 s[40:41], -1, v51
	v_cvt_f32_u32_e32 v51, v51
	v_mul_f32_e32 v48, v185, v48
	v_exp_f32_e32 v48, v48
	v_exp_f32_e32 v49, v49
	v_mul_f32_e32 v51, v185, v51
	v_exp_f32_e32 v51, v51
	v_mul_f32_e32 v44, v48, v44
	v_cndmask_b32_e32 v44, 0, v44, vcc
	v_cvt_pk_bf16_f32 v44, v44, v45
	v_mul_f32_e32 v46, v51, v46
	v_or_b32_e32 v51, 0x63, v208
	v_sub_u32_e32 v52, v238, v51
	v_cndmask_b32_e64 v46, 0, v46, s[40:41]
	v_cmp_lt_i32_e64 s[40:41], -1, v52
	v_cvt_f32_u32_e32 v52, v52
	v_mul_f32_e32 v52, v185, v52
	v_exp_f32_e32 v52, v52
	s_nop 0
	v_mul_f32_e32 v47, v52, v47
	v_cndmask_b32_e64 v47, 0, v47, s[40:41]
	v_cvt_pk_bf16_f32 v45, v46, v47
	v_cvt_pk_bf16_f32 v46, v197, v197
	v_cvt_pk_bf16_f32 v47, v197, v197
	v_sub_u32_e32 v52, v210, v208
	v_cvt_f32_ubyte0_e32 v52, v52
	s_waitcnt vmcnt(7)
	v_mfma_f32_16x16x32_bf16 v[92:95], v[96:99], v[44:47], v[92:95]
	v_mul_f32_e32 v52, v185, v52
	v_exp_f32_e32 v52, v52
	s_waitcnt vmcnt(6)
	v_mfma_f32_16x16x32_bf16 v[88:91], v[100:103], v[44:47], v[88:91]
	s_waitcnt vmcnt(5)
	v_mfma_f32_16x16x32_bf16 v[84:87], v[104:107], v[44:47], v[84:87]
	s_waitcnt vmcnt(4)
	v_mfma_f32_16x16x32_bf16 v[80:83], v[108:111], v[44:47], v[80:83]
	s_waitcnt vmcnt(3)
	v_mfma_f32_16x16x32_bf16 v[76:79], v[112:115], v[44:47], v[76:79]
	s_waitcnt vmcnt(2)
	v_mfma_f32_16x16x32_bf16 v[72:75], v[116:119], v[44:47], v[72:75]
	s_waitcnt vmcnt(1)
	v_mfma_f32_16x16x32_bf16 v[68:71], v[120:123], v[44:47], v[68:71]
	s_waitcnt vmcnt(0)
	v_mfma_f32_16x16x32_bf16 v[64:67], v[124:127], v[44:47], v[64:67]
	v_mfma_f32_16x16x32_bf16 v[44:47], v[156:159], v[32:35], 0
	v_mfma_f32_16x16x32_bf16 v[32:35], v[140:143], v[32:35], 0
	v_mfma_f32_16x16x32_bf16 v[44:47], v[144:147], v[20:23], v[44:47]
	v_mfma_f32_16x16x32_bf16 v[20:23], v[128:131], v[20:23], v[32:35]
	v_mfma_f32_16x16x32_bf16 v[20:23], v[132:135], v[24:27], v[20:23]
	v_mfma_f32_16x16x32_bf16 v[20:23], v[136:139], v[28:31], v[20:23]
	v_mfma_f32_16x16x32_bf16 v[44:47], v[148:151], v[24:27], v[44:47]
	v_or_b32_e32 v24, 0x71, v208
	s_nop 5
	v_mul_f32_e32 v20, v48, v20
	v_sub_u32_e32 v24, v223, v24
	v_cndmask_b32_e32 v20, 0, v20, vcc
	v_cmp_lt_i32_e32 vcc, -1, v24
	v_cvt_f32_u32_e32 v24, v24
	v_mfma_f32_16x16x32_bf16 v[44:47], v[152:155], v[28:31], v[44:47]
	v_mul_f32_e32 v24, v185, v24
	v_exp_f32_e32 v24, v24
	s_nop 0
	v_mul_f32_e32 v21, v24, v21
	v_or_b32_e32 v24, 0x72, v208
	v_sub_u32_e32 v24, v223, v24
	v_cndmask_b32_e32 v21, 0, v21, vcc
	v_cmp_lt_i32_e32 vcc, -1, v24
	v_cvt_f32_u32_e32 v24, v24
	v_mul_f32_e32 v45, v49, v45
	v_sub_u32_e32 v49, v223, v50
	v_cvt_f32_ubyte0_e32 v49, v49
	v_mul_f32_e32 v24, v185, v24
	v_exp_f32_e32 v24, v24
	v_mul_f32_e32 v49, v185, v49
	v_exp_f32_e32 v49, v49
	v_mul_f32_e32 v44, v52, v44
	v_mul_f32_e32 v22, v24, v22
	v_or_b32_e32 v24, 0x73, v208
	v_sub_u32_e32 v24, v223, v24
	v_cndmask_b32_e32 v22, 0, v22, vcc
	v_cmp_lt_i32_e32 vcc, -1, v24
	v_cvt_f32_u32_e32 v24, v24
	v_mul_f32_e32 v46, v49, v46
	v_sub_u32_e32 v49, v223, v51
	v_cvt_f32_ubyte0_e32 v49, v49
	v_mul_f32_e32 v49, v185, v49
	v_mul_f32_e32 v24, v185, v24
	v_exp_f32_e32 v49, v49
	v_exp_f32_e32 v24, v24
	v_cvt_pk_bf16_f32 v44, v44, v45
	v_mul_f32_e32 v47, v49, v47
	v_mul_f32_e32 v23, v24, v23
	v_cvt_pk_bf16_f32 v45, v46, v47
	v_cndmask_b32_e32 v23, 0, v23, vcc
	v_cvt_pk_bf16_f32 v46, v20, v21
	v_cvt_pk_bf16_f32 v47, v22, v23
	s_nop 0
	v_mfma_f32_16x16x32_bf16 v[60:63], v[96:99], v[44:47], v[60:63]
	v_mfma_f32_16x16x32_bf16 v[40:43], v[100:103], v[44:47], v[40:43]
	v_mfma_f32_16x16x32_bf16 v[36:39], v[104:107], v[44:47], v[36:39]
	v_mfma_f32_16x16x32_bf16 v[16:19], v[108:111], v[44:47], v[16:19]
	v_mfma_f32_16x16x32_bf16 v[12:15], v[112:115], v[44:47], v[12:15]
	v_mfma_f32_16x16x32_bf16 v[8:11], v[116:119], v[44:47], v[8:11]
	v_mfma_f32_16x16x32_bf16 v[4:7], v[120:123], v[44:47], v[4:7]
	v_mfma_f32_16x16x32_bf16 v[0:3], v[124:127], v[44:47], v[0:3]
.LBB0_787:
	v_and_b32_e32 v22, 64, v228
	v_xor_b32_e32 v20, 16, v228
	v_add_u32_e32 v22, 64, v22
	v_cmp_lt_i32_e32 vcc, v20, v22
	v_or_b32_e32 v54, s38, v206
	v_mov_b32_e32 v21, s39
	v_cndmask_b32_e32 v20, v228, v20, vcc
	v_lshlrev_b32_e32 v53, 2, v20
	v_xor_b32_e32 v20, 32, v228
	v_cmp_lt_i32_e32 vcc, v20, v22
	s_add_i32 s9, s22, 0x200
	s_ashr_i32 s10, s9, 4
	v_cndmask_b32_e32 v20, v228, v20, vcc
	v_lshlrev_b32_e32 v52, 2, v20
	v_or_b32_e32 v20, s68, v54
	v_lshlrev_b64 v[22:23], 2, v[20:21]
	v_and_b32_e32 v25, 0x7fffff, v23
	v_and_b32_e32 v24, 0xffffff80, v22
	s_ashr_i32 s11, s10, 31
	v_lshl_add_u64 v[22:23], s[20:21], 0, v[196:197]
	s_mov_b64 s[0:1], 0x1c801000
	v_lshl_add_u64 v[26:27], v[24:25], 0, s[10:11]
	v_lshl_add_u64 v[22:23], v[22:23], 0, s[0:1]
	v_lshlrev_b64 v[26:27], 9, v[26:27]
	v_lshl_add_u64 v[26:27], v[22:23], 0, v[26:27]
	global_load_dwordx2 v[44:45], v[26:27], off nt
	s_add_i32 s8, s22, 0x210
	v_mul_f32_e32 v55, v93, v93
	s_ashr_i32 s12, s8, 4
	v_fmac_f32_e32 v55, v92, v92
	s_ashr_i32 s13, s12, 31
	v_fmac_f32_e32 v55, v94, v94
	v_lshl_add_u64 v[26:27], v[24:25], 0, s[12:13]
	v_fmac_f32_e32 v55, v95, v95
	v_lshlrev_b64 v[26:27], 9, v[26:27]
	v_fmac_f32_e32 v55, v88, v88
	v_lshl_add_u64 v[26:27], v[22:23], 0, v[26:27]
	v_fmac_f32_e32 v55, v89, v89
	global_load_dwordx2 v[50:51], v[26:27], off nt
	v_fmac_f32_e32 v55, v90, v90
	s_add_i32 s7, s22, 0x220
	v_fmac_f32_e32 v55, v91, v91
	s_ashr_i32 s24, s7, 4
	v_fmac_f32_e32 v55, v84, v84
	s_ashr_i32 s25, s24, 31
	v_fmac_f32_e32 v55, v85, v85
	v_lshl_add_u64 v[26:27], v[24:25], 0, s[24:25]
	s_add_i32 s6, s22, 0x230
	v_fmac_f32_e32 v55, v86, v86
	v_lshlrev_b64 v[26:27], 9, v[26:27]
	s_ashr_i32 s34, s6, 4
	v_fmac_f32_e32 v55, v87, v87
	v_lshl_add_u64 v[26:27], v[22:23], 0, v[26:27]
	s_ashr_i32 s35, s34, 31
	v_fmac_f32_e32 v55, v80, v80
	global_load_dwordx2 v[48:49], v[26:27], off nt
	v_lshl_add_u64 v[26:27], v[24:25], 0, s[34:35]
	s_add_i32 s5, s22, 0x240
	v_fmac_f32_e32 v55, v81, v81
	v_lshlrev_b64 v[26:27], 9, v[26:27]
	s_ashr_i32 s36, s5, 4
	v_fmac_f32_e32 v55, v82, v82
	v_lshl_add_u64 v[26:27], v[22:23], 0, v[26:27]
	s_ashr_i32 s37, s36, 31
	v_fmac_f32_e32 v55, v83, v83
	global_load_dwordx2 v[46:47], v[26:27], off nt
	v_lshl_add_u64 v[26:27], v[24:25], 0, s[36:37]
	s_add_i32 s4, s22, 0x250
	v_fmac_f32_e32 v55, v76, v76
	v_lshlrev_b64 v[26:27], 9, v[26:27]
	s_ashr_i32 s40, s4, 4
	v_fmac_f32_e32 v55, v77, v77
	v_lshl_add_u64 v[26:27], v[22:23], 0, v[26:27]
	s_ashr_i32 s41, s40, 31
	v_fmac_f32_e32 v55, v78, v78
	global_load_dwordx2 v[34:35], v[26:27], off nt
	v_lshl_add_u64 v[26:27], v[24:25], 0, s[40:41]
	s_add_i32 s1, s22, 0x260
	s_add_i32 s0, s22, 0x270
	v_fmac_f32_e32 v55, v79, v79
	v_lshlrev_b64 v[26:27], 9, v[26:27]
	s_ashr_i32 s44, s1, 4
	s_ashr_i32 s46, s0, 4
	v_fmac_f32_e32 v55, v72, v72
	v_lshl_add_u64 v[26:27], v[22:23], 0, v[26:27]
	s_ashr_i32 s45, s44, 31
	s_ashr_i32 s47, s46, 31
	v_fmac_f32_e32 v55, v73, v73
	global_load_dwordx2 v[32:33], v[26:27], off nt
	v_lshl_add_u64 v[26:27], v[24:25], 0, s[44:45]
	v_lshl_add_u64 v[24:25], v[24:25], 0, s[46:47]
	v_fmac_f32_e32 v55, v74, v74
	v_lshlrev_b64 v[26:27], 9, v[26:27]
	v_lshlrev_b64 v[24:25], 9, v[24:25]
	v_fmac_f32_e32 v55, v75, v75
	v_pk_mul_f32 v[28:29], v[68:69], v[68:69]
	v_lshl_add_u64 v[26:27], v[22:23], 0, v[26:27]
	v_lshl_add_u64 v[24:25], v[22:23], 0, v[24:25]
	v_add_f32_e32 v28, v28, v55
	global_load_dwordx2 v[30:31], v[26:27], off nt
	v_add_f32_e32 v28, v29, v28
	global_load_dwordx2 v[24:25], v[24:25], off nt
	v_pk_mul_f32 v[26:27], v[70:71], v[70:71]
	v_mov_b32_e32 v97, v92
	v_add_f32_e32 v26, v26, v28
	v_add_f32_e32 v55, v27, v26
	v_pk_mul_f32 v[28:29], v[64:65], v[64:65]
	v_pk_mul_f32 v[26:27], v[66:67], v[66:67]
	v_add_f32_e32 v28, v28, v55
	v_add_f32_e32 v28, v29, v28
	v_add_f32_e32 v26, v26, v28
	v_add_f32_e32 v26, v27, v26
	ds_bpermute_b32 v27, v53, v26
	s_waitcnt vmcnt(7)
	v_lshlrev_b32_e32 v28, 16, v44
	v_and_b32_e32 v44, 0xffff0000, v44
	v_lshlrev_b32_e32 v56, 16, v45
	v_and_b32_e32 v58, 0xffff0000, v45
	s_waitcnt lgkmcnt(0)
	v_add_f32_e32 v26, v26, v27
	ds_bpermute_b32 v27, v52, v26
	s_ashr_i32 s48, s9, 5
	s_ashr_i32 s49, s48, 31
	v_mov_b32_e32 v185, v197
	s_ashr_i32 s50, s7, 5
	s_waitcnt lgkmcnt(0)
	v_add_f32_e32 v26, v26, v27
	v_fmamk_f32 v26, v26, 0x3c000000, v227
	v_cmp_gt_f32_e32 vcc, s15, v26
	v_mul_f32_e32 v27, 0x4b800000, v26
	s_ashr_i32 s51, s50, 31
	v_cndmask_b32_e32 v26, v26, v27, vcc
	v_rsq_f32_e32 v26, v26
	s_ashr_i32 s52, s6, 5
	s_ashr_i32 s53, s52, 31
	s_ashr_i32 s54, s5, 5
	v_mul_f32_e32 v27, 0x45800000, v26
	v_cndmask_b32_e32 v29, v26, v27, vcc
	v_lshlrev_b64 v[26:27], 1, v[20:21]
	v_mul_f32_e32 v20, 0xbfb8aa3b, v28
	v_exp_f32_e32 v20, v20
	v_mov_b32_e32 v45, v29
	v_mov_b32_e32 v57, v29
	v_mov_b32_e32 v59, v29
	v_add_f32_e32 v20, 1.0, v20
	v_rcp_f32_e32 v96, v20
	v_and_b32_e32 v27, 0x3fffff, v27
	v_and_b32_e32 v26, 0xffffffc0, v26
	s_ashr_i32 s55, s54, 31
	v_pk_mul_f32 v[96:97], v[96:97], v[28:29]
	v_mul_f32_e32 v28, 0xbfb8aa3b, v44
	v_exp_f32_e32 v28, v28
	v_mul_f32_e32 v20, v96, v97
	s_ashr_i32 s56, s4, 5
	s_ashr_i32 s57, s56, 31
	v_add_f32_e32 v28, 1.0, v28
	v_rcp_f32_e32 v92, v28
	s_ashr_i32 s58, s1, 5
	s_ashr_i32 s59, s58, 31
	s_ashr_i32 s60, s0, 5
	v_pk_mul_f32 v[44:45], v[92:93], v[44:45]
	s_ashr_i32 s61, s60, 31
	v_mul_f32_e32 v28, v44, v45
	v_cvt_pk_bf16_f32 v92, v20, v28
	v_mul_f32_e32 v20, 0xbfb8aa3b, v56
	v_exp_f32_e32 v20, v20
	v_mul_f32_e32 v28, 0xbfb8aa3b, v58
	v_exp_f32_e32 v28, v28
	v_mov_b32_e32 v45, v94
	v_add_f32_e32 v20, 1.0, v20
	v_rcp_f32_e32 v44, v20
	v_add_f32_e32 v28, 1.0, v28
	v_rcp_f32_e32 v94, v28
	v_mov_b32_e32 v55, v60
	v_pk_mul_f32 v[44:45], v[44:45], v[56:57]
	v_lshl_add_u64 v[56:57], v[26:27], 0, s[48:49]
	v_mul_f32_e32 v20, v44, v45
	v_pk_mul_f32 v[44:45], v[94:95], v[58:59]
	v_lshlrev_b64 v[56:57], 10, v[56:57]
	v_mul_f32_e32 v28, v44, v45
	v_cvt_pk_bf16_f32 v93, v20, v28
	v_and_or_b32 v20, v207, 16, v206
	s_waitcnt vmcnt(6)
	v_lshlrev_b32_e32 v28, 16, v50
	v_lshlrev_b32_e32 v44, 4, v20
	v_mul_f32_e32 v20, 0xbfb8aa3b, v28
	v_mov_b32_e32 v45, v197
	v_exp_f32_e32 v20, v20
	v_lshl_add_u64 v[44:45], s[20:21], 0, v[44:45]
	s_mov_b64 s[20:21], 0xfe01000
	v_lshl_add_u64 v[44:45], v[44:45], 0, s[20:21]
	v_lshl_add_u64 v[56:57], v[44:45], 0, v[56:57]
	v_lshl_add_u64 v[56:57], v[56:57], 0, v[184:185]
	v_add_f32_e32 v20, 1.0, v20
	global_store_dwordx2 v[56:57], v[92:93], off nt
	v_rcp_f32_e32 v92, v20
	v_and_b32_e32 v50, 0xffff0000, v50
	v_mov_b32_e32 v93, v88
	v_lshlrev_b32_e32 v56, 16, v51
	v_pk_mul_f32 v[92:93], v[92:93], v[28:29]
	v_mul_f32_e32 v28, 0xbfb8aa3b, v50
	v_exp_f32_e32 v28, v28
	v_and_b32_e32 v58, 0xffff0000, v51
	v_mov_b32_e32 v51, v29
	v_mul_f32_e32 v20, v92, v93
	v_add_f32_e32 v28, 1.0, v28
	v_rcp_f32_e32 v88, v28
	v_mov_b32_e32 v57, v29
	s_ashr_i32 s20, s8, 5
	s_ashr_i32 s21, s20, 31
	v_pk_mul_f32 v[50:51], v[88:89], v[50:51]
	v_mov_b32_e32 v89, v90
	v_mul_f32_e32 v28, v50, v51
	v_cvt_pk_bf16_f32 v50, v20, v28
	v_mul_f32_e32 v20, 0xbfb8aa3b, v56
	v_exp_f32_e32 v20, v20
	v_mul_f32_e32 v28, 0xbfb8aa3b, v58
	v_exp_f32_e32 v28, v28
	s_mov_b64 s[0:1], 0
	v_add_f32_e32 v20, 1.0, v20
	v_rcp_f32_e32 v88, v20
	v_add_f32_e32 v28, 1.0, v28
	v_rcp_f32_e32 v90, v28
	v_pk_mul_f32 v[56:57], v[88:89], v[56:57]
	s_nop 0
	v_mul_f32_e32 v20, v56, v57
	v_pk_mul_f32 v[56:57], v[90:91], v[58:59]
	v_mov_b32_e32 v59, v84
	v_mul_f32_e32 v28, v56, v57
	v_cvt_pk_bf16_f32 v51, v20, v28
	s_waitcnt vmcnt(6)
	v_lshlrev_b32_e32 v28, 16, v48
	v_mul_f32_e32 v20, 0xbfb8aa3b, v28
	v_exp_f32_e32 v20, v20
	v_and_b32_e32 v48, 0xffff0000, v48
	v_lshl_add_u64 v[56:57], v[26:27], 0, s[20:21]
	v_lshlrev_b64 v[56:57], 10, v[56:57]
	v_add_f32_e32 v20, 1.0, v20
	v_rcp_f32_e32 v58, v20
	v_lshl_add_u64 v[56:57], v[44:45], 0, v[56:57]
	v_lshl_add_u64 v[56:57], v[56:57], 0, v[184:185]
	global_store_dwordx2 v[56:57], v[50:51], off offset:512 nt
	v_pk_mul_f32 v[58:59], v[58:59], v[28:29]
	v_mul_f32_e32 v28, 0xbfb8aa3b, v48
	v_exp_f32_e32 v28, v28
	v_lshlrev_b32_e32 v50, 16, v49
	v_and_b32_e32 v56, 0xffff0000, v49
	v_mov_b32_e32 v49, v29
	v_add_f32_e32 v28, 1.0, v28
	v_rcp_f32_e32 v84, v28
	v_mul_f32_e32 v20, v58, v59
	v_mov_b32_e32 v59, v86
	v_mov_b32_e32 v51, v29
	v_pk_mul_f32 v[48:49], v[84:85], v[48:49]
	v_mov_b32_e32 v57, v29
	v_mul_f32_e32 v28, v48, v49
	v_cvt_pk_bf16_f32 v48, v20, v28
	v_mul_f32_e32 v20, 0xbfb8aa3b, v50
	v_exp_f32_e32 v20, v20
	v_mul_f32_e32 v28, 0xbfb8aa3b, v56
	v_exp_f32_e32 v28, v28
	v_add_f32_e32 v20, 1.0, v20
	v_rcp_f32_e32 v58, v20
	v_add_f32_e32 v28, 1.0, v28
	v_rcp_f32_e32 v86, v28
	v_pk_mul_f32 v[50:51], v[58:59], v[50:51]
	s_nop 0
	v_mul_f32_e32 v20, v50, v51
	v_pk_mul_f32 v[50:51], v[86:87], v[56:57]
	v_mov_b32_e32 v57, v80
	v_mul_f32_e32 v28, v50, v51
	v_cvt_pk_bf16_f32 v49, v20, v28
	s_waitcnt vmcnt(6)
	v_lshlrev_b32_e32 v28, 16, v46
	v_mul_f32_e32 v20, 0xbfb8aa3b, v28
	v_exp_f32_e32 v20, v20
	v_and_b32_e32 v46, 0xffff0000, v46
	v_lshl_add_u64 v[50:51], v[26:27], 0, s[50:51]
	v_lshlrev_b64 v[50:51], 10, v[50:51]
	v_add_f32_e32 v20, 1.0, v20
	v_rcp_f32_e32 v56, v20
	v_lshl_add_u64 v[50:51], v[44:45], 0, v[50:51]
	v_lshl_add_u64 v[50:51], v[50:51], 0, v[184:185]
	global_store_dwordx2 v[50:51], v[48:49], off nt
	v_pk_mul_f32 v[56:57], v[56:57], v[28:29]
	v_mul_f32_e32 v28, 0xbfb8aa3b, v46
	v_exp_f32_e32 v28, v28
	v_lshlrev_b32_e32 v48, 16, v47
	v_and_b32_e32 v50, 0xffff0000, v47
	v_mov_b32_e32 v47, v29
	v_add_f32_e32 v28, 1.0, v28
	v_rcp_f32_e32 v80, v28
	v_mul_f32_e32 v20, v56, v57
	v_mov_b32_e32 v57, v82
	v_mov_b32_e32 v49, v29
	v_pk_mul_f32 v[46:47], v[80:81], v[46:47]
	v_mov_b32_e32 v51, v29
	v_mul_f32_e32 v28, v46, v47
	v_cvt_pk_bf16_f32 v46, v20, v28
	v_mul_f32_e32 v20, 0xbfb8aa3b, v48
	v_exp_f32_e32 v20, v20
	v_mul_f32_e32 v28, 0xbfb8aa3b, v50
	v_exp_f32_e32 v28, v28
	v_add_f32_e32 v20, 1.0, v20
	v_rcp_f32_e32 v56, v20
	v_add_f32_e32 v28, 1.0, v28
	v_rcp_f32_e32 v82, v28
	v_pk_mul_f32 v[48:49], v[56:57], v[48:49]
	s_nop 0
	v_mul_f32_e32 v20, v48, v49
	v_pk_mul_f32 v[48:49], v[82:83], v[50:51]
	v_mov_b32_e32 v51, v76
	v_mul_f32_e32 v28, v48, v49
	v_cvt_pk_bf16_f32 v47, v20, v28
	s_waitcnt vmcnt(6)
	v_lshlrev_b32_e32 v28, 16, v34
	v_mul_f32_e32 v20, 0xbfb8aa3b, v28
	v_exp_f32_e32 v20, v20
	v_and_b32_e32 v34, 0xffff0000, v34
	v_lshl_add_u64 v[48:49], v[26:27], 0, s[52:53]
	v_lshlrev_b64 v[48:49], 10, v[48:49]
	v_add_f32_e32 v20, 1.0, v20
	v_rcp_f32_e32 v50, v20
	v_lshl_add_u64 v[48:49], v[44:45], 0, v[48:49]
	v_lshl_add_u64 v[48:49], v[48:49], 0, v[184:185]
	global_store_dwordx2 v[48:49], v[46:47], off offset:512 nt
	v_pk_mul_f32 v[50:51], v[50:51], v[28:29]
	v_mul_f32_e32 v28, 0xbfb8aa3b, v34
	v_exp_f32_e32 v28, v28
	v_lshlrev_b32_e32 v46, 16, v35
	v_and_b32_e32 v48, 0xffff0000, v35
	v_mov_b32_e32 v35, v29
	v_add_f32_e32 v28, 1.0, v28
	v_rcp_f32_e32 v76, v28
	v_mul_f32_e32 v20, v50, v51
	v_mov_b32_e32 v51, v78
	v_mov_b32_e32 v47, v29
	v_pk_mul_f32 v[34:35], v[76:77], v[34:35]
	v_mov_b32_e32 v49, v29
	v_mul_f32_e32 v28, v34, v35
	v_cvt_pk_bf16_f32 v34, v20, v28
	v_mul_f32_e32 v20, 0xbfb8aa3b, v46
	v_exp_f32_e32 v20, v20
	v_mul_f32_e32 v28, 0xbfb8aa3b, v48
	v_exp_f32_e32 v28, v28
	v_add_f32_e32 v20, 1.0, v20
	v_rcp_f32_e32 v50, v20
	v_add_f32_e32 v28, 1.0, v28
	v_rcp_f32_e32 v78, v28
	v_pk_mul_f32 v[46:47], v[50:51], v[46:47]
	s_nop 0
	v_mul_f32_e32 v20, v46, v47
	v_pk_mul_f32 v[46:47], v[78:79], v[48:49]
	v_mov_b32_e32 v49, v72
	v_mul_f32_e32 v28, v46, v47
	v_cvt_pk_bf16_f32 v35, v20, v28
	s_waitcnt vmcnt(6)
	v_lshlrev_b32_e32 v28, 16, v32
	v_mul_f32_e32 v20, 0xbfb8aa3b, v28
	v_exp_f32_e32 v20, v20
	v_and_b32_e32 v32, 0xffff0000, v32
	v_lshl_add_u64 v[46:47], v[26:27], 0, s[54:55]
	v_lshlrev_b64 v[46:47], 10, v[46:47]
	v_add_f32_e32 v20, 1.0, v20
	v_rcp_f32_e32 v48, v20
	v_lshl_add_u64 v[46:47], v[44:45], 0, v[46:47]
	v_lshl_add_u64 v[46:47], v[46:47], 0, v[184:185]
	global_store_dwordx2 v[46:47], v[34:35], off nt
	v_pk_mul_f32 v[48:49], v[48:49], v[28:29]
	v_mul_f32_e32 v28, 0xbfb8aa3b, v32
	v_exp_f32_e32 v28, v28
	v_lshlrev_b32_e32 v34, 16, v33
	v_and_b32_e32 v46, 0xffff0000, v33
	v_mov_b32_e32 v33, v29
	v_add_f32_e32 v28, 1.0, v28
	v_rcp_f32_e32 v72, v28
	v_mul_f32_e32 v20, v48, v49
	v_mov_b32_e32 v49, v74
	v_mov_b32_e32 v35, v29
	v_pk_mul_f32 v[32:33], v[72:73], v[32:33]
	v_mov_b32_e32 v47, v29
	v_mul_f32_e32 v28, v32, v33
	v_cvt_pk_bf16_f32 v32, v20, v28
	v_mul_f32_e32 v20, 0xbfb8aa3b, v34
	v_exp_f32_e32 v20, v20
	v_mul_f32_e32 v28, 0xbfb8aa3b, v46
	v_exp_f32_e32 v28, v28
	v_pk_mul_f32 v[50:51], v[4:5], v[4:5]
	v_add_f32_e32 v20, 1.0, v20
	v_rcp_f32_e32 v48, v20
	v_add_f32_e32 v28, 1.0, v28
	v_rcp_f32_e32 v74, v28
	v_pk_mul_f32 v[34:35], v[48:49], v[34:35]
	s_nop 0
	v_mul_f32_e32 v20, v34, v35
	v_pk_mul_f32 v[34:35], v[74:75], v[46:47]
	v_mov_b32_e32 v47, v68
	v_mul_f32_e32 v28, v34, v35
	v_cvt_pk_bf16_f32 v33, v20, v28
	s_waitcnt vmcnt(6)
	v_lshlrev_b32_e32 v28, 16, v30
	v_mul_f32_e32 v20, 0xbfb8aa3b, v28
	v_exp_f32_e32 v20, v20
	v_and_b32_e32 v30, 0xffff0000, v30
	v_lshl_add_u64 v[34:35], v[26:27], 0, s[56:57]
	v_lshlrev_b64 v[34:35], 10, v[34:35]
	v_add_f32_e32 v20, 1.0, v20
	v_rcp_f32_e32 v46, v20
	v_lshl_add_u64 v[34:35], v[44:45], 0, v[34:35]
	v_lshl_add_u64 v[34:35], v[34:35], 0, v[184:185]
	global_store_dwordx2 v[34:35], v[32:33], off offset:512 nt
	v_pk_mul_f32 v[46:47], v[46:47], v[28:29]
	v_mul_f32_e32 v28, 0xbfb8aa3b, v30
	v_exp_f32_e32 v28, v28
	v_lshlrev_b32_e32 v32, 16, v31
	v_and_b32_e32 v34, 0xffff0000, v31
	v_mov_b32_e32 v31, v29
	v_add_f32_e32 v28, 1.0, v28
	v_rcp_f32_e32 v68, v28
	v_mul_f32_e32 v20, v46, v47
	v_mov_b32_e32 v47, v70
	v_mov_b32_e32 v33, v29
	v_pk_mul_f32 v[30:31], v[68:69], v[30:31]
	v_mov_b32_e32 v35, v29
	v_mul_f32_e32 v28, v30, v31
	v_cvt_pk_bf16_f32 v30, v20, v28
	v_mul_f32_e32 v20, 0xbfb8aa3b, v32
	v_exp_f32_e32 v20, v20
	v_mul_f32_e32 v28, 0xbfb8aa3b, v34
	v_exp_f32_e32 v28, v28
	v_add_f32_e32 v20, 1.0, v20
	v_rcp_f32_e32 v46, v20
	v_add_f32_e32 v28, 1.0, v28
	v_rcp_f32_e32 v70, v28
	v_pk_mul_f32 v[32:33], v[46:47], v[32:33]
	s_nop 0
	v_mul_f32_e32 v20, v32, v33
	v_pk_mul_f32 v[32:33], v[70:71], v[34:35]
	v_mov_b32_e32 v35, v64
	v_mul_f32_e32 v28, v32, v33
	v_lshl_add_u64 v[32:33], v[26:27], 0, s[58:59]
	v_lshlrev_b64 v[32:33], 10, v[32:33]
	v_lshl_add_u64 v[32:33], v[44:45], 0, v[32:33]
	v_cvt_pk_bf16_f32 v31, v20, v28
	v_lshl_add_u64 v[32:33], v[32:33], 0, v[184:185]
	s_waitcnt vmcnt(6)
	v_lshlrev_b32_e32 v28, 16, v24
	v_and_b32_e32 v24, 0xffff0000, v24
	global_store_dwordx2 v[32:33], v[30:31], off nt
	v_lshlrev_b32_e32 v30, 16, v25
	v_and_b32_e32 v32, 0xffff0000, v25
	v_mul_f32_e32 v20, 0xbfb8aa3b, v28
	v_mul_f32_e32 v25, 0xbfb8aa3b, v24
	v_exp_f32_e32 v20, v20
	v_exp_f32_e32 v25, v25
	v_mov_b32_e32 v31, v29
	v_mov_b32_e32 v33, v29
	v_add_f32_e32 v20, 1.0, v20
	v_add_f32_e32 v25, 1.0, v25
	v_rcp_f32_e32 v34, v20
	v_rcp_f32_e32 v64, v25
	v_mov_b32_e32 v25, v29
	v_lshl_add_u64 v[26:27], v[26:27], 0, s[60:61]
	v_pk_mul_f32 v[34:35], v[34:35], v[28:29]
	v_pk_mul_f32 v[24:25], v[64:65], v[24:25]
	v_mul_f32_e32 v20, v34, v35
	v_mul_f32_e32 v24, v24, v25
	v_cvt_pk_bf16_f32 v24, v20, v24
	v_mul_f32_e32 v20, 0xbfb8aa3b, v30
	v_mul_f32_e32 v25, 0xbfb8aa3b, v32
	v_exp_f32_e32 v20, v20
	v_exp_f32_e32 v25, v25
	v_mov_b32_e32 v35, v66
	v_lshlrev_b64 v[26:27], 10, v[26:27]
	v_add_f32_e32 v20, 1.0, v20
	v_add_f32_e32 v25, 1.0, v25
	v_rcp_f32_e32 v34, v20
	v_rcp_f32_e32 v66, v25
	v_lshl_add_u64 v[26:27], v[44:45], 0, v[26:27]
	v_lshl_add_u64 v[26:27], v[26:27], 0, v[184:185]
	v_pk_mul_f32 v[30:31], v[34:35], v[30:31]
	v_pk_mul_f32 v[28:29], v[66:67], v[32:33]
	v_mul_f32_e32 v20, v30, v31
	v_mul_f32_e32 v25, v28, v29
	v_cvt_pk_bf16_f32 v25, v20, v25
	v_or_b32_e32 v20, s17, v54
	global_store_dwordx2 v[26:27], v[24:25], off offset:512 nt
	v_lshlrev_b64 v[24:25], 2, v[20:21]
	v_and_b32_e32 v25, 0x7fffff, v25
	v_and_b32_e32 v24, 0xffffffc0, v24
	v_lshl_add_u64 v[26:27], v[24:25], 0, s[10:11]
	v_lshlrev_b64 v[26:27], 9, v[26:27]
	v_lshl_add_u64 v[26:27], v[22:23], 0, v[26:27]
	global_load_dwordx2 v[48:49], v[26:27], off nt
	v_mul_f32_e32 v54, v61, v61
	v_fmac_f32_e32 v54, v60, v60
	v_lshl_add_u64 v[26:27], v[24:25], 0, s[12:13]
	v_fmac_f32_e32 v54, v62, v62
	v_lshlrev_b64 v[26:27], 9, v[26:27]
	v_fmac_f32_e32 v54, v63, v63
	v_lshl_add_u64 v[26:27], v[22:23], 0, v[26:27]
	v_fmac_f32_e32 v54, v40, v40
	global_load_dwordx2 v[46:47], v[26:27], off nt
	v_fmac_f32_e32 v54, v41, v41
	v_fmac_f32_e32 v54, v42, v42
	v_fmac_f32_e32 v54, v43, v43
	v_fmac_f32_e32 v54, v36, v36
	v_fmac_f32_e32 v54, v37, v37
	v_fmac_f32_e32 v54, v38, v38
	v_lshl_add_u64 v[26:27], v[24:25], 0, s[24:25]
	v_fmac_f32_e32 v54, v39, v39
	v_lshlrev_b64 v[26:27], 9, v[26:27]
	v_fmac_f32_e32 v54, v16, v16
	v_lshl_add_u64 v[26:27], v[22:23], 0, v[26:27]
	v_fmac_f32_e32 v54, v17, v17
	global_load_dwordx2 v[34:35], v[26:27], off nt
	v_lshl_add_u64 v[26:27], v[24:25], 0, s[34:35]
	v_fmac_f32_e32 v54, v18, v18
	v_lshlrev_b64 v[26:27], 9, v[26:27]
	v_fmac_f32_e32 v54, v19, v19
	v_lshl_add_u64 v[26:27], v[22:23], 0, v[26:27]
	v_fmac_f32_e32 v54, v12, v12
	global_load_dwordx2 v[32:33], v[26:27], off nt
	v_lshl_add_u64 v[26:27], v[24:25], 0, s[36:37]
	v_fmac_f32_e32 v54, v13, v13
	v_lshlrev_b64 v[26:27], 9, v[26:27]
	v_fmac_f32_e32 v54, v14, v14
	v_lshl_add_u64 v[26:27], v[22:23], 0, v[26:27]
	v_fmac_f32_e32 v54, v15, v15
	global_load_dwordx2 v[30:31], v[26:27], off nt
	v_lshl_add_u64 v[26:27], v[24:25], 0, s[40:41]
	v_fmac_f32_e32 v54, v8, v8
	v_lshlrev_b64 v[26:27], 9, v[26:27]
	v_fmac_f32_e32 v54, v9, v9
	v_lshl_add_u64 v[26:27], v[22:23], 0, v[26:27]
	v_fmac_f32_e32 v54, v10, v10
	global_load_dwordx2 v[28:29], v[26:27], off nt
	v_lshl_add_u64 v[26:27], v[24:25], 0, s[44:45]
	v_lshl_add_u64 v[24:25], v[24:25], 0, s[46:47]
	v_fmac_f32_e32 v54, v11, v11
	v_lshlrev_b64 v[26:27], 9, v[26:27]
	v_lshlrev_b64 v[24:25], 9, v[24:25]
	v_add_f32_e32 v50, v50, v54
	v_lshl_add_u64 v[26:27], v[22:23], 0, v[26:27]
	v_lshl_add_u64 v[22:23], v[22:23], 0, v[24:25]
	v_pk_mul_f32 v[24:25], v[6:7], v[6:7]
	v_add_f32_e32 v50, v51, v50
	v_add_f32_e32 v24, v24, v50
	v_add_f32_e32 v54, v25, v24
	v_pk_mul_f32 v[50:51], v[0:1], v[0:1]
	v_pk_mul_f32 v[24:25], v[2:3], v[2:3]
	v_add_f32_e32 v50, v50, v54
	v_add_f32_e32 v50, v51, v50
	v_add_f32_e32 v24, v24, v50
	v_add_f32_e32 v24, v25, v24
	ds_bpermute_b32 v25, v53, v24
	global_load_dwordx2 v[26:27], v[26:27], off nt
	v_lshlrev_b64 v[20:21], 1, v[20:21]
	global_load_dwordx2 v[22:23], v[22:23], off nt
	v_and_b32_e32 v21, 0x3fffff, v21
	s_waitcnt lgkmcnt(0)
	v_add_f32_e32 v24, v24, v25
	ds_bpermute_b32 v25, v52, v24
	v_and_b32_e32 v20, 0xffffffe0, v20
	s_waitcnt lgkmcnt(0)
	v_add_f32_e32 v24, v24, v25
	v_fmamk_f32 v24, v24, 0x3c000000, v227
	v_cmp_gt_f32_e32 vcc, s15, v24
	v_mul_f32_e32 v25, 0x4b800000, v24
	s_waitcnt vmcnt(7)
	v_lshlrev_b32_e32 v50, 16, v49
	v_cndmask_b32_e32 v24, v24, v25, vcc
	v_rsq_f32_e32 v24, v24
	v_and_b32_e32 v52, 0xffff0000, v49
	v_mul_f32_e32 v25, 0x45800000, v24
	v_cndmask_b32_e32 v25, v24, v25, vcc
	v_lshlrev_b32_e32 v24, 16, v48
	v_mul_f32_e32 v49, 0xbfb8aa3b, v24
	v_exp_f32_e32 v49, v49
	v_and_b32_e32 v48, 0xffff0000, v48
	v_mov_b32_e32 v51, v25
	v_mov_b32_e32 v53, v25
	v_add_f32_e32 v49, 1.0, v49
	v_rcp_f32_e32 v54, v49
	v_mul_f32_e32 v49, 0xbfb8aa3b, v48
	v_exp_f32_e32 v49, v49
	v_pk_mul_f32 v[54:55], v[54:55], v[24:25]
	s_nop 0
	v_mul_f32_e32 v24, v54, v55
	v_add_f32_e32 v49, 1.0, v49
	v_rcp_f32_e32 v60, v49
	v_mov_b32_e32 v49, v25
	v_mov_b32_e32 v55, v62
	v_pk_mul_f32 v[48:49], v[60:61], v[48:49]
	s_nop 0
	v_mul_f32_e32 v48, v48, v49
	v_cvt_pk_bf16_f32 v48, v24, v48
	v_mul_f32_e32 v24, 0xbfb8aa3b, v50
	v_exp_f32_e32 v24, v24
	v_mul_f32_e32 v49, 0xbfb8aa3b, v52
	v_exp_f32_e32 v49, v49
	v_add_f32_e32 v24, 1.0, v24
	v_rcp_f32_e32 v54, v24
	v_add_f32_e32 v49, 1.0, v49
	v_rcp_f32_e32 v62, v49
	v_pk_mul_f32 v[50:51], v[54:55], v[50:51]
	s_nop 0
	v_mul_f32_e32 v24, v50, v51
	v_pk_mul_f32 v[50:51], v[62:63], v[52:53]
	v_mov_b32_e32 v53, v40
	v_mul_f32_e32 v49, v50, v51
	v_lshl_add_u64 v[50:51], v[20:21], 0, s[48:49]
	v_lshlrev_b64 v[50:51], 10, v[50:51]
	v_cvt_pk_bf16_f32 v49, v24, v49
	v_lshl_add_u64 v[50:51], v[44:45], 0, v[50:51]
	s_waitcnt vmcnt(6)
	v_lshlrev_b32_e32 v24, 16, v46
	v_and_b32_e32 v46, 0xffff0000, v46
	v_lshl_add_u64 v[50:51], v[50:51], 0, v[184:185]
	v_mul_f32_e32 v40, 0xbfb8aa3b, v46
	global_store_dwordx2 v[50:51], v[48:49], off nt
	v_lshlrev_b32_e32 v48, 16, v47
	v_and_b32_e32 v50, 0xffff0000, v47
	v_mul_f32_e32 v47, 0xbfb8aa3b, v24
	v_exp_f32_e32 v40, v40
	v_exp_f32_e32 v47, v47
	v_mov_b32_e32 v51, v25
	v_mov_b32_e32 v49, v25
	v_add_f32_e32 v40, 1.0, v40
	v_add_f32_e32 v47, 1.0, v47
	v_rcp_f32_e32 v40, v40
	v_rcp_f32_e32 v52, v47
	v_mov_b32_e32 v47, v25
	v_pk_mul_f32 v[40:41], v[40:41], v[46:47]
	v_pk_mul_f32 v[52:53], v[52:53], v[24:25]
	v_mul_f32_e32 v40, v40, v41
	v_mul_f32_e32 v41, 0xbfb8aa3b, v50
	v_mul_f32_e32 v24, v52, v53
	v_exp_f32_e32 v41, v41
	v_cvt_pk_bf16_f32 v40, v24, v40
	v_mul_f32_e32 v24, 0xbfb8aa3b, v48
	v_exp_f32_e32 v24, v24
	v_add_f32_e32 v41, 1.0, v41
	v_mov_b32_e32 v47, v42
	v_rcp_f32_e32 v42, v41
	v_add_f32_e32 v24, 1.0, v24
	v_rcp_f32_e32 v46, v24
	v_pk_mul_f32 v[42:43], v[42:43], v[50:51]
	s_nop 0
	v_mul_f32_e32 v41, v42, v43
	v_lshl_add_u64 v[42:43], v[20:21], 0, s[20:21]
	v_pk_mul_f32 v[46:47], v[46:47], v[48:49]
	v_lshlrev_b64 v[42:43], 10, v[42:43]
	v_mul_f32_e32 v24, v46, v47
	v_lshl_add_u64 v[42:43], v[44:45], 0, v[42:43]
	v_cvt_pk_bf16_f32 v41, v24, v41
	v_lshl_add_u64 v[42:43], v[42:43], 0, v[184:185]
	s_waitcnt vmcnt(6)
	v_lshlrev_b32_e32 v24, 16, v34
	global_store_dwordx2 v[42:43], v[40:41], off offset:512 nt
	v_lshlrev_b32_e32 v40, 16, v35
	v_and_b32_e32 v42, 0xffff0000, v35
	v_mul_f32_e32 v35, 0xbfb8aa3b, v24
	v_exp_f32_e32 v35, v35
	v_and_b32_e32 v34, 0xffff0000, v34
	v_mov_b32_e32 v47, v36
	v_mov_b32_e32 v41, v25
	v_add_f32_e32 v35, 1.0, v35
	v_rcp_f32_e32 v46, v35
	v_mul_f32_e32 v35, 0xbfb8aa3b, v34
	v_exp_f32_e32 v35, v35
	v_mov_b32_e32 v43, v25
	v_pk_mul_f32 v[46:47], v[46:47], v[24:25]
	v_add_f32_e32 v35, 1.0, v35
	v_rcp_f32_e32 v36, v35
	v_mov_b32_e32 v35, v25
	v_mul_f32_e32 v24, v46, v47
	v_pk_mul_f32 v[34:35], v[36:37], v[34:35]
	s_nop 0
	v_mul_f32_e32 v34, v34, v35
	v_cvt_pk_bf16_f32 v34, v24, v34
	v_mul_f32_e32 v24, 0xbfb8aa3b, v40
	v_exp_f32_e32 v24, v24
	v_mul_f32_e32 v35, 0xbfb8aa3b, v42
	v_exp_f32_e32 v35, v35
	v_mov_b32_e32 v37, v38
	v_add_f32_e32 v24, 1.0, v24
	v_rcp_f32_e32 v36, v24
	v_add_f32_e32 v35, 1.0, v35
	v_rcp_f32_e32 v38, v35
	v_pk_mul_f32 v[36:37], v[36:37], v[40:41]
	s_nop 0
	v_mul_f32_e32 v24, v36, v37
	v_pk_mul_f32 v[36:37], v[38:39], v[42:43]
	v_mov_b32_e32 v39, v16
	v_mul_f32_e32 v35, v36, v37
	v_cvt_pk_bf16_f32 v35, v24, v35
	v_lshl_add_u64 v[36:37], v[20:21], 0, s[50:51]
	s_waitcnt vmcnt(6)
	v_lshlrev_b32_e32 v24, 16, v32
	v_and_b32_e32 v32, 0xffff0000, v32
	v_lshlrev_b64 v[36:37], 10, v[36:37]
	v_mul_f32_e32 v16, 0xbfb8aa3b, v32
	v_lshl_add_u64 v[36:37], v[44:45], 0, v[36:37]
	v_exp_f32_e32 v16, v16
	v_lshl_add_u64 v[36:37], v[36:37], 0, v[184:185]
	global_store_dwordx2 v[36:37], v[34:35], off nt
	v_lshlrev_b32_e32 v34, 16, v33
	v_and_b32_e32 v36, 0xffff0000, v33
	v_mul_f32_e32 v33, 0xbfb8aa3b, v24
	v_exp_f32_e32 v33, v33
	v_add_f32_e32 v16, 1.0, v16
	v_rcp_f32_e32 v16, v16
	v_mov_b32_e32 v35, v25
	v_add_f32_e32 v33, 1.0, v33
	v_rcp_f32_e32 v38, v33
	v_mov_b32_e32 v33, v25
	v_pk_mul_f32 v[16:17], v[16:17], v[32:33]
	v_mov_b32_e32 v33, v18
	v_mul_f32_e32 v16, v16, v17
	v_mul_f32_e32 v17, 0xbfb8aa3b, v34
	v_mul_f32_e32 v18, 0xbfb8aa3b, v36
	v_exp_f32_e32 v17, v17
	v_exp_f32_e32 v18, v18
	v_mov_b32_e32 v37, v25
	v_pk_mul_f32 v[38:39], v[38:39], v[24:25]
	v_add_f32_e32 v17, 1.0, v17
	v_add_f32_e32 v18, 1.0, v18
	v_rcp_f32_e32 v32, v17
	v_rcp_f32_e32 v18, v18
	v_mul_f32_e32 v24, v38, v39
	v_cvt_pk_bf16_f32 v16, v24, v16
	v_pk_mul_f32 v[32:33], v[32:33], v[34:35]
	v_pk_mul_f32 v[18:19], v[18:19], v[36:37]
	v_mul_f32_e32 v17, v32, v33
	v_mul_f32_e32 v18, v18, v19
	v_cvt_pk_bf16_f32 v17, v17, v18
	v_lshl_add_u64 v[18:19], v[20:21], 0, s[52:53]
	v_lshlrev_b64 v[18:19], 10, v[18:19]
	v_lshl_add_u64 v[18:19], v[44:45], 0, v[18:19]
	v_lshl_add_u64 v[18:19], v[18:19], 0, v[184:185]
	global_store_dwordx2 v[18:19], v[16:17], off offset:512 nt
	s_waitcnt vmcnt(7)
	v_and_b32_e32 v16, 0xffff0000, v30
	v_mov_b32_e32 v33, v12
	v_mul_f32_e32 v12, 0xbfb8aa3b, v16
	v_exp_f32_e32 v12, v12
	v_lshlrev_b32_e32 v24, 16, v30
	v_mul_f32_e32 v17, 0xbfb8aa3b, v24
	v_exp_f32_e32 v17, v17
	v_add_f32_e32 v12, 1.0, v12
	v_rcp_f32_e32 v12, v12
	v_lshlrev_b32_e32 v18, 16, v31
	v_add_f32_e32 v17, 1.0, v17
	v_rcp_f32_e32 v32, v17
	v_mov_b32_e32 v17, v25
	v_and_b32_e32 v30, 0xffff0000, v31
	v_pk_mul_f32 v[12:13], v[12:13], v[16:17]
	v_mov_b32_e32 v17, v14
	v_mul_f32_e32 v12, v12, v13
	v_mul_f32_e32 v13, 0xbfb8aa3b, v18
	v_mul_f32_e32 v14, 0xbfb8aa3b, v30
	v_exp_f32_e32 v13, v13
	v_exp_f32_e32 v14, v14
	v_pk_mul_f32 v[32:33], v[32:33], v[24:25]
	v_mov_b32_e32 v31, v25
	v_add_f32_e32 v13, 1.0, v13
	v_add_f32_e32 v14, 1.0, v14
	v_rcp_f32_e32 v16, v13
	v_rcp_f32_e32 v14, v14
	v_mul_f32_e32 v19, v32, v33
	v_cvt_pk_bf16_f32 v12, v19, v12
	v_mov_b32_e32 v19, v25
	v_pk_mul_f32 v[16:17], v[16:17], v[18:19]
	v_pk_mul_f32 v[14:15], v[14:15], v[30:31]
	v_mul_f32_e32 v13, v16, v17
	v_mul_f32_e32 v14, v14, v15
	v_cvt_pk_bf16_f32 v13, v13, v14
	v_lshl_add_u64 v[14:15], v[20:21], 0, s[54:55]
	v_lshlrev_b64 v[14:15], 10, v[14:15]
	v_lshl_add_u64 v[14:15], v[44:45], 0, v[14:15]
	v_lshl_add_u64 v[14:15], v[14:15], 0, v[184:185]
	global_store_dwordx2 v[14:15], v[12:13], off nt
	s_waitcnt vmcnt(7)
	v_and_b32_e32 v12, 0xffff0000, v28
	v_mov_b32_e32 v19, v8
	v_mul_f32_e32 v8, 0xbfb8aa3b, v12
	v_exp_f32_e32 v8, v8
	v_lshlrev_b32_e32 v24, 16, v28
	v_mul_f32_e32 v13, 0xbfb8aa3b, v24
	v_exp_f32_e32 v13, v13
	v_add_f32_e32 v8, 1.0, v8
	v_rcp_f32_e32 v8, v8
	v_lshlrev_b32_e32 v14, 16, v29
	v_add_f32_e32 v13, 1.0, v13
	v_rcp_f32_e32 v18, v13
	v_mov_b32_e32 v13, v25
	v_and_b32_e32 v16, 0xffff0000, v29
	v_pk_mul_f32 v[8:9], v[8:9], v[12:13]
	v_mov_b32_e32 v13, v10
	v_mul_f32_e32 v8, v8, v9
	v_mul_f32_e32 v9, 0xbfb8aa3b, v14
	v_mul_f32_e32 v10, 0xbfb8aa3b, v16
	v_exp_f32_e32 v9, v9
	v_exp_f32_e32 v10, v10
	v_pk_mul_f32 v[18:19], v[18:19], v[24:25]
	v_mov_b32_e32 v17, v25
	v_add_f32_e32 v9, 1.0, v9
	v_add_f32_e32 v10, 1.0, v10
	v_rcp_f32_e32 v12, v9
	v_rcp_f32_e32 v10, v10
	v_mul_f32_e32 v15, v18, v19
	v_cvt_pk_bf16_f32 v8, v15, v8
	v_mov_b32_e32 v15, v25
	v_pk_mul_f32 v[12:13], v[12:13], v[14:15]
	v_pk_mul_f32 v[10:11], v[10:11], v[16:17]
	v_mul_f32_e32 v9, v12, v13
	v_mul_f32_e32 v10, v10, v11
	v_cvt_pk_bf16_f32 v9, v9, v10
	v_lshl_add_u64 v[10:11], v[20:21], 0, s[56:57]
	v_lshlrev_b64 v[10:11], 10, v[10:11]
	v_lshl_add_u64 v[10:11], v[44:45], 0, v[10:11]
	v_lshl_add_u64 v[10:11], v[10:11], 0, v[184:185]
	global_store_dwordx2 v[10:11], v[8:9], off offset:512 nt
	s_waitcnt vmcnt(7)
	v_and_b32_e32 v8, 0xffff0000, v26
	v_mov_b32_e32 v15, v4
	v_mul_f32_e32 v4, 0xbfb8aa3b, v8
	v_exp_f32_e32 v4, v4
	v_lshlrev_b32_e32 v24, 16, v26
	v_mul_f32_e32 v9, 0xbfb8aa3b, v24
	v_exp_f32_e32 v9, v9
	v_add_f32_e32 v4, 1.0, v4
	v_rcp_f32_e32 v4, v4
	v_lshlrev_b32_e32 v10, 16, v27
	v_add_f32_e32 v9, 1.0, v9
	v_rcp_f32_e32 v14, v9
	v_mov_b32_e32 v9, v25
	v_and_b32_e32 v12, 0xffff0000, v27
	v_pk_mul_f32 v[4:5], v[4:5], v[8:9]
	v_mov_b32_e32 v9, v6
	v_mul_f32_e32 v4, v4, v5
	v_mul_f32_e32 v5, 0xbfb8aa3b, v10
	v_mul_f32_e32 v6, 0xbfb8aa3b, v12
	v_exp_f32_e32 v5, v5
	v_exp_f32_e32 v6, v6
	v_pk_mul_f32 v[14:15], v[14:15], v[24:25]
	v_mov_b32_e32 v13, v25
	v_add_f32_e32 v5, 1.0, v5
	v_add_f32_e32 v6, 1.0, v6
	v_rcp_f32_e32 v8, v5
	v_rcp_f32_e32 v6, v6
	v_mul_f32_e32 v11, v14, v15
	v_cvt_pk_bf16_f32 v4, v11, v4
	v_mov_b32_e32 v11, v25
	v_pk_mul_f32 v[8:9], v[8:9], v[10:11]
	v_pk_mul_f32 v[6:7], v[6:7], v[12:13]
	v_mul_f32_e32 v5, v8, v9
	v_mul_f32_e32 v6, v6, v7
	v_cvt_pk_bf16_f32 v5, v5, v6
	v_lshl_add_u64 v[6:7], v[20:21], 0, s[58:59]
	v_lshlrev_b64 v[6:7], 10, v[6:7]
	v_lshl_add_u64 v[6:7], v[44:45], 0, v[6:7]
	v_lshl_add_u64 v[6:7], v[6:7], 0, v[184:185]
	global_store_dwordx2 v[6:7], v[4:5], off nt
	s_waitcnt vmcnt(7)
	v_and_b32_e32 v4, 0xffff0000, v22
	v_mov_b32_e32 v11, v0
	v_mul_f32_e32 v0, 0xbfb8aa3b, v4
	v_exp_f32_e32 v0, v0
	v_lshlrev_b32_e32 v24, 16, v22
	v_mul_f32_e32 v5, 0xbfb8aa3b, v24
	v_exp_f32_e32 v5, v5
	v_add_f32_e32 v0, 1.0, v0
	v_rcp_f32_e32 v0, v0
	v_lshlrev_b32_e32 v6, 16, v23
	v_add_f32_e32 v5, 1.0, v5
	v_rcp_f32_e32 v10, v5
	v_mov_b32_e32 v5, v25
	v_and_b32_e32 v8, 0xffff0000, v23
	v_pk_mul_f32 v[0:1], v[0:1], v[4:5]
	v_mov_b32_e32 v5, v2
	v_mul_f32_e32 v0, v0, v1
	v_mul_f32_e32 v1, 0xbfb8aa3b, v6
	v_mul_f32_e32 v2, 0xbfb8aa3b, v8
	v_exp_f32_e32 v1, v1
	v_exp_f32_e32 v2, v2
	v_pk_mul_f32 v[10:11], v[10:11], v[24:25]
	v_mov_b32_e32 v9, v25
	v_add_f32_e32 v1, 1.0, v1
	v_add_f32_e32 v2, 1.0, v2
	v_rcp_f32_e32 v4, v1
	v_rcp_f32_e32 v2, v2
	v_mul_f32_e32 v7, v10, v11
	v_cvt_pk_bf16_f32 v0, v7, v0
	v_mov_b32_e32 v7, v25
	v_pk_mul_f32 v[4:5], v[4:5], v[6:7]
	v_pk_mul_f32 v[2:3], v[2:3], v[8:9]
	v_mul_f32_e32 v1, v4, v5
	v_mul_f32_e32 v2, v2, v3
	v_cvt_pk_bf16_f32 v1, v1, v2
	v_lshl_add_u64 v[2:3], v[20:21], 0, s[60:61]
	s_mov_b64 s[58:59], 0xde01000
